# stacked: retention ring + final P.V ring + state-scan steps' read->wait->MFMA ladders ringed (25 of 32 unrolled steps)
# speedup vs baseline: 1.0014x; 1.0014x over previous
.LBB0_315:
	s_and_b32 s5, s28, 7
	v_cvt_f32_ubyte0_e32 v16, s5
	v_sub_f32_e32 v16, 0xc0a00000, v16
	v_cmp_gt_f32_e32 vcc, s9, v16
	v_mov_b32_e32 v0, v181
	s_lshr_b32 s3, s28, 3
	v_cndmask_b32_e32 v17, 0, v200, vcc
	v_add_f32_e32 v16, v16, v17
	v_readfirstlane_b32 s1, v0
	v_exp_f32_e32 v16, v16
	s_ashr_i32 s1, s1, 6
	s_and_b64 s[18:19], vcc, exec
	s_cselect_b32 s11, 0xffffffc0, 0
	v_ldexp_f32 v16, v16, s11
	v_sub_f32_e32 v16, 1.0, v16
	v_cmp_gt_f32_e32 vcc, s7, v16
	s_and_b64 s[18:19], vcc, exec
	s_cselect_b32 s11, 32, 0
	v_ldexp_f32 v16, v16, s11
	v_log_f32_e32 v16, v16
	v_cndmask_b32_e32 v17, 0, v201, vcc
	v_lshlrev_b32_e32 v18, 2, v0
	v_and_b32_e32 v116, 32, v18
	v_sub_f32_e32 v16, v16, v17
	v_mul_f32_e32 v17, 0x42800000, v16
	v_cmp_gt_f32_e32 vcc, s9, v17
	s_and_b64 s[18:19], vcc, exec
	s_cselect_b32 s11, 0xffffffc0, 0
	v_cndmask_b32_e32 v17, 0, v200, vcc
	v_fmac_f32_e32 v17, 0x42800000, v16
	v_exp_f32_e32 v16, v17
	v_bfe_u32 v17, v0, 2, 1
	v_lshlrev_b32_e32 v18, 3, v0
	v_and_b32_e32 v18, 24, v18
	v_ldexp_f32 v184, v16, s11
	v_lshlrev_b32_e32 v16, 6, v0
	v_and_b32_e32 v115, 0x3c0, v16
	v_lshrrev_b32_e32 v16, 3, v0
	v_and_or_b32 v17, v16, 62, v17
	v_or_b32_e32 v19, v116, v18
	v_lshrrev_b32_e32 v20, 6, v0
	v_lshlrev_b32_e32 v21, 6, v17
	v_lshlrev_b32_e32 v18, 1, v18
	s_movk_i32 s11, 0x3c0
	s_mul_i32 s52, s3, 0x630000
	s_ashr_i32 s3, s1, 31
	v_and_b32_e32 v114, 63, v0
	v_and_or_b32 v117, v21, s11, v18
	v_lshrrev_b32_e32 v18, 1, v0
	v_lshl_or_b32 v17, s5, 7, v17
	s_add_u32 s18, s1, s27
	v_and_b32_e32 v119, 48, v0
	v_and_b32_e32 v0, 6, v20
	v_and_b32_e32 v118, 32, v18
	v_mul_u32_u24_e32 v18, 0x840, v17
	s_addc_u32 s19, s3, 0
	v_and_or_b32 v0, v16, 1, v0
	s_lshl_b64 s[22:23], s[52:53], 1
	v_lshlrev_b32_e32 v120, 10, v0
	v_lshl_add_u64 v[16:17], v[10:11], 0, s[22:23]
	v_lshlrev_b32_e32 v0, 1, v18
	v_lshl_add_u64 v[16:17], v[16:17], 0, v[0:1]
	v_lshlrev_b32_e32 v0, 1, v19
	v_lshl_add_u64 v[188:189], v[16:17], 0, v[0:1]
	v_add_co_u32_e32 v190, vcc, s14, v188
	s_mov_b32 s3, 0x420000
	s_nop 0
	v_addc_co_u32_e32 v191, vcc, 0, v189, vcc
	global_load_dwordx4 v[96:99], v[188:189], off
	global_load_dwordx4 v[100:103], v[190:191], off
	v_add_co_u32_e32 v192, vcc, s3, v188
	s_mov_b32 s3, 0x462000
	s_nop 0
	v_addc_co_u32_e32 v193, vcc, 0, v189, vcc
	global_load_dwordx4 v[104:107], v[192:193], off
	v_add_co_u32_e32 v194, vcc, s3, v188
	s_lshl_b64 s[18:19], s[18:19], 12
	s_nop 0
	v_addc_co_u32_e32 v195, vcc, 0, v189, vcc
	global_load_dwordx4 v[108:111], v[194:195], off
	global_load_dwordx4 v[16:19], v[188:189], off offset:128
	global_load_dwordx4 v[20:23], v[190:191], off offset:128
	global_load_dwordx4 v[24:27], v[192:193], off offset:128
	global_load_dwordx4 v[28:31], v[194:195], off offset:128
	global_load_dwordx4 v[32:35], v[188:189], off offset:256
	global_load_dwordx4 v[36:39], v[190:191], off offset:256
	global_load_dwordx4 v[40:43], v[192:193], off offset:256
	global_load_dwordx4 v[44:47], v[194:195], off offset:256
	global_load_dwordx4 v[48:51], v[188:189], off offset:384
	global_load_dwordx4 v[52:55], v[190:191], off offset:384
	global_load_dwordx4 v[56:59], v[192:193], off offset:384
	global_load_dwordx4 v[60:63], v[194:195], off offset:384
	global_load_dwordx4 v[64:67], v[188:189], off offset:512
	global_load_dwordx4 v[68:71], v[190:191], off offset:512
	global_load_dwordx4 v[72:75], v[192:193], off offset:512
	global_load_dwordx4 v[76:79], v[194:195], off offset:512
	global_load_dwordx4 v[80:83], v[188:189], off offset:640
	global_load_dwordx4 v[84:87], v[190:191], off offset:640
	global_load_dwordx4 v[88:91], v[192:193], off offset:640
	global_load_dwordx4 v[92:95], v[194:195], off offset:640
	v_bitop3_b32 v115, v115, v116, v119 bitop3:0x36
	v_bitop3_b32 v116, v117, v120, v118 bitop3:0xde
	s_mov_b32 s54, s53
	s_mov_b32 s55, s53
	v_lshl_add_u64 v[112:113], v[6:7], 0, s[18:19]
	s_lshl_b32 s1, s1, 11
	v_add_u32_e32 v185, 0, v116
	s_mov_b32 s52, s53
	v_mov_b64_e32 v[118:119], s[54:55]
	v_lshlrev_b32_e32 v0, 4, v114
	v_mov_b64_e32 v[116:117], s[52:53]
	v_readfirstlane_b32 s18, v112
	v_readfirstlane_b32 s19, v113
	s_add_i32 s1, s1, 0
	v_lshl_add_u64 v[186:187], v[112:113], 0, v[0:1]
	v_add_u32_e32 v208, s1, v115
	v_mul_f32_e32 v144, 0, v184
	v_mov_b32_e32 v145, v144
	v_mov_b32_e32 v146, v144
	v_mov_b32_e32 v147, v144
	s_mov_b32 s1, 0x8000
	s_waitcnt vmcnt(0)
	ds_write_b128 v185, v[96:99]
	ds_write_b128 v185, v[100:103] offset:8192
	ds_write_b128 v185, v[104:107] offset:16384
	ds_write_b128 v185, v[108:111] offset:24576
	global_load_dwordx4 v[96:99], v[188:189], off offset:768
	global_load_dwordx4 v[100:103], v[190:191], off offset:768
	global_load_dwordx4 v[104:107], v[192:193], off offset:768
	global_load_dwordx4 v[108:111], v[194:195], off offset:768
	s_waitcnt lgkmcnt(0)
	s_barrier
	global_store_dwordx4 v0, v[116:119], s[18:19]
	global_store_dwordx4 v0, v[116:119], s[18:19] offset:1024
	global_store_dwordx4 v0, v[116:119], s[18:19] offset:2048
	global_store_dwordx4 v0, v[116:119], s[18:19] offset:3072
	v_add_u32_e32 v0, 0, v115
	ds_read_b128 v[116:119], v208 offset:16384
	ds_read_b128 v[120:123], v208 offset:17408
	ds_read_b128 v[112:115], v0
	ds_read_b128 v[124:127], v0 offset:1024
	s_waitcnt lgkmcnt(1)
	v_mfma_f32_16x16x32_bf16 v[112:115], v[112:115], v[116:119], v[144:147]
	s_waitcnt lgkmcnt(0)
	v_mfma_f32_16x16x32_bf16 v[148:151], v[124:127], v[120:123], v[112:115]
	s_nop 5
	ds_read_b128 v[112:115], v0 offset:2048
	ds_read_b128 v[124:127], v0 offset:3072
	s_waitcnt lgkmcnt(1)
	v_mfma_f32_16x16x32_bf16 v[112:115], v[112:115], v[116:119], v[144:147]
	s_waitcnt lgkmcnt(0)
	v_mfma_f32_16x16x32_bf16 v[112:115], v[124:127], v[120:123], v[112:115]
	ds_read_b128 v[124:127], v0 offset:4096
	ds_read_b128 v[128:131], v0 offset:5120
	s_waitcnt lgkmcnt(1)
	v_mfma_f32_16x16x32_bf16 v[124:127], v[124:127], v[116:119], v[144:147]
	s_waitcnt lgkmcnt(0)
	v_mfma_f32_16x16x32_bf16 v[124:127], v[128:131], v[120:123], v[124:127]
	ds_read_b128 v[128:131], v0 offset:6144
	ds_read_b128 v[132:135], v0 offset:7168
	s_waitcnt lgkmcnt(1)
	v_mfma_f32_16x16x32_bf16 v[128:131], v[128:131], v[116:119], v[144:147]
	s_waitcnt lgkmcnt(0)
	v_mfma_f32_16x16x32_bf16 v[128:131], v[132:135], v[120:123], v[128:131]
	ds_read_b128 v[132:135], v0 offset:8192
	ds_read_b128 v[136:139], v0 offset:9216
	s_waitcnt lgkmcnt(1)
	v_mfma_f32_16x16x32_bf16 v[132:135], v[132:135], v[116:119], v[144:147]
	s_waitcnt lgkmcnt(0)
	v_mfma_f32_16x16x32_bf16 v[132:135], v[136:139], v[120:123], v[132:135]
	ds_read_b128 v[136:139], v0 offset:10240
	ds_read_b128 v[140:143], v0 offset:11264
	s_waitcnt lgkmcnt(1)
	v_mfma_f32_16x16x32_bf16 v[136:139], v[136:139], v[116:119], v[144:147]
	s_waitcnt lgkmcnt(0)
	v_mfma_f32_16x16x32_bf16 v[136:139], v[140:143], v[120:123], v[136:139]
	ds_read_b128 v[140:143], v0 offset:12288
	ds_read_b128 v[152:155], v0 offset:13312
	s_waitcnt lgkmcnt(1)
	v_mfma_f32_16x16x32_bf16 v[140:143], v[140:143], v[116:119], v[144:147]
	s_waitcnt lgkmcnt(0)
	v_mfma_f32_16x16x32_bf16 v[140:143], v[152:155], v[120:123], v[140:143]
	ds_read_b128 v[152:155], v0 offset:14336
	ds_read_b128 v[156:159], v0 offset:15360
	ds_write_b128 v185, v[16:19] offset:32768
	ds_write_b128 v185, v[20:23] offset:40960
	ds_write_b128 v185, v[24:27] offset:49152
	ds_write_b128 v185, v[28:31] offset:57344
	global_load_dwordx4 v[16:19], v[188:189], off offset:896
	global_load_dwordx4 v[20:23], v[190:191], off offset:896
	global_load_dwordx4 v[24:27], v[192:193], off offset:896
	global_load_dwordx4 v[28:31], v[194:195], off offset:896
	s_waitcnt lgkmcnt(5)
	v_mfma_f32_16x16x32_bf16 v[116:119], v[152:155], v[116:119], v[144:147]
	s_waitcnt lgkmcnt(0)
	s_barrier
	v_mfma_f32_16x16x32_bf16 v[144:147], v[156:159], v[120:123], v[116:119]
	ds_read_b128 v[216:219], v208 offset:49152
	ds_read_b128 v[220:223], v0 offset:32768
	ds_read_b128 v[224:227], v0 offset:33792
	ds_read_b128 v[228:231], v0 offset:34816
	ds_read_b128 v[232:235], v0 offset:35840
	ds_read_b128 v[236:239], v0 offset:36864
	ds_read_b128 v[240:243], v0 offset:37888
	ds_read_b128 v[244:247], v0 offset:38912
	ds_read_b128 v[248:251], v0 offset:39936
	v_add_co_u32_e32 v120, vcc, s1, v186
	s_mov_b32 s1, 0x10000
	s_nop 2
	v_cvt_pk_bf16_f32 v116, v148, v149
	v_cvt_pk_bf16_f32 v117, v150, v151
	v_cvt_pk_bf16_f32 v118, v112, v113
	v_cvt_pk_bf16_f32 v119, v114, v115
	v_addc_co_u32_e32 v121, vcc, 0, v187, vcc
	global_store_dwordx4 v[120:121], v[116:119], off
	v_pk_mul_f32 v[148:149], v[184:185], v[148:149] op_sel_hi:[0,1]
	v_pk_mul_f32 v[150:151], v[184:185], v[150:151] op_sel_hi:[0,1]
	v_cvt_pk_bf16_f32 v116, v124, v125
	v_cvt_pk_bf16_f32 v117, v126, v127
	v_cvt_pk_bf16_f32 v118, v128, v129
	v_cvt_pk_bf16_f32 v119, v130, v131
	global_store_dwordx4 v[120:121], v[116:119], off offset:1024
	v_pk_mul_f32 v[112:113], v[184:185], v[112:113] op_sel_hi:[0,1]
	v_pk_mul_f32 v[114:115], v[184:185], v[114:115] op_sel_hi:[0,1]
	v_cvt_pk_bf16_f32 v116, v132, v133
	v_cvt_pk_bf16_f32 v117, v134, v135
	v_cvt_pk_bf16_f32 v118, v136, v137
	v_cvt_pk_bf16_f32 v119, v138, v139
	global_store_dwordx4 v[120:121], v[116:119], off offset:2048
	v_pk_mul_f32 v[124:125], v[184:185], v[124:125] op_sel_hi:[0,1]
	v_pk_mul_f32 v[126:127], v[184:185], v[126:127] op_sel_hi:[0,1]
	v_cvt_pk_bf16_f32 v116, v140, v141
	v_cvt_pk_bf16_f32 v117, v142, v143
	v_cvt_pk_bf16_f32 v118, v144, v145
	v_cvt_pk_bf16_f32 v119, v146, v147
	global_store_dwordx4 v[120:121], v[116:119], off offset:3072
	ds_read_b128 v[116:119], v208 offset:50176
	s_waitcnt lgkmcnt(8)
	v_mfma_f32_16x16x32_bf16 v[148:151], v[220:223], v[216:219], v[148:151]
	ds_read_b128 v[220:223], v0 offset:40960
	v_mul_f32_e64 v128, v184, v128
	v_mul_f32_e64 v129, v184, v129
	v_pk_mul_f32 v[130:131], v[184:185], v[130:131] op_sel_hi:[0,1]
	v_pk_mul_f32 v[132:133], v[184:185], v[132:133] op_sel_hi:[0,1]
	s_waitcnt lgkmcnt(1)
	v_mfma_f32_16x16x32_bf16 v[148:151], v[224:227], v[116:119], v[148:151]
	ds_read_b128 v[224:227], v0 offset:41984
	v_pk_mul_f32 v[134:135], v[184:185], v[134:135] op_sel_hi:[0,1]
	v_pk_mul_f32 v[136:137], v[184:185], v[136:137] op_sel_hi:[0,1]
	s_waitcnt lgkmcnt(8)
	v_mfma_f32_16x16x32_bf16 v[112:115], v[228:231], v[216:219], v[112:115]
	ds_read_b128 v[228:231], v0 offset:43008
	v_mul_f32_e64 v138, v184, v138
	v_mul_f32_e64 v139, v184, v139
	v_pk_mul_f32 v[140:141], v[184:185], v[140:141] op_sel_hi:[0,1]
	v_pk_mul_f32 v[142:143], v[184:185], v[142:143] op_sel_hi:[0,1]
	s_waitcnt lgkmcnt(3)
	v_mfma_f32_16x16x32_bf16 v[112:115], v[232:235], v[116:119], v[112:115]
	ds_read_b128 v[232:235], v0 offset:44032
	v_pk_mul_f32 v[144:145], v[184:185], v[144:145] op_sel_hi:[0,1]
	v_pk_mul_f32 v[146:147], v[184:185], v[146:147] op_sel_hi:[0,1]
	s_waitcnt lgkmcnt(8)
	v_mfma_f32_16x16x32_bf16 v[124:127], v[236:239], v[216:219], v[124:127]
	ds_read_b128 v[236:239], v0 offset:45056
	s_waitcnt lgkmcnt(5)
	v_mfma_f32_16x16x32_bf16 v[124:127], v[240:243], v[116:119], v[124:127]
	ds_read_b128 v[240:243], v0 offset:46080
	s_waitcnt lgkmcnt(8)
	v_mfma_f32_16x16x32_bf16 v[128:131], v[244:247], v[216:219], v[128:131]
	ds_read_b128 v[244:247], v0 offset:47104
	s_waitcnt lgkmcnt(7)
	v_mfma_f32_16x16x32_bf16 v[128:131], v[248:251], v[116:119], v[128:131]
	s_waitcnt lgkmcnt(6)
	v_mfma_f32_16x16x32_bf16 v[132:135], v[220:223], v[216:219], v[132:135]
	s_waitcnt lgkmcnt(5)
	v_mfma_f32_16x16x32_bf16 v[132:135], v[224:227], v[116:119], v[132:135]
	s_waitcnt lgkmcnt(4)
	v_mfma_f32_16x16x32_bf16 v[136:139], v[228:231], v[216:219], v[136:139]
	s_waitcnt lgkmcnt(3)
	v_mfma_f32_16x16x32_bf16 v[136:139], v[232:235], v[116:119], v[136:139]
	s_waitcnt lgkmcnt(2)
	v_mfma_f32_16x16x32_bf16 v[140:143], v[236:239], v[216:219], v[140:143]
	s_waitcnt lgkmcnt(1)
	v_mfma_f32_16x16x32_bf16 v[140:143], v[240:243], v[116:119], v[140:143]
	ds_read_b128 v[156:159], v0 offset:48128
	ds_write_b128 v185, v[32:35]
	ds_write_b128 v185, v[36:39] offset:8192
	ds_write_b128 v185, v[40:43] offset:16384
	ds_write_b128 v185, v[44:47] offset:24576
	global_load_dwordx4 v[32:35], v[188:189], off offset:1024
	global_load_dwordx4 v[36:39], v[190:191], off offset:1024
	global_load_dwordx4 v[40:43], v[192:193], off offset:1024
	global_load_dwordx4 v[44:47], v[194:195], off offset:1024
	s_waitcnt lgkmcnt(5)
	v_mfma_f32_16x16x32_bf16 v[120:123], v[244:247], v[216:219], v[144:147]
	s_waitcnt lgkmcnt(0)
	s_barrier
	v_mfma_f32_16x16x32_bf16 v[144:147], v[156:159], v[116:119], v[120:123]
	ds_read_b128 v[216:219], v208 offset:16384
	ds_read_b128 v[220:223], v0
	ds_read_b128 v[224:227], v0 offset:1024
	ds_read_b128 v[228:231], v0 offset:2048
	ds_read_b128 v[232:235], v0 offset:3072
	ds_read_b128 v[236:239], v0 offset:4096
	ds_read_b128 v[240:243], v0 offset:5120
	ds_read_b128 v[244:247], v0 offset:6144
	ds_read_b128 v[248:251], v0 offset:7168
	v_cvt_pk_bf16_f32 v116, v148, v149
	v_cvt_pk_bf16_f32 v117, v150, v151
	v_cvt_pk_bf16_f32 v118, v112, v113
	s_nop 1
	v_add_co_u32_e32 v120, vcc, s1, v186
	v_cvt_pk_bf16_f32 v119, v114, v115
	s_nop 0
	v_addc_co_u32_e32 v121, vcc, 0, v187, vcc
	global_store_dwordx4 v[120:121], v[116:119], off
	v_pk_mul_f32 v[150:151], v[184:185], v[150:151] op_sel_hi:[0,1]
	v_pk_mul_f32 v[148:149], v[184:185], v[148:149] op_sel_hi:[0,1]
	v_cvt_pk_bf16_f32 v116, v124, v125
	v_cvt_pk_bf16_f32 v117, v126, v127
	v_cvt_pk_bf16_f32 v118, v128, v129
	v_cvt_pk_bf16_f32 v119, v130, v131
	global_store_dwordx4 v[120:121], v[116:119], off offset:1024
	v_pk_mul_f32 v[114:115], v[184:185], v[114:115] op_sel_hi:[0,1]
	v_pk_mul_f32 v[112:113], v[184:185], v[112:113] op_sel_hi:[0,1]
	v_cvt_pk_bf16_f32 v116, v132, v133
	v_cvt_pk_bf16_f32 v117, v134, v135
	v_cvt_pk_bf16_f32 v118, v136, v137
	v_cvt_pk_bf16_f32 v119, v138, v139
	global_store_dwordx4 v[120:121], v[116:119], off offset:2048
	v_pk_mul_f32 v[126:127], v[184:185], v[126:127] op_sel_hi:[0,1]
	v_pk_mul_f32 v[124:125], v[184:185], v[124:125] op_sel_hi:[0,1]
	v_cvt_pk_bf16_f32 v116, v140, v141
	v_cvt_pk_bf16_f32 v117, v142, v143
	v_cvt_pk_bf16_f32 v118, v144, v145
	v_cvt_pk_bf16_f32 v119, v146, v147
	global_store_dwordx4 v[120:121], v[116:119], off offset:3072
	ds_read_b128 v[116:119], v208 offset:17408
	s_waitcnt lgkmcnt(8)
	v_mfma_f32_16x16x32_bf16 v[148:151], v[220:223], v[216:219], v[148:151]
	ds_read_b128 v[220:223], v0 offset:8192
	v_mul_f32_e64 v130, v184, v130
	v_mul_f32_e64 v131, v184, v131
	v_pk_mul_f32 v[128:129], v[184:185], v[128:129] op_sel_hi:[0,1]
	v_pk_mul_f32 v[134:135], v[184:185], v[134:135] op_sel_hi:[0,1]
	s_waitcnt lgkmcnt(1)
	v_mfma_f32_16x16x32_bf16 v[148:151], v[224:227], v[116:119], v[148:151]
	ds_read_b128 v[224:227], v0 offset:9216
	v_pk_mul_f32 v[132:133], v[184:185], v[132:133] op_sel_hi:[0,1]
	v_pk_mul_f32 v[138:139], v[184:185], v[138:139] op_sel_hi:[0,1]
	s_waitcnt lgkmcnt(8)
	v_mfma_f32_16x16x32_bf16 v[112:115], v[228:231], v[216:219], v[112:115]
	ds_read_b128 v[228:231], v0 offset:10240
	v_mul_f32_e64 v136, v184, v136
	v_mul_f32_e64 v137, v184, v137
	v_pk_mul_f32 v[142:143], v[184:185], v[142:143] op_sel_hi:[0,1]
	v_pk_mul_f32 v[140:141], v[184:185], v[140:141] op_sel_hi:[0,1]
	s_waitcnt lgkmcnt(3)
	v_mfma_f32_16x16x32_bf16 v[112:115], v[232:235], v[116:119], v[112:115]
	ds_read_b128 v[232:235], v0 offset:11264
	v_pk_mul_f32 v[146:147], v[184:185], v[146:147] op_sel_hi:[0,1]
	v_pk_mul_f32 v[144:145], v[184:185], v[144:145] op_sel_hi:[0,1]
	s_waitcnt lgkmcnt(8)
	v_mfma_f32_16x16x32_bf16 v[124:127], v[236:239], v[216:219], v[124:127]
	ds_read_b128 v[236:239], v0 offset:12288
	s_mov_b32 s1, 0x18000
	s_waitcnt lgkmcnt(5)
	v_mfma_f32_16x16x32_bf16 v[124:127], v[240:243], v[116:119], v[124:127]
	ds_read_b128 v[240:243], v0 offset:13312
	s_waitcnt lgkmcnt(8)
	v_mfma_f32_16x16x32_bf16 v[128:131], v[244:247], v[216:219], v[128:131]
	ds_read_b128 v[244:247], v0 offset:14336
	s_waitcnt lgkmcnt(7)
	v_mfma_f32_16x16x32_bf16 v[128:131], v[248:251], v[116:119], v[128:131]
	s_waitcnt lgkmcnt(6)
	v_mfma_f32_16x16x32_bf16 v[132:135], v[220:223], v[216:219], v[132:135]
	s_waitcnt lgkmcnt(5)
	v_mfma_f32_16x16x32_bf16 v[132:135], v[224:227], v[116:119], v[132:135]
	s_waitcnt lgkmcnt(4)
	v_mfma_f32_16x16x32_bf16 v[136:139], v[228:231], v[216:219], v[136:139]
	s_waitcnt lgkmcnt(3)
	v_mfma_f32_16x16x32_bf16 v[136:139], v[232:235], v[116:119], v[136:139]
	s_waitcnt lgkmcnt(2)
	v_mfma_f32_16x16x32_bf16 v[140:143], v[236:239], v[216:219], v[140:143]
	s_waitcnt lgkmcnt(1)
	v_mfma_f32_16x16x32_bf16 v[140:143], v[240:243], v[116:119], v[140:143]
	ds_read_b128 v[156:159], v0 offset:15360
	ds_write_b128 v185, v[48:51] offset:32768
	ds_write_b128 v185, v[52:55] offset:40960
	ds_write_b128 v185, v[56:59] offset:49152
	ds_write_b128 v185, v[60:63] offset:57344
	global_load_dwordx4 v[48:51], v[188:189], off offset:1152
	global_load_dwordx4 v[52:55], v[190:191], off offset:1152
	global_load_dwordx4 v[56:59], v[192:193], off offset:1152
	global_load_dwordx4 v[60:63], v[194:195], off offset:1152
	s_waitcnt lgkmcnt(5)
	v_mfma_f32_16x16x32_bf16 v[120:123], v[244:247], v[216:219], v[144:147]
	s_waitcnt lgkmcnt(0)
	s_barrier
	v_mfma_f32_16x16x32_bf16 v[144:147], v[156:159], v[116:119], v[120:123]
	ds_read_b128 v[216:219], v208 offset:49152
	ds_read_b128 v[220:223], v0 offset:32768
	ds_read_b128 v[224:227], v0 offset:33792
	ds_read_b128 v[228:231], v0 offset:34816
	ds_read_b128 v[232:235], v0 offset:35840
	ds_read_b128 v[236:239], v0 offset:36864
	ds_read_b128 v[240:243], v0 offset:37888
	ds_read_b128 v[244:247], v0 offset:38912
	ds_read_b128 v[248:251], v0 offset:39936
	v_cvt_pk_bf16_f32 v116, v148, v149
	v_cvt_pk_bf16_f32 v117, v150, v151
	v_cvt_pk_bf16_f32 v118, v112, v113
	s_nop 1
	v_add_co_u32_e32 v120, vcc, s1, v186
	v_cvt_pk_bf16_f32 v119, v114, v115
	s_nop 0
	v_addc_co_u32_e32 v121, vcc, 0, v187, vcc
	global_store_dwordx4 v[120:121], v[116:119], off
	v_pk_mul_f32 v[150:151], v[184:185], v[150:151] op_sel_hi:[0,1]
	v_pk_mul_f32 v[148:149], v[184:185], v[148:149] op_sel_hi:[0,1]
	v_cvt_pk_bf16_f32 v116, v124, v125
	v_cvt_pk_bf16_f32 v117, v126, v127
	v_cvt_pk_bf16_f32 v118, v128, v129
	v_cvt_pk_bf16_f32 v119, v130, v131
	global_store_dwordx4 v[120:121], v[116:119], off offset:1024
	v_pk_mul_f32 v[114:115], v[184:185], v[114:115] op_sel_hi:[0,1]
	v_pk_mul_f32 v[112:113], v[184:185], v[112:113] op_sel_hi:[0,1]
	v_cvt_pk_bf16_f32 v116, v132, v133
	v_cvt_pk_bf16_f32 v117, v134, v135
	v_cvt_pk_bf16_f32 v118, v136, v137
	v_cvt_pk_bf16_f32 v119, v138, v139
	global_store_dwordx4 v[120:121], v[116:119], off offset:2048
	v_pk_mul_f32 v[126:127], v[184:185], v[126:127] op_sel_hi:[0,1]
	v_pk_mul_f32 v[124:125], v[184:185], v[124:125] op_sel_hi:[0,1]
	v_cvt_pk_bf16_f32 v116, v140, v141
	v_cvt_pk_bf16_f32 v117, v142, v143
	v_cvt_pk_bf16_f32 v118, v144, v145
	v_cvt_pk_bf16_f32 v119, v146, v147
	global_store_dwordx4 v[120:121], v[116:119], off offset:3072
	ds_read_b128 v[116:119], v208 offset:50176
	s_waitcnt lgkmcnt(8)
	v_mfma_f32_16x16x32_bf16 v[148:151], v[220:223], v[216:219], v[148:151]
	ds_read_b128 v[220:223], v0 offset:40960
	v_mul_f32_e64 v130, v184, v130
	v_mul_f32_e64 v131, v184, v131
	v_pk_mul_f32 v[128:129], v[184:185], v[128:129] op_sel_hi:[0,1]
	v_pk_mul_f32 v[134:135], v[184:185], v[134:135] op_sel_hi:[0,1]
	s_waitcnt lgkmcnt(1)
	v_mfma_f32_16x16x32_bf16 v[148:151], v[224:227], v[116:119], v[148:151]
	ds_read_b128 v[224:227], v0 offset:41984
	v_pk_mul_f32 v[132:133], v[184:185], v[132:133] op_sel_hi:[0,1]
	v_pk_mul_f32 v[138:139], v[184:185], v[138:139] op_sel_hi:[0,1]
	s_waitcnt lgkmcnt(8)
	v_mfma_f32_16x16x32_bf16 v[112:115], v[228:231], v[216:219], v[112:115]
	ds_read_b128 v[228:231], v0 offset:43008
	v_mul_f32_e64 v136, v184, v136
	v_mul_f32_e64 v137, v184, v137
	v_pk_mul_f32 v[142:143], v[184:185], v[142:143] op_sel_hi:[0,1]
	v_pk_mul_f32 v[140:141], v[184:185], v[140:141] op_sel_hi:[0,1]
	s_waitcnt lgkmcnt(3)
	v_mfma_f32_16x16x32_bf16 v[112:115], v[232:235], v[116:119], v[112:115]
	ds_read_b128 v[232:235], v0 offset:44032
	v_pk_mul_f32 v[146:147], v[184:185], v[146:147] op_sel_hi:[0,1]
	v_pk_mul_f32 v[144:145], v[184:185], v[144:145] op_sel_hi:[0,1]
	s_waitcnt lgkmcnt(8)
	v_mfma_f32_16x16x32_bf16 v[124:127], v[236:239], v[216:219], v[124:127]
	ds_read_b128 v[236:239], v0 offset:45056
	s_mov_b32 s1, 0x20000
	s_waitcnt lgkmcnt(5)
	v_mfma_f32_16x16x32_bf16 v[124:127], v[240:243], v[116:119], v[124:127]
	ds_read_b128 v[240:243], v0 offset:46080
	s_waitcnt lgkmcnt(8)
	v_mfma_f32_16x16x32_bf16 v[128:131], v[244:247], v[216:219], v[128:131]
	ds_read_b128 v[244:247], v0 offset:47104
	s_waitcnt lgkmcnt(7)
	v_mfma_f32_16x16x32_bf16 v[128:131], v[248:251], v[116:119], v[128:131]
	s_waitcnt lgkmcnt(6)
	v_mfma_f32_16x16x32_bf16 v[132:135], v[220:223], v[216:219], v[132:135]
	s_waitcnt lgkmcnt(5)
	v_mfma_f32_16x16x32_bf16 v[132:135], v[224:227], v[116:119], v[132:135]
	s_waitcnt lgkmcnt(4)
	v_mfma_f32_16x16x32_bf16 v[136:139], v[228:231], v[216:219], v[136:139]
	s_waitcnt lgkmcnt(3)
	v_mfma_f32_16x16x32_bf16 v[136:139], v[232:235], v[116:119], v[136:139]
	s_waitcnt lgkmcnt(2)
	v_mfma_f32_16x16x32_bf16 v[140:143], v[236:239], v[216:219], v[140:143]
	s_waitcnt lgkmcnt(1)
	v_mfma_f32_16x16x32_bf16 v[140:143], v[240:243], v[116:119], v[140:143]
	ds_read_b128 v[156:159], v0 offset:48128
	ds_write_b128 v185, v[64:67]
	ds_write_b128 v185, v[68:71] offset:8192
	ds_write_b128 v185, v[72:75] offset:16384
	ds_write_b128 v185, v[76:79] offset:24576
	global_load_dwordx4 v[64:67], v[188:189], off offset:1280
	global_load_dwordx4 v[68:71], v[190:191], off offset:1280
	global_load_dwordx4 v[72:75], v[192:193], off offset:1280
	global_load_dwordx4 v[76:79], v[194:195], off offset:1280
	s_waitcnt lgkmcnt(5)
	v_mfma_f32_16x16x32_bf16 v[120:123], v[244:247], v[216:219], v[144:147]
	s_waitcnt lgkmcnt(0)
	s_barrier
	v_mfma_f32_16x16x32_bf16 v[144:147], v[156:159], v[116:119], v[120:123]
	ds_read_b128 v[216:219], v208 offset:16384
	ds_read_b128 v[220:223], v0
	ds_read_b128 v[224:227], v0 offset:1024
	ds_read_b128 v[228:231], v0 offset:2048
	ds_read_b128 v[232:235], v0 offset:3072
	ds_read_b128 v[236:239], v0 offset:4096
	ds_read_b128 v[240:243], v0 offset:5120
	ds_read_b128 v[244:247], v0 offset:6144
	ds_read_b128 v[248:251], v0 offset:7168
	v_cvt_pk_bf16_f32 v116, v148, v149
	v_cvt_pk_bf16_f32 v117, v150, v151
	v_cvt_pk_bf16_f32 v118, v112, v113
	s_nop 1
	v_add_co_u32_e32 v120, vcc, s1, v186
	v_cvt_pk_bf16_f32 v119, v114, v115
	s_nop 0
	v_addc_co_u32_e32 v121, vcc, 0, v187, vcc
	global_store_dwordx4 v[120:121], v[116:119], off
	v_pk_mul_f32 v[150:151], v[184:185], v[150:151] op_sel_hi:[0,1]
	v_pk_mul_f32 v[148:149], v[184:185], v[148:149] op_sel_hi:[0,1]
	v_cvt_pk_bf16_f32 v116, v124, v125
	v_cvt_pk_bf16_f32 v117, v126, v127
	v_cvt_pk_bf16_f32 v118, v128, v129
	v_cvt_pk_bf16_f32 v119, v130, v131
	global_store_dwordx4 v[120:121], v[116:119], off offset:1024
	v_pk_mul_f32 v[114:115], v[184:185], v[114:115] op_sel_hi:[0,1]
	v_pk_mul_f32 v[112:113], v[184:185], v[112:113] op_sel_hi:[0,1]
	v_cvt_pk_bf16_f32 v116, v132, v133
	v_cvt_pk_bf16_f32 v117, v134, v135
	v_cvt_pk_bf16_f32 v118, v136, v137
	v_cvt_pk_bf16_f32 v119, v138, v139
	global_store_dwordx4 v[120:121], v[116:119], off offset:2048
	v_pk_mul_f32 v[126:127], v[184:185], v[126:127] op_sel_hi:[0,1]
	v_pk_mul_f32 v[124:125], v[184:185], v[124:125] op_sel_hi:[0,1]
	v_cvt_pk_bf16_f32 v116, v140, v141
	v_cvt_pk_bf16_f32 v117, v142, v143
	v_cvt_pk_bf16_f32 v118, v144, v145
	v_cvt_pk_bf16_f32 v119, v146, v147
	global_store_dwordx4 v[120:121], v[116:119], off offset:3072
	ds_read_b128 v[116:119], v208 offset:17408
	s_waitcnt lgkmcnt(8)
	v_mfma_f32_16x16x32_bf16 v[148:151], v[220:223], v[216:219], v[148:151]
	ds_read_b128 v[220:223], v0 offset:8192
	v_mul_f32_e64 v130, v184, v130
	v_mul_f32_e64 v131, v184, v131
	v_pk_mul_f32 v[128:129], v[184:185], v[128:129] op_sel_hi:[0,1]
	v_pk_mul_f32 v[134:135], v[184:185], v[134:135] op_sel_hi:[0,1]
	s_waitcnt lgkmcnt(1)
	v_mfma_f32_16x16x32_bf16 v[148:151], v[224:227], v[116:119], v[148:151]
	ds_read_b128 v[224:227], v0 offset:9216
	v_pk_mul_f32 v[132:133], v[184:185], v[132:133] op_sel_hi:[0,1]
	v_pk_mul_f32 v[138:139], v[184:185], v[138:139] op_sel_hi:[0,1]
	s_waitcnt lgkmcnt(8)
	v_mfma_f32_16x16x32_bf16 v[112:115], v[228:231], v[216:219], v[112:115]
	ds_read_b128 v[228:231], v0 offset:10240
	v_mul_f32_e64 v136, v184, v136
	v_mul_f32_e64 v137, v184, v137
	v_pk_mul_f32 v[142:143], v[184:185], v[142:143] op_sel_hi:[0,1]
	v_pk_mul_f32 v[140:141], v[184:185], v[140:141] op_sel_hi:[0,1]
	s_waitcnt lgkmcnt(3)
	v_mfma_f32_16x16x32_bf16 v[112:115], v[232:235], v[116:119], v[112:115]
	ds_read_b128 v[232:235], v0 offset:11264
	v_pk_mul_f32 v[146:147], v[184:185], v[146:147] op_sel_hi:[0,1]
	v_pk_mul_f32 v[144:145], v[184:185], v[144:145] op_sel_hi:[0,1]
	s_waitcnt lgkmcnt(8)
	v_mfma_f32_16x16x32_bf16 v[124:127], v[236:239], v[216:219], v[124:127]
	ds_read_b128 v[236:239], v0 offset:12288
	s_mov_b32 s1, 0x28000
	s_waitcnt lgkmcnt(5)
	v_mfma_f32_16x16x32_bf16 v[124:127], v[240:243], v[116:119], v[124:127]
	ds_read_b128 v[240:243], v0 offset:13312
	s_waitcnt lgkmcnt(8)
	v_mfma_f32_16x16x32_bf16 v[128:131], v[244:247], v[216:219], v[128:131]
	ds_read_b128 v[244:247], v0 offset:14336
	s_waitcnt lgkmcnt(7)
	v_mfma_f32_16x16x32_bf16 v[128:131], v[248:251], v[116:119], v[128:131]
	s_waitcnt lgkmcnt(6)
	v_mfma_f32_16x16x32_bf16 v[132:135], v[220:223], v[216:219], v[132:135]
	s_waitcnt lgkmcnt(5)
	v_mfma_f32_16x16x32_bf16 v[132:135], v[224:227], v[116:119], v[132:135]
	s_waitcnt lgkmcnt(4)
	v_mfma_f32_16x16x32_bf16 v[136:139], v[228:231], v[216:219], v[136:139]
	s_waitcnt lgkmcnt(3)
	v_mfma_f32_16x16x32_bf16 v[136:139], v[232:235], v[116:119], v[136:139]
	s_waitcnt lgkmcnt(2)
	v_mfma_f32_16x16x32_bf16 v[140:143], v[236:239], v[216:219], v[140:143]
	s_waitcnt lgkmcnt(1)
	v_mfma_f32_16x16x32_bf16 v[140:143], v[240:243], v[116:119], v[140:143]
	ds_read_b128 v[156:159], v0 offset:15360
	ds_write_b128 v185, v[80:83] offset:32768
	ds_write_b128 v185, v[84:87] offset:40960
	ds_write_b128 v185, v[88:91] offset:49152
	ds_write_b128 v185, v[92:95] offset:57344
	global_load_dwordx4 v[80:83], v[188:189], off offset:1408
	global_load_dwordx4 v[84:87], v[190:191], off offset:1408
	global_load_dwordx4 v[88:91], v[192:193], off offset:1408
	global_load_dwordx4 v[92:95], v[194:195], off offset:1408
	s_waitcnt lgkmcnt(5)
	v_mfma_f32_16x16x32_bf16 v[120:123], v[244:247], v[216:219], v[144:147]
	s_waitcnt lgkmcnt(0)
	s_barrier
	v_mfma_f32_16x16x32_bf16 v[144:147], v[156:159], v[116:119], v[120:123]
	ds_read_b128 v[216:219], v208 offset:49152
	ds_read_b128 v[220:223], v0 offset:32768
	ds_read_b128 v[224:227], v0 offset:33792
	ds_read_b128 v[228:231], v0 offset:34816
	ds_read_b128 v[232:235], v0 offset:35840
	ds_read_b128 v[236:239], v0 offset:36864
	ds_read_b128 v[240:243], v0 offset:37888
	ds_read_b128 v[244:247], v0 offset:38912
	ds_read_b128 v[248:251], v0 offset:39936
	v_cvt_pk_bf16_f32 v116, v148, v149
	v_cvt_pk_bf16_f32 v117, v150, v151
	v_cvt_pk_bf16_f32 v118, v112, v113
	s_nop 1
	v_add_co_u32_e32 v120, vcc, s1, v186
	v_cvt_pk_bf16_f32 v119, v114, v115
	s_nop 0
	v_addc_co_u32_e32 v121, vcc, 0, v187, vcc
	global_store_dwordx4 v[120:121], v[116:119], off
	v_pk_mul_f32 v[150:151], v[184:185], v[150:151] op_sel_hi:[0,1]
	v_pk_mul_f32 v[148:149], v[184:185], v[148:149] op_sel_hi:[0,1]
	v_cvt_pk_bf16_f32 v116, v124, v125
	v_cvt_pk_bf16_f32 v117, v126, v127
	v_cvt_pk_bf16_f32 v118, v128, v129
	v_cvt_pk_bf16_f32 v119, v130, v131
	global_store_dwordx4 v[120:121], v[116:119], off offset:1024
	v_pk_mul_f32 v[114:115], v[184:185], v[114:115] op_sel_hi:[0,1]
	v_pk_mul_f32 v[112:113], v[184:185], v[112:113] op_sel_hi:[0,1]
	v_cvt_pk_bf16_f32 v116, v132, v133
	v_cvt_pk_bf16_f32 v117, v134, v135
	v_cvt_pk_bf16_f32 v118, v136, v137
	v_cvt_pk_bf16_f32 v119, v138, v139
	global_store_dwordx4 v[120:121], v[116:119], off offset:2048
	v_pk_mul_f32 v[126:127], v[184:185], v[126:127] op_sel_hi:[0,1]
	v_pk_mul_f32 v[124:125], v[184:185], v[124:125] op_sel_hi:[0,1]
	v_cvt_pk_bf16_f32 v116, v140, v141
	v_cvt_pk_bf16_f32 v117, v142, v143
	v_cvt_pk_bf16_f32 v118, v144, v145
	v_cvt_pk_bf16_f32 v119, v146, v147
	global_store_dwordx4 v[120:121], v[116:119], off offset:3072
	ds_read_b128 v[116:119], v208 offset:50176
	s_waitcnt lgkmcnt(8)
	v_mfma_f32_16x16x32_bf16 v[148:151], v[220:223], v[216:219], v[148:151]
	ds_read_b128 v[220:223], v0 offset:40960
	v_mul_f32_e64 v130, v184, v130
	v_mul_f32_e64 v131, v184, v131
	v_pk_mul_f32 v[128:129], v[184:185], v[128:129] op_sel_hi:[0,1]
	v_pk_mul_f32 v[134:135], v[184:185], v[134:135] op_sel_hi:[0,1]
	s_waitcnt lgkmcnt(1)
	v_mfma_f32_16x16x32_bf16 v[148:151], v[224:227], v[116:119], v[148:151]
	ds_read_b128 v[224:227], v0 offset:41984
	v_pk_mul_f32 v[132:133], v[184:185], v[132:133] op_sel_hi:[0,1]
	v_pk_mul_f32 v[138:139], v[184:185], v[138:139] op_sel_hi:[0,1]
	s_waitcnt lgkmcnt(8)
	v_mfma_f32_16x16x32_bf16 v[112:115], v[228:231], v[216:219], v[112:115]
	ds_read_b128 v[228:231], v0 offset:43008
	v_mul_f32_e64 v136, v184, v136
	v_mul_f32_e64 v137, v184, v137
	v_pk_mul_f32 v[142:143], v[184:185], v[142:143] op_sel_hi:[0,1]
	v_pk_mul_f32 v[140:141], v[184:185], v[140:141] op_sel_hi:[0,1]
	s_waitcnt lgkmcnt(3)
	v_mfma_f32_16x16x32_bf16 v[112:115], v[232:235], v[116:119], v[112:115]
	ds_read_b128 v[232:235], v0 offset:44032
	v_pk_mul_f32 v[146:147], v[184:185], v[146:147] op_sel_hi:[0,1]
	v_pk_mul_f32 v[144:145], v[184:185], v[144:145] op_sel_hi:[0,1]
	s_waitcnt lgkmcnt(8)
	v_mfma_f32_16x16x32_bf16 v[124:127], v[236:239], v[216:219], v[124:127]
	ds_read_b128 v[236:239], v0 offset:45056
	s_mov_b32 s1, 0x30000
	s_waitcnt lgkmcnt(5)
	v_mfma_f32_16x16x32_bf16 v[124:127], v[240:243], v[116:119], v[124:127]
	ds_read_b128 v[240:243], v0 offset:46080
	s_waitcnt lgkmcnt(8)
	v_mfma_f32_16x16x32_bf16 v[128:131], v[244:247], v[216:219], v[128:131]
	ds_read_b128 v[244:247], v0 offset:47104
	s_waitcnt lgkmcnt(7)
	v_mfma_f32_16x16x32_bf16 v[128:131], v[248:251], v[116:119], v[128:131]
	s_waitcnt lgkmcnt(6)
	v_mfma_f32_16x16x32_bf16 v[132:135], v[220:223], v[216:219], v[132:135]
	s_waitcnt lgkmcnt(5)
	v_mfma_f32_16x16x32_bf16 v[132:135], v[224:227], v[116:119], v[132:135]
	s_waitcnt lgkmcnt(4)
	v_mfma_f32_16x16x32_bf16 v[136:139], v[228:231], v[216:219], v[136:139]
	s_waitcnt lgkmcnt(3)
	v_mfma_f32_16x16x32_bf16 v[136:139], v[232:235], v[116:119], v[136:139]
	s_waitcnt lgkmcnt(2)
	v_mfma_f32_16x16x32_bf16 v[140:143], v[236:239], v[216:219], v[140:143]
	s_waitcnt lgkmcnt(1)
	v_mfma_f32_16x16x32_bf16 v[140:143], v[240:243], v[116:119], v[140:143]
	ds_read_b128 v[156:159], v0 offset:48128
	s_waitcnt vmcnt(47)
	ds_write_b128 v185, v[96:99]
	s_waitcnt vmcnt(46)
	ds_write_b128 v185, v[100:103] offset:8192
	s_waitcnt vmcnt(45)
	ds_write_b128 v185, v[104:107] offset:16384
	s_waitcnt vmcnt(44)
	ds_write_b128 v185, v[108:111] offset:24576
	global_load_dwordx4 v[96:99], v[188:189], off offset:1536
	global_load_dwordx4 v[100:103], v[190:191], off offset:1536
	global_load_dwordx4 v[104:107], v[192:193], off offset:1536
	global_load_dwordx4 v[108:111], v[194:195], off offset:1536
	s_waitcnt lgkmcnt(5)
	v_mfma_f32_16x16x32_bf16 v[120:123], v[244:247], v[216:219], v[144:147]
	s_waitcnt lgkmcnt(0)
	s_barrier
	v_mfma_f32_16x16x32_bf16 v[144:147], v[156:159], v[116:119], v[120:123]
	ds_read_b128 v[216:219], v208 offset:16384
	ds_read_b128 v[220:223], v0
	ds_read_b128 v[224:227], v0 offset:1024
	ds_read_b128 v[228:231], v0 offset:2048
	ds_read_b128 v[232:235], v0 offset:3072
	ds_read_b128 v[236:239], v0 offset:4096
	ds_read_b128 v[240:243], v0 offset:5120
	ds_read_b128 v[244:247], v0 offset:6144
	ds_read_b128 v[248:251], v0 offset:7168
	v_cvt_pk_bf16_f32 v116, v148, v149
	v_cvt_pk_bf16_f32 v117, v150, v151
	v_cvt_pk_bf16_f32 v118, v112, v113
	s_nop 1
	v_add_co_u32_e32 v120, vcc, s1, v186
	v_cvt_pk_bf16_f32 v119, v114, v115
	s_nop 0
	v_addc_co_u32_e32 v121, vcc, 0, v187, vcc
	global_store_dwordx4 v[120:121], v[116:119], off
	v_pk_mul_f32 v[150:151], v[184:185], v[150:151] op_sel_hi:[0,1]
	v_pk_mul_f32 v[148:149], v[184:185], v[148:149] op_sel_hi:[0,1]
	v_cvt_pk_bf16_f32 v116, v124, v125
	v_cvt_pk_bf16_f32 v117, v126, v127
	v_cvt_pk_bf16_f32 v118, v128, v129
	v_cvt_pk_bf16_f32 v119, v130, v131
	global_store_dwordx4 v[120:121], v[116:119], off offset:1024
	v_pk_mul_f32 v[114:115], v[184:185], v[114:115] op_sel_hi:[0,1]
	v_pk_mul_f32 v[112:113], v[184:185], v[112:113] op_sel_hi:[0,1]
	v_cvt_pk_bf16_f32 v116, v132, v133
	v_cvt_pk_bf16_f32 v117, v134, v135
	v_cvt_pk_bf16_f32 v118, v136, v137
	v_cvt_pk_bf16_f32 v119, v138, v139
	global_store_dwordx4 v[120:121], v[116:119], off offset:2048
	v_pk_mul_f32 v[126:127], v[184:185], v[126:127] op_sel_hi:[0,1]
	v_pk_mul_f32 v[124:125], v[184:185], v[124:125] op_sel_hi:[0,1]
	v_cvt_pk_bf16_f32 v116, v140, v141
	v_cvt_pk_bf16_f32 v117, v142, v143
	v_cvt_pk_bf16_f32 v118, v144, v145
	v_cvt_pk_bf16_f32 v119, v146, v147
	global_store_dwordx4 v[120:121], v[116:119], off offset:3072
	ds_read_b128 v[116:119], v208 offset:17408
	s_waitcnt lgkmcnt(8)
	v_mfma_f32_16x16x32_bf16 v[148:151], v[220:223], v[216:219], v[148:151]
	ds_read_b128 v[220:223], v0 offset:8192
	v_mul_f32_e64 v130, v184, v130
	v_mul_f32_e64 v131, v184, v131
	v_pk_mul_f32 v[128:129], v[184:185], v[128:129] op_sel_hi:[0,1]
	v_pk_mul_f32 v[134:135], v[184:185], v[134:135] op_sel_hi:[0,1]
	s_waitcnt lgkmcnt(1)
	v_mfma_f32_16x16x32_bf16 v[148:151], v[224:227], v[116:119], v[148:151]
	ds_read_b128 v[224:227], v0 offset:9216
	v_pk_mul_f32 v[132:133], v[184:185], v[132:133] op_sel_hi:[0,1]
	v_pk_mul_f32 v[138:139], v[184:185], v[138:139] op_sel_hi:[0,1]
	s_waitcnt lgkmcnt(8)
	v_mfma_f32_16x16x32_bf16 v[112:115], v[228:231], v[216:219], v[112:115]
	ds_read_b128 v[228:231], v0 offset:10240
	v_mul_f32_e64 v136, v184, v136
	v_mul_f32_e64 v137, v184, v137
	v_pk_mul_f32 v[142:143], v[184:185], v[142:143] op_sel_hi:[0,1]
	v_pk_mul_f32 v[140:141], v[184:185], v[140:141] op_sel_hi:[0,1]
	s_waitcnt lgkmcnt(3)
	v_mfma_f32_16x16x32_bf16 v[112:115], v[232:235], v[116:119], v[112:115]
	ds_read_b128 v[232:235], v0 offset:11264
	v_pk_mul_f32 v[146:147], v[184:185], v[146:147] op_sel_hi:[0,1]
	v_pk_mul_f32 v[144:145], v[184:185], v[144:145] op_sel_hi:[0,1]
	s_waitcnt lgkmcnt(8)
	v_mfma_f32_16x16x32_bf16 v[124:127], v[236:239], v[216:219], v[124:127]
	ds_read_b128 v[236:239], v0 offset:12288
	s_mov_b32 s1, 0x38000
	s_waitcnt lgkmcnt(5)
	v_mfma_f32_16x16x32_bf16 v[124:127], v[240:243], v[116:119], v[124:127]
	ds_read_b128 v[240:243], v0 offset:13312
	s_waitcnt lgkmcnt(8)
	v_mfma_f32_16x16x32_bf16 v[128:131], v[244:247], v[216:219], v[128:131]
	ds_read_b128 v[244:247], v0 offset:14336
	s_waitcnt lgkmcnt(7)
	v_mfma_f32_16x16x32_bf16 v[128:131], v[248:251], v[116:119], v[128:131]
	s_waitcnt lgkmcnt(6)
	v_mfma_f32_16x16x32_bf16 v[132:135], v[220:223], v[216:219], v[132:135]
	s_waitcnt lgkmcnt(5)
	v_mfma_f32_16x16x32_bf16 v[132:135], v[224:227], v[116:119], v[132:135]
	s_waitcnt lgkmcnt(4)
	v_mfma_f32_16x16x32_bf16 v[136:139], v[228:231], v[216:219], v[136:139]
	s_waitcnt lgkmcnt(3)
	v_mfma_f32_16x16x32_bf16 v[136:139], v[232:235], v[116:119], v[136:139]
	s_waitcnt lgkmcnt(2)
	v_mfma_f32_16x16x32_bf16 v[140:143], v[236:239], v[216:219], v[140:143]
	s_waitcnt lgkmcnt(1)
	v_mfma_f32_16x16x32_bf16 v[140:143], v[240:243], v[116:119], v[140:143]
	ds_read_b128 v[156:159], v0 offset:15360
	s_waitcnt vmcnt(47)
	ds_write_b128 v185, v[16:19] offset:32768
	s_waitcnt vmcnt(46)
	ds_write_b128 v185, v[20:23] offset:40960
	s_waitcnt vmcnt(45)
	ds_write_b128 v185, v[24:27] offset:49152
	s_waitcnt vmcnt(44)
	ds_write_b128 v185, v[28:31] offset:57344
	global_load_dwordx4 v[16:19], v[188:189], off offset:1664
	global_load_dwordx4 v[20:23], v[190:191], off offset:1664
	global_load_dwordx4 v[24:27], v[192:193], off offset:1664
	global_load_dwordx4 v[28:31], v[194:195], off offset:1664
	s_waitcnt lgkmcnt(5)
	v_mfma_f32_16x16x32_bf16 v[120:123], v[244:247], v[216:219], v[144:147]
	s_waitcnt lgkmcnt(0)
	s_barrier
	v_mfma_f32_16x16x32_bf16 v[144:147], v[156:159], v[116:119], v[120:123]
	ds_read_b128 v[216:219], v208 offset:49152
	ds_read_b128 v[220:223], v0 offset:32768
	ds_read_b128 v[224:227], v0 offset:33792
	ds_read_b128 v[228:231], v0 offset:34816
	ds_read_b128 v[232:235], v0 offset:35840
	ds_read_b128 v[236:239], v0 offset:36864
	ds_read_b128 v[240:243], v0 offset:37888
	ds_read_b128 v[244:247], v0 offset:38912
	ds_read_b128 v[248:251], v0 offset:39936
	v_cvt_pk_bf16_f32 v116, v148, v149
	v_cvt_pk_bf16_f32 v117, v150, v151
	v_cvt_pk_bf16_f32 v118, v112, v113
	s_nop 1
	v_add_co_u32_e32 v120, vcc, s1, v186
	v_cvt_pk_bf16_f32 v119, v114, v115
	s_nop 0
	v_addc_co_u32_e32 v121, vcc, 0, v187, vcc
	global_store_dwordx4 v[120:121], v[116:119], off
	v_pk_mul_f32 v[150:151], v[184:185], v[150:151] op_sel_hi:[0,1]
	v_pk_mul_f32 v[148:149], v[184:185], v[148:149] op_sel_hi:[0,1]
	v_cvt_pk_bf16_f32 v116, v124, v125
	v_cvt_pk_bf16_f32 v117, v126, v127
	v_cvt_pk_bf16_f32 v118, v128, v129
	v_cvt_pk_bf16_f32 v119, v130, v131
	global_store_dwordx4 v[120:121], v[116:119], off offset:1024
	v_pk_mul_f32 v[114:115], v[184:185], v[114:115] op_sel_hi:[0,1]
	v_pk_mul_f32 v[112:113], v[184:185], v[112:113] op_sel_hi:[0,1]
	v_cvt_pk_bf16_f32 v116, v132, v133
	v_cvt_pk_bf16_f32 v117, v134, v135
	v_cvt_pk_bf16_f32 v118, v136, v137
	v_cvt_pk_bf16_f32 v119, v138, v139
	global_store_dwordx4 v[120:121], v[116:119], off offset:2048
	v_pk_mul_f32 v[126:127], v[184:185], v[126:127] op_sel_hi:[0,1]
	v_pk_mul_f32 v[124:125], v[184:185], v[124:125] op_sel_hi:[0,1]
	v_cvt_pk_bf16_f32 v116, v140, v141
	v_cvt_pk_bf16_f32 v117, v142, v143
	v_cvt_pk_bf16_f32 v118, v144, v145
	v_cvt_pk_bf16_f32 v119, v146, v147
	global_store_dwordx4 v[120:121], v[116:119], off offset:3072
	ds_read_b128 v[116:119], v208 offset:50176
	s_waitcnt lgkmcnt(8)
	v_mfma_f32_16x16x32_bf16 v[148:151], v[220:223], v[216:219], v[148:151]
	ds_read_b128 v[220:223], v0 offset:40960
	v_mul_f32_e64 v130, v184, v130
	v_mul_f32_e64 v131, v184, v131
	v_pk_mul_f32 v[128:129], v[184:185], v[128:129] op_sel_hi:[0,1]
	v_pk_mul_f32 v[134:135], v[184:185], v[134:135] op_sel_hi:[0,1]
	s_waitcnt lgkmcnt(1)
	v_mfma_f32_16x16x32_bf16 v[148:151], v[224:227], v[116:119], v[148:151]
	ds_read_b128 v[224:227], v0 offset:41984
	v_pk_mul_f32 v[132:133], v[184:185], v[132:133] op_sel_hi:[0,1]
	v_pk_mul_f32 v[138:139], v[184:185], v[138:139] op_sel_hi:[0,1]
	s_waitcnt lgkmcnt(8)
	v_mfma_f32_16x16x32_bf16 v[112:115], v[228:231], v[216:219], v[112:115]
	ds_read_b128 v[228:231], v0 offset:43008
	v_mul_f32_e64 v136, v184, v136
	v_mul_f32_e64 v137, v184, v137
	v_pk_mul_f32 v[142:143], v[184:185], v[142:143] op_sel_hi:[0,1]
	v_pk_mul_f32 v[140:141], v[184:185], v[140:141] op_sel_hi:[0,1]
	s_waitcnt lgkmcnt(3)
	v_mfma_f32_16x16x32_bf16 v[112:115], v[232:235], v[116:119], v[112:115]
	ds_read_b128 v[232:235], v0 offset:44032
	v_pk_mul_f32 v[146:147], v[184:185], v[146:147] op_sel_hi:[0,1]
	v_pk_mul_f32 v[144:145], v[184:185], v[144:145] op_sel_hi:[0,1]
	s_waitcnt lgkmcnt(8)
	v_mfma_f32_16x16x32_bf16 v[124:127], v[236:239], v[216:219], v[124:127]
	ds_read_b128 v[236:239], v0 offset:45056
	s_mov_b32 s1, 0x40000
	s_waitcnt lgkmcnt(5)
	v_mfma_f32_16x16x32_bf16 v[124:127], v[240:243], v[116:119], v[124:127]
	ds_read_b128 v[240:243], v0 offset:46080
	s_waitcnt lgkmcnt(8)
	v_mfma_f32_16x16x32_bf16 v[128:131], v[244:247], v[216:219], v[128:131]
	ds_read_b128 v[244:247], v0 offset:47104
	s_waitcnt lgkmcnt(7)
	v_mfma_f32_16x16x32_bf16 v[128:131], v[248:251], v[116:119], v[128:131]
	s_waitcnt lgkmcnt(6)
	v_mfma_f32_16x16x32_bf16 v[132:135], v[220:223], v[216:219], v[132:135]
	s_waitcnt lgkmcnt(5)
	v_mfma_f32_16x16x32_bf16 v[132:135], v[224:227], v[116:119], v[132:135]
	s_waitcnt lgkmcnt(4)
	v_mfma_f32_16x16x32_bf16 v[136:139], v[228:231], v[216:219], v[136:139]
	s_waitcnt lgkmcnt(3)
	v_mfma_f32_16x16x32_bf16 v[136:139], v[232:235], v[116:119], v[136:139]
	s_waitcnt lgkmcnt(2)
	v_mfma_f32_16x16x32_bf16 v[140:143], v[236:239], v[216:219], v[140:143]
	s_waitcnt lgkmcnt(1)
	v_mfma_f32_16x16x32_bf16 v[140:143], v[240:243], v[116:119], v[140:143]
	ds_read_b128 v[156:159], v0 offset:48128
	s_waitcnt vmcnt(47)
	ds_write_b128 v185, v[32:35]
	s_waitcnt vmcnt(46)
	ds_write_b128 v185, v[36:39] offset:8192
	s_waitcnt vmcnt(45)
	ds_write_b128 v185, v[40:43] offset:16384
	s_waitcnt vmcnt(44)
	ds_write_b128 v185, v[44:47] offset:24576
	global_load_dwordx4 v[32:35], v[188:189], off offset:1792
	global_load_dwordx4 v[36:39], v[190:191], off offset:1792
	global_load_dwordx4 v[40:43], v[192:193], off offset:1792
	global_load_dwordx4 v[44:47], v[194:195], off offset:1792
	s_waitcnt lgkmcnt(5)
	v_mfma_f32_16x16x32_bf16 v[120:123], v[244:247], v[216:219], v[144:147]
	s_waitcnt lgkmcnt(0)
	s_barrier
	v_mfma_f32_16x16x32_bf16 v[144:147], v[156:159], v[116:119], v[120:123]
	ds_read_b128 v[216:219], v208 offset:16384
	ds_read_b128 v[220:223], v0
	ds_read_b128 v[224:227], v0 offset:1024
	ds_read_b128 v[228:231], v0 offset:2048
	ds_read_b128 v[232:235], v0 offset:3072
	ds_read_b128 v[236:239], v0 offset:4096
	ds_read_b128 v[240:243], v0 offset:5120
	ds_read_b128 v[244:247], v0 offset:6144
	ds_read_b128 v[248:251], v0 offset:7168
	v_cvt_pk_bf16_f32 v116, v148, v149
	v_cvt_pk_bf16_f32 v117, v150, v151
	v_cvt_pk_bf16_f32 v118, v112, v113
	s_nop 1
	v_add_co_u32_e32 v120, vcc, s1, v186
	v_cvt_pk_bf16_f32 v119, v114, v115
	s_nop 0
	v_addc_co_u32_e32 v121, vcc, 0, v187, vcc
	global_store_dwordx4 v[120:121], v[116:119], off
	v_pk_mul_f32 v[150:151], v[184:185], v[150:151] op_sel_hi:[0,1]
	v_pk_mul_f32 v[148:149], v[184:185], v[148:149] op_sel_hi:[0,1]
	v_cvt_pk_bf16_f32 v116, v124, v125
	v_cvt_pk_bf16_f32 v117, v126, v127
	v_cvt_pk_bf16_f32 v118, v128, v129
	v_cvt_pk_bf16_f32 v119, v130, v131
	global_store_dwordx4 v[120:121], v[116:119], off offset:1024
	v_pk_mul_f32 v[114:115], v[184:185], v[114:115] op_sel_hi:[0,1]
	v_pk_mul_f32 v[112:113], v[184:185], v[112:113] op_sel_hi:[0,1]
	v_cvt_pk_bf16_f32 v116, v132, v133
	v_cvt_pk_bf16_f32 v117, v134, v135
	v_cvt_pk_bf16_f32 v118, v136, v137
	v_cvt_pk_bf16_f32 v119, v138, v139
	global_store_dwordx4 v[120:121], v[116:119], off offset:2048
	v_pk_mul_f32 v[126:127], v[184:185], v[126:127] op_sel_hi:[0,1]
	v_pk_mul_f32 v[124:125], v[184:185], v[124:125] op_sel_hi:[0,1]
	v_cvt_pk_bf16_f32 v116, v140, v141
	v_cvt_pk_bf16_f32 v117, v142, v143
	v_cvt_pk_bf16_f32 v118, v144, v145
	v_cvt_pk_bf16_f32 v119, v146, v147
	global_store_dwordx4 v[120:121], v[116:119], off offset:3072
	ds_read_b128 v[116:119], v208 offset:17408
	s_waitcnt lgkmcnt(8)
	v_mfma_f32_16x16x32_bf16 v[148:151], v[220:223], v[216:219], v[148:151]
	ds_read_b128 v[220:223], v0 offset:8192
	v_mul_f32_e64 v130, v184, v130
	v_mul_f32_e64 v131, v184, v131
	v_pk_mul_f32 v[128:129], v[184:185], v[128:129] op_sel_hi:[0,1]
	v_pk_mul_f32 v[134:135], v[184:185], v[134:135] op_sel_hi:[0,1]
	s_waitcnt lgkmcnt(1)
	v_mfma_f32_16x16x32_bf16 v[148:151], v[224:227], v[116:119], v[148:151]
	ds_read_b128 v[224:227], v0 offset:9216
	v_pk_mul_f32 v[132:133], v[184:185], v[132:133] op_sel_hi:[0,1]
	v_pk_mul_f32 v[138:139], v[184:185], v[138:139] op_sel_hi:[0,1]
	s_waitcnt lgkmcnt(8)
	v_mfma_f32_16x16x32_bf16 v[112:115], v[228:231], v[216:219], v[112:115]
	ds_read_b128 v[228:231], v0 offset:10240
	v_mul_f32_e64 v136, v184, v136
	v_mul_f32_e64 v137, v184, v137
	v_pk_mul_f32 v[142:143], v[184:185], v[142:143] op_sel_hi:[0,1]
	v_pk_mul_f32 v[140:141], v[184:185], v[140:141] op_sel_hi:[0,1]
	s_waitcnt lgkmcnt(3)
	v_mfma_f32_16x16x32_bf16 v[112:115], v[232:235], v[116:119], v[112:115]
	ds_read_b128 v[232:235], v0 offset:11264
	v_pk_mul_f32 v[146:147], v[184:185], v[146:147] op_sel_hi:[0,1]
	v_pk_mul_f32 v[144:145], v[184:185], v[144:145] op_sel_hi:[0,1]
	s_waitcnt lgkmcnt(8)
	v_mfma_f32_16x16x32_bf16 v[124:127], v[236:239], v[216:219], v[124:127]
	ds_read_b128 v[236:239], v0 offset:12288
	s_mov_b32 s1, 0x48000
	s_waitcnt lgkmcnt(5)
	v_mfma_f32_16x16x32_bf16 v[124:127], v[240:243], v[116:119], v[124:127]
	ds_read_b128 v[240:243], v0 offset:13312
	s_waitcnt lgkmcnt(8)
	v_mfma_f32_16x16x32_bf16 v[128:131], v[244:247], v[216:219], v[128:131]
	ds_read_b128 v[244:247], v0 offset:14336
	s_waitcnt lgkmcnt(7)
	v_mfma_f32_16x16x32_bf16 v[128:131], v[248:251], v[116:119], v[128:131]
	s_waitcnt lgkmcnt(6)
	v_mfma_f32_16x16x32_bf16 v[132:135], v[220:223], v[216:219], v[132:135]
	s_waitcnt lgkmcnt(5)
	v_mfma_f32_16x16x32_bf16 v[132:135], v[224:227], v[116:119], v[132:135]
	s_waitcnt lgkmcnt(4)
	v_mfma_f32_16x16x32_bf16 v[136:139], v[228:231], v[216:219], v[136:139]
	s_waitcnt lgkmcnt(3)
	v_mfma_f32_16x16x32_bf16 v[136:139], v[232:235], v[116:119], v[136:139]
	s_waitcnt lgkmcnt(2)
	v_mfma_f32_16x16x32_bf16 v[140:143], v[236:239], v[216:219], v[140:143]
	s_waitcnt lgkmcnt(1)
	v_mfma_f32_16x16x32_bf16 v[140:143], v[240:243], v[116:119], v[140:143]
	ds_read_b128 v[156:159], v0 offset:15360
	s_waitcnt vmcnt(47)
	ds_write_b128 v185, v[48:51] offset:32768
	s_waitcnt vmcnt(46)
	ds_write_b128 v185, v[52:55] offset:40960
	s_waitcnt vmcnt(45)
	ds_write_b128 v185, v[56:59] offset:49152
	s_waitcnt vmcnt(44)
	ds_write_b128 v185, v[60:63] offset:57344
	global_load_dwordx4 v[48:51], v[188:189], off offset:1920
	global_load_dwordx4 v[52:55], v[190:191], off offset:1920
	global_load_dwordx4 v[56:59], v[192:193], off offset:1920
	global_load_dwordx4 v[60:63], v[194:195], off offset:1920
	s_waitcnt lgkmcnt(5)
	v_mfma_f32_16x16x32_bf16 v[120:123], v[244:247], v[216:219], v[144:147]
	s_waitcnt lgkmcnt(0)
	s_barrier
	v_mfma_f32_16x16x32_bf16 v[144:147], v[156:159], v[116:119], v[120:123]
	ds_read_b128 v[216:219], v208 offset:49152
	ds_read_b128 v[220:223], v0 offset:32768
	ds_read_b128 v[224:227], v0 offset:33792
	ds_read_b128 v[228:231], v0 offset:34816
	ds_read_b128 v[232:235], v0 offset:35840
	ds_read_b128 v[236:239], v0 offset:36864
	ds_read_b128 v[240:243], v0 offset:37888
	ds_read_b128 v[244:247], v0 offset:38912
	ds_read_b128 v[248:251], v0 offset:39936
	v_cvt_pk_bf16_f32 v116, v148, v149
	v_cvt_pk_bf16_f32 v117, v150, v151
	v_cvt_pk_bf16_f32 v118, v112, v113
	s_nop 1
	v_add_co_u32_e32 v120, vcc, s1, v186
	v_cvt_pk_bf16_f32 v119, v114, v115
	s_nop 0
	v_addc_co_u32_e32 v121, vcc, 0, v187, vcc
	global_store_dwordx4 v[120:121], v[116:119], off
	v_pk_mul_f32 v[150:151], v[184:185], v[150:151] op_sel_hi:[0,1]
	v_pk_mul_f32 v[148:149], v[184:185], v[148:149] op_sel_hi:[0,1]
	v_cvt_pk_bf16_f32 v116, v124, v125
	v_cvt_pk_bf16_f32 v117, v126, v127
	v_cvt_pk_bf16_f32 v118, v128, v129
	v_cvt_pk_bf16_f32 v119, v130, v131
	global_store_dwordx4 v[120:121], v[116:119], off offset:1024
	v_pk_mul_f32 v[114:115], v[184:185], v[114:115] op_sel_hi:[0,1]
	v_pk_mul_f32 v[112:113], v[184:185], v[112:113] op_sel_hi:[0,1]
	v_cvt_pk_bf16_f32 v116, v132, v133
	v_cvt_pk_bf16_f32 v117, v134, v135
	v_cvt_pk_bf16_f32 v118, v136, v137
	v_cvt_pk_bf16_f32 v119, v138, v139
	global_store_dwordx4 v[120:121], v[116:119], off offset:2048
	v_pk_mul_f32 v[126:127], v[184:185], v[126:127] op_sel_hi:[0,1]
	v_pk_mul_f32 v[124:125], v[184:185], v[124:125] op_sel_hi:[0,1]
	v_cvt_pk_bf16_f32 v116, v140, v141
	v_cvt_pk_bf16_f32 v117, v142, v143
	v_cvt_pk_bf16_f32 v118, v144, v145
	v_cvt_pk_bf16_f32 v119, v146, v147
	global_store_dwordx4 v[120:121], v[116:119], off offset:3072
	ds_read_b128 v[116:119], v208 offset:50176
	s_waitcnt lgkmcnt(8)
	v_mfma_f32_16x16x32_bf16 v[148:151], v[220:223], v[216:219], v[148:151]
	ds_read_b128 v[220:223], v0 offset:40960
	v_mul_f32_e64 v130, v184, v130
	v_mul_f32_e64 v131, v184, v131
	v_pk_mul_f32 v[128:129], v[184:185], v[128:129] op_sel_hi:[0,1]
	v_pk_mul_f32 v[134:135], v[184:185], v[134:135] op_sel_hi:[0,1]
	s_waitcnt lgkmcnt(1)
	v_mfma_f32_16x16x32_bf16 v[148:151], v[224:227], v[116:119], v[148:151]
	ds_read_b128 v[224:227], v0 offset:41984
	v_pk_mul_f32 v[132:133], v[184:185], v[132:133] op_sel_hi:[0,1]
	v_pk_mul_f32 v[138:139], v[184:185], v[138:139] op_sel_hi:[0,1]
	s_waitcnt lgkmcnt(8)
	v_mfma_f32_16x16x32_bf16 v[112:115], v[228:231], v[216:219], v[112:115]
	ds_read_b128 v[228:231], v0 offset:43008
	v_mul_f32_e64 v136, v184, v136
	v_mul_f32_e64 v137, v184, v137
	v_pk_mul_f32 v[142:143], v[184:185], v[142:143] op_sel_hi:[0,1]
	v_pk_mul_f32 v[140:141], v[184:185], v[140:141] op_sel_hi:[0,1]
	s_waitcnt lgkmcnt(3)
	v_mfma_f32_16x16x32_bf16 v[112:115], v[232:235], v[116:119], v[112:115]
	ds_read_b128 v[232:235], v0 offset:44032
	v_pk_mul_f32 v[146:147], v[184:185], v[146:147] op_sel_hi:[0,1]
	v_pk_mul_f32 v[144:145], v[184:185], v[144:145] op_sel_hi:[0,1]
	s_waitcnt lgkmcnt(8)
	v_mfma_f32_16x16x32_bf16 v[124:127], v[236:239], v[216:219], v[124:127]
	ds_read_b128 v[236:239], v0 offset:45056
	s_mov_b32 s1, 0x50000
	s_waitcnt lgkmcnt(5)
	v_mfma_f32_16x16x32_bf16 v[124:127], v[240:243], v[116:119], v[124:127]
	ds_read_b128 v[240:243], v0 offset:46080
	s_waitcnt lgkmcnt(8)
	v_mfma_f32_16x16x32_bf16 v[128:131], v[244:247], v[216:219], v[128:131]
	ds_read_b128 v[244:247], v0 offset:47104
	s_waitcnt lgkmcnt(7)
	v_mfma_f32_16x16x32_bf16 v[128:131], v[248:251], v[116:119], v[128:131]
	s_waitcnt lgkmcnt(6)
	v_mfma_f32_16x16x32_bf16 v[132:135], v[220:223], v[216:219], v[132:135]
	s_waitcnt lgkmcnt(5)
	v_mfma_f32_16x16x32_bf16 v[132:135], v[224:227], v[116:119], v[132:135]
	s_waitcnt lgkmcnt(4)
	v_mfma_f32_16x16x32_bf16 v[136:139], v[228:231], v[216:219], v[136:139]
	s_waitcnt lgkmcnt(3)
	v_mfma_f32_16x16x32_bf16 v[136:139], v[232:235], v[116:119], v[136:139]
	s_waitcnt lgkmcnt(2)
	v_mfma_f32_16x16x32_bf16 v[140:143], v[236:239], v[216:219], v[140:143]
	s_waitcnt lgkmcnt(1)
	v_mfma_f32_16x16x32_bf16 v[140:143], v[240:243], v[116:119], v[140:143]
	ds_read_b128 v[156:159], v0 offset:48128
	s_waitcnt vmcnt(47)
	ds_write_b128 v185, v[64:67]
	s_waitcnt vmcnt(46)
	ds_write_b128 v185, v[68:71] offset:8192
	s_waitcnt vmcnt(45)
	ds_write_b128 v185, v[72:75] offset:16384
	s_waitcnt vmcnt(44)
	ds_write_b128 v185, v[76:79] offset:24576
	global_load_dwordx4 v[64:67], v[188:189], off offset:2048
	global_load_dwordx4 v[68:71], v[190:191], off offset:2048
	global_load_dwordx4 v[72:75], v[192:193], off offset:2048
	global_load_dwordx4 v[76:79], v[194:195], off offset:2048
	s_waitcnt lgkmcnt(5)
	v_mfma_f32_16x16x32_bf16 v[120:123], v[244:247], v[216:219], v[144:147]
	s_waitcnt lgkmcnt(0)
	s_barrier
	v_mfma_f32_16x16x32_bf16 v[144:147], v[156:159], v[116:119], v[120:123]
	ds_read_b128 v[216:219], v208 offset:16384
	ds_read_b128 v[220:223], v0
	ds_read_b128 v[224:227], v0 offset:1024
	ds_read_b128 v[228:231], v0 offset:2048
	ds_read_b128 v[232:235], v0 offset:3072
	ds_read_b128 v[236:239], v0 offset:4096
	ds_read_b128 v[240:243], v0 offset:5120
	ds_read_b128 v[244:247], v0 offset:6144
	ds_read_b128 v[248:251], v0 offset:7168
	v_cvt_pk_bf16_f32 v116, v148, v149
	v_cvt_pk_bf16_f32 v117, v150, v151
	v_cvt_pk_bf16_f32 v118, v112, v113
	s_nop 1
	v_add_co_u32_e32 v120, vcc, s1, v186
	v_cvt_pk_bf16_f32 v119, v114, v115
	s_nop 0
	v_addc_co_u32_e32 v121, vcc, 0, v187, vcc
	global_store_dwordx4 v[120:121], v[116:119], off
	v_pk_mul_f32 v[150:151], v[184:185], v[150:151] op_sel_hi:[0,1]
	v_pk_mul_f32 v[148:149], v[184:185], v[148:149] op_sel_hi:[0,1]
	v_cvt_pk_bf16_f32 v116, v124, v125
	v_cvt_pk_bf16_f32 v117, v126, v127
	v_cvt_pk_bf16_f32 v118, v128, v129
	v_cvt_pk_bf16_f32 v119, v130, v131
	global_store_dwordx4 v[120:121], v[116:119], off offset:1024
	v_pk_mul_f32 v[114:115], v[184:185], v[114:115] op_sel_hi:[0,1]
	v_pk_mul_f32 v[112:113], v[184:185], v[112:113] op_sel_hi:[0,1]
	v_cvt_pk_bf16_f32 v116, v132, v133
	v_cvt_pk_bf16_f32 v117, v134, v135
	v_cvt_pk_bf16_f32 v118, v136, v137
	v_cvt_pk_bf16_f32 v119, v138, v139
	global_store_dwordx4 v[120:121], v[116:119], off offset:2048
	v_pk_mul_f32 v[126:127], v[184:185], v[126:127] op_sel_hi:[0,1]
	v_pk_mul_f32 v[124:125], v[184:185], v[124:125] op_sel_hi:[0,1]
	v_cvt_pk_bf16_f32 v116, v140, v141
	v_cvt_pk_bf16_f32 v117, v142, v143
	v_cvt_pk_bf16_f32 v118, v144, v145
	v_cvt_pk_bf16_f32 v119, v146, v147
	global_store_dwordx4 v[120:121], v[116:119], off offset:3072
	ds_read_b128 v[116:119], v208 offset:17408
	s_waitcnt lgkmcnt(8)
	v_mfma_f32_16x16x32_bf16 v[148:151], v[220:223], v[216:219], v[148:151]
	ds_read_b128 v[220:223], v0 offset:8192
	v_mul_f32_e64 v130, v184, v130
	v_mul_f32_e64 v131, v184, v131
	v_pk_mul_f32 v[128:129], v[184:185], v[128:129] op_sel_hi:[0,1]
	v_pk_mul_f32 v[134:135], v[184:185], v[134:135] op_sel_hi:[0,1]
	s_waitcnt lgkmcnt(1)
	v_mfma_f32_16x16x32_bf16 v[152:155], v[224:227], v[116:119], v[148:151]
	ds_read_b128 v[224:227], v0 offset:9216
	v_pk_mul_f32 v[132:133], v[184:185], v[132:133] op_sel_hi:[0,1]
	v_pk_mul_f32 v[138:139], v[184:185], v[138:139] op_sel_hi:[0,1]
	s_waitcnt lgkmcnt(8)
	v_mfma_f32_16x16x32_bf16 v[112:115], v[228:231], v[216:219], v[112:115]
	ds_read_b128 v[228:231], v0 offset:10240
	v_mul_f32_e64 v136, v184, v136
	v_mul_f32_e64 v137, v184, v137
	v_pk_mul_f32 v[142:143], v[184:185], v[142:143] op_sel_hi:[0,1]
	v_pk_mul_f32 v[140:141], v[184:185], v[140:141] op_sel_hi:[0,1]
	s_waitcnt lgkmcnt(3)
	v_mfma_f32_16x16x32_bf16 v[112:115], v[232:235], v[116:119], v[112:115]
	ds_read_b128 v[232:235], v0 offset:11264
	v_pk_mul_f32 v[146:147], v[184:185], v[146:147] op_sel_hi:[0,1]
	v_pk_mul_f32 v[144:145], v[184:185], v[144:145] op_sel_hi:[0,1]
	s_waitcnt lgkmcnt(8)
	v_mfma_f32_16x16x32_bf16 v[124:127], v[236:239], v[216:219], v[124:127]
	ds_read_b128 v[236:239], v0 offset:12288
	s_mov_b32 s1, 0x58000
	s_waitcnt lgkmcnt(5)
	v_mfma_f32_16x16x32_bf16 v[124:127], v[240:243], v[116:119], v[124:127]
	ds_read_b128 v[240:243], v0 offset:13312
	s_waitcnt lgkmcnt(8)
	v_mfma_f32_16x16x32_bf16 v[128:131], v[244:247], v[216:219], v[128:131]
	ds_read_b128 v[244:247], v0 offset:14336
	s_waitcnt lgkmcnt(7)
	v_mfma_f32_16x16x32_bf16 v[128:131], v[248:251], v[116:119], v[128:131]
	s_waitcnt lgkmcnt(6)
	v_mfma_f32_16x16x32_bf16 v[132:135], v[220:223], v[216:219], v[132:135]
	s_waitcnt lgkmcnt(5)
	v_mfma_f32_16x16x32_bf16 v[132:135], v[224:227], v[116:119], v[132:135]
	s_waitcnt lgkmcnt(4)
	v_mfma_f32_16x16x32_bf16 v[136:139], v[228:231], v[216:219], v[136:139]
	s_waitcnt lgkmcnt(3)
	v_mfma_f32_16x16x32_bf16 v[136:139], v[232:235], v[116:119], v[136:139]
	s_waitcnt lgkmcnt(2)
	v_mfma_f32_16x16x32_bf16 v[140:143], v[236:239], v[216:219], v[140:143]
	s_waitcnt lgkmcnt(1)
	v_mfma_f32_16x16x32_bf16 v[140:143], v[240:243], v[116:119], v[140:143]
	ds_read_b128 v[156:159], v0 offset:15360
	s_waitcnt vmcnt(47)
	ds_write_b128 v185, v[80:83] offset:32768
	s_waitcnt vmcnt(46)
	ds_write_b128 v185, v[84:87] offset:40960
	s_waitcnt vmcnt(45)
	ds_write_b128 v185, v[88:91] offset:49152
	s_waitcnt vmcnt(44)
	ds_write_b128 v185, v[92:95] offset:57344
	global_load_dwordx4 v[80:83], v[188:189], off offset:2176
	global_load_dwordx4 v[84:87], v[190:191], off offset:2176
	global_load_dwordx4 v[88:91], v[192:193], off offset:2176
	global_load_dwordx4 v[92:95], v[194:195], off offset:2176
	s_waitcnt lgkmcnt(5)
	v_mfma_f32_16x16x32_bf16 v[120:123], v[244:247], v[216:219], v[144:147]
	s_waitcnt lgkmcnt(0)
	s_barrier
	v_mfma_f32_16x16x32_bf16 v[148:151], v[156:159], v[116:119], v[120:123]
	v_cvt_pk_bf16_f32 v116, v152, v153
	v_cvt_pk_bf16_f32 v117, v154, v155
	v_cvt_pk_bf16_f32 v118, v112, v113
	s_nop 1
	v_add_co_u32_e32 v120, vcc, s1, v186
	v_cvt_pk_bf16_f32 v119, v114, v115
	s_nop 0
	v_addc_co_u32_e32 v121, vcc, 0, v187, vcc
	global_store_dwordx4 v[120:121], v[116:119], off
	v_pk_mul_f32 v[146:147], v[184:185], v[154:155] op_sel_hi:[0,1]
	v_pk_mul_f32 v[144:145], v[184:185], v[152:153] op_sel_hi:[0,1]
	v_cvt_pk_bf16_f32 v116, v124, v125
	v_cvt_pk_bf16_f32 v117, v126, v127
	v_cvt_pk_bf16_f32 v118, v128, v129
	v_cvt_pk_bf16_f32 v119, v130, v131
	global_store_dwordx4 v[120:121], v[116:119], off offset:1024
	v_pk_mul_f32 v[114:115], v[184:185], v[114:115] op_sel_hi:[0,1]
	v_pk_mul_f32 v[112:113], v[184:185], v[112:113] op_sel_hi:[0,1]
	v_cvt_pk_bf16_f32 v116, v132, v133
	v_cvt_pk_bf16_f32 v117, v134, v135
	v_cvt_pk_bf16_f32 v118, v136, v137
	v_cvt_pk_bf16_f32 v119, v138, v139
	global_store_dwordx4 v[120:121], v[116:119], off offset:2048
	v_pk_mul_f32 v[126:127], v[184:185], v[126:127] op_sel_hi:[0,1]
	v_pk_mul_f32 v[124:125], v[184:185], v[124:125] op_sel_hi:[0,1]
	v_cvt_pk_bf16_f32 v116, v140, v141
	v_cvt_pk_bf16_f32 v117, v142, v143
	v_cvt_pk_bf16_f32 v118, v148, v149
	v_cvt_pk_bf16_f32 v119, v150, v151
	global_store_dwordx4 v[120:121], v[116:119], off offset:3072
	ds_read_b128 v[120:123], v208 offset:49152
	ds_read_b128 v[116:119], v208 offset:50176
	ds_read_b128 v[152:155], v0 offset:32768
	ds_read_b128 v[156:159], v0 offset:33792
	s_waitcnt lgkmcnt(1)
	v_mfma_f32_16x16x32_bf16 v[144:147], v[152:155], v[120:123], v[144:147]
	v_mul_f32_e64 v130, v184, v130
	v_mul_f32_e64 v131, v184, v131
	v_pk_mul_f32 v[128:129], v[184:185], v[128:129] op_sel_hi:[0,1]
	s_mov_b32 s1, 0x60000
	s_waitcnt lgkmcnt(0)
	v_mfma_f32_16x16x32_bf16 v[156:159], v[156:159], v[116:119], v[144:147]
	s_nop 2
	ds_read_b128 v[144:147], v0 offset:34816
	ds_read_b128 v[152:155], v0 offset:35840
	s_waitcnt lgkmcnt(1)
	v_mfma_f32_16x16x32_bf16 v[112:115], v[144:147], v[120:123], v[112:115]
	s_waitcnt lgkmcnt(0)
	v_mfma_f32_16x16x32_bf16 v[112:115], v[152:155], v[116:119], v[112:115]
	ds_read_b128 v[144:147], v0 offset:36864
	ds_read_b128 v[152:155], v0 offset:37888
	s_waitcnt lgkmcnt(1)
	v_mfma_f32_16x16x32_bf16 v[124:127], v[144:147], v[120:123], v[124:127]
	s_waitcnt lgkmcnt(0)
	v_mfma_f32_16x16x32_bf16 v[124:127], v[152:155], v[116:119], v[124:127]
	ds_read_b128 v[144:147], v0 offset:38912
	ds_read_b128 v[152:155], v0 offset:39936
	s_waitcnt lgkmcnt(1)
	v_mfma_f32_16x16x32_bf16 v[128:131], v[144:147], v[120:123], v[128:131]
	s_waitcnt lgkmcnt(0)
	v_mfma_f32_16x16x32_bf16 v[144:147], v[152:155], v[116:119], v[128:131]
	s_nop 5
	v_mul_f32_e64 v130, v184, v134
	v_mul_f32_e64 v131, v184, v135
	v_pk_mul_f32 v[128:129], v[184:185], v[132:133] op_sel_hi:[0,1]
	ds_read_b128 v[132:135], v0 offset:40960
	ds_read_b128 v[152:155], v0 offset:41984
	s_waitcnt lgkmcnt(1)
	v_mfma_f32_16x16x32_bf16 v[128:131], v[132:135], v[120:123], v[128:131]
	s_waitcnt lgkmcnt(0)
	v_mfma_f32_16x16x32_bf16 v[132:135], v[152:155], v[116:119], v[128:131]
	s_nop 5
	v_mul_f32_e64 v130, v184, v138
	v_mul_f32_e64 v131, v184, v139
	v_pk_mul_f32 v[128:129], v[184:185], v[136:137] op_sel_hi:[0,1]
	ds_read_b128 v[136:139], v0 offset:43008
	ds_read_b128 v[152:155], v0 offset:44032
	s_waitcnt lgkmcnt(1)
	v_mfma_f32_16x16x32_bf16 v[128:131], v[136:139], v[120:123], v[128:131]
	s_waitcnt lgkmcnt(0)
	v_mfma_f32_16x16x32_bf16 v[136:139], v[152:155], v[116:119], v[128:131]
	s_nop 5
	v_mul_f32_e64 v130, v184, v142
	v_mul_f32_e64 v131, v184, v143
	v_pk_mul_f32 v[128:129], v[184:185], v[140:141] op_sel_hi:[0,1]
	ds_read_b128 v[140:143], v0 offset:45056
	ds_read_b128 v[152:155], v0 offset:46080
	s_waitcnt lgkmcnt(1)
	v_mfma_f32_16x16x32_bf16 v[128:131], v[140:143], v[120:123], v[128:131]
	s_waitcnt lgkmcnt(0)
	v_mfma_f32_16x16x32_bf16 v[140:143], v[152:155], v[116:119], v[128:131]
	s_nop 5
	v_mul_f32_e64 v130, v184, v150
	v_mul_f32_e64 v131, v184, v151
	v_pk_mul_f32 v[128:129], v[184:185], v[148:149] op_sel_hi:[0,1]
	ds_read_b128 v[148:151], v0 offset:47104
	ds_read_b128 v[152:155], v0 offset:48128
	s_waitcnt lgkmcnt(1)
	v_mfma_f32_16x16x32_bf16 v[120:123], v[148:151], v[120:123], v[128:131]
	s_waitcnt vmcnt(47)
	ds_write_b128 v185, v[96:99]
	s_waitcnt vmcnt(46)
	ds_write_b128 v185, v[100:103] offset:8192
	s_waitcnt vmcnt(45)
	ds_write_b128 v185, v[104:107] offset:16384
	s_waitcnt vmcnt(44)
	ds_write_b128 v185, v[108:111] offset:24576
	global_load_dwordx4 v[96:99], v[188:189], off offset:2304
	global_load_dwordx4 v[100:103], v[190:191], off offset:2304
	global_load_dwordx4 v[104:107], v[192:193], off offset:2304
	global_load_dwordx4 v[108:111], v[194:195], off offset:2304
	s_waitcnt lgkmcnt(0)
	v_mfma_f32_16x16x32_bf16 v[152:155], v[152:155], v[116:119], v[120:123]
	v_cvt_pk_bf16_f32 v116, v156, v157
	v_cvt_pk_bf16_f32 v117, v158, v159
	v_cvt_pk_bf16_f32 v118, v112, v113
	v_add_co_u32_e32 v120, vcc, s1, v186
	v_cvt_pk_bf16_f32 v119, v114, v115
	s_nop 0
	v_addc_co_u32_e32 v121, vcc, 0, v187, vcc
	s_barrier
	global_store_dwordx4 v[120:121], v[116:119], off
	v_pk_mul_f32 v[130:131], v[184:185], v[158:159] op_sel_hi:[0,1]
	v_pk_mul_f32 v[128:129], v[184:185], v[156:157] op_sel_hi:[0,1]
	v_cvt_pk_bf16_f32 v116, v124, v125
	v_cvt_pk_bf16_f32 v117, v126, v127
	v_cvt_pk_bf16_f32 v118, v144, v145
	v_cvt_pk_bf16_f32 v119, v146, v147
	global_store_dwordx4 v[120:121], v[116:119], off offset:1024
	v_pk_mul_f32 v[114:115], v[184:185], v[114:115] op_sel_hi:[0,1]
	v_pk_mul_f32 v[112:113], v[184:185], v[112:113] op_sel_hi:[0,1]
	v_cvt_pk_bf16_f32 v116, v132, v133
	v_cvt_pk_bf16_f32 v117, v134, v135
	v_cvt_pk_bf16_f32 v118, v136, v137
	v_cvt_pk_bf16_f32 v119, v138, v139
	global_store_dwordx4 v[120:121], v[116:119], off offset:2048
	s_mov_b32 s1, 0x68000
	s_nop 0
	v_cvt_pk_bf16_f32 v116, v140, v141
	v_cvt_pk_bf16_f32 v117, v142, v143
	v_cvt_pk_bf16_f32 v118, v152, v153
	v_cvt_pk_bf16_f32 v119, v154, v155
	global_store_dwordx4 v[120:121], v[116:119], off offset:3072
	ds_read_b128 v[216:219], v208 offset:16384
	ds_read_b128 v[220:223], v0
	ds_read_b128 v[224:227], v208 offset:17408
	ds_read_b128 v[228:231], v0 offset:1024
	ds_read_b128 v[232:235], v0 offset:2048
	ds_read_b128 v[236:239], v0 offset:3072
	ds_read_b128 v[240:243], v0 offset:4096
	ds_read_b128 v[244:247], v0 offset:5120
	ds_read_b128 v[248:251], v0 offset:6144
	s_waitcnt lgkmcnt(7)
	v_mfma_f32_16x16x32_bf16 v[128:131], v[220:223], v[216:219], v[128:131]
	ds_read_b128 v[220:223], v0 offset:7168
	s_waitcnt lgkmcnt(6)
	v_mfma_f32_16x16x32_bf16 v[156:159], v[228:231], v[224:227], v[128:131]
	ds_read_b128 v[228:231], v0 offset:8192
	s_waitcnt lgkmcnt(6)
	v_mfma_f32_16x16x32_bf16 v[112:115], v[232:235], v[216:219], v[112:115]
	ds_read_b128 v[232:235], v0 offset:9216
	s_waitcnt lgkmcnt(6)
	v_mfma_f32_16x16x32_bf16 v[128:131], v[236:239], v[224:227], v[112:115]
	ds_read_b128 v[236:239], v0 offset:10240
	s_nop 5
	v_mul_f32_e64 v114, v184, v126
	v_mul_f32_e64 v115, v184, v127
	v_pk_mul_f32 v[112:113], v[184:185], v[124:125] op_sel_hi:[0,1]
	s_waitcnt lgkmcnt(6)
	v_mfma_f32_16x16x32_bf16 v[112:115], v[240:243], v[216:219], v[112:115]
	ds_read_b128 v[240:243], v0 offset:11264
	s_waitcnt lgkmcnt(6)
	v_mfma_f32_16x16x32_bf16 v[148:151], v[244:247], v[224:227], v[112:115]
	ds_read_b128 v[244:247], v0 offset:12288
	s_nop 5
	v_mul_f32_e64 v114, v184, v146
	v_mul_f32_e64 v115, v184, v147
	v_pk_mul_f32 v[112:113], v[184:185], v[144:145] op_sel_hi:[0,1]
	s_waitcnt lgkmcnt(6)
	v_mfma_f32_16x16x32_bf16 v[112:115], v[248:251], v[216:219], v[112:115]
	ds_read_b128 v[248:251], v0 offset:13312
	s_waitcnt lgkmcnt(6)
	v_mfma_f32_16x16x32_bf16 v[144:147], v[220:223], v[224:227], v[112:115]
	ds_read_b128 v[220:223], v0 offset:14336
	s_nop 5
	v_mul_f32_e64 v114, v184, v134
	v_mul_f32_e64 v115, v184, v135
	v_pk_mul_f32 v[112:113], v[184:185], v[132:133] op_sel_hi:[0,1]
	s_waitcnt lgkmcnt(6)
	v_mfma_f32_16x16x32_bf16 v[112:115], v[228:231], v[216:219], v[112:115]
	ds_read_b128 v[228:231], v0 offset:15360
	s_waitcnt lgkmcnt(6)
	v_mfma_f32_16x16x32_bf16 v[132:135], v[232:235], v[224:227], v[112:115]
	s_nop 5
	v_mul_f32_e64 v114, v184, v138
	v_mul_f32_e64 v115, v184, v139
	v_pk_mul_f32 v[112:113], v[184:185], v[136:137] op_sel_hi:[0,1]
	s_waitcnt lgkmcnt(5)
	v_mfma_f32_16x16x32_bf16 v[112:115], v[236:239], v[216:219], v[112:115]
	s_waitcnt lgkmcnt(4)
	v_mfma_f32_16x16x32_bf16 v[136:139], v[240:243], v[224:227], v[112:115]
	s_nop 5
	v_mul_f32_e64 v114, v184, v142
	v_mul_f32_e64 v115, v184, v143
	v_pk_mul_f32 v[112:113], v[184:185], v[140:141] op_sel_hi:[0,1]
	s_waitcnt lgkmcnt(3)
	v_mfma_f32_16x16x32_bf16 v[112:115], v[244:247], v[216:219], v[112:115]
	s_waitcnt lgkmcnt(2)
	v_mfma_f32_16x16x32_bf16 v[140:143], v[248:251], v[224:227], v[112:115]
	s_nop 5
	v_mul_f32_e64 v114, v184, v154
	v_mul_f32_e64 v115, v184, v155
	v_pk_mul_f32 v[112:113], v[184:185], v[152:153] op_sel_hi:[0,1]
	s_waitcnt lgkmcnt(1)
	v_mfma_f32_16x16x32_bf16 v[112:115], v[220:223], v[216:219], v[112:115]
	s_waitcnt vmcnt(47)
	ds_write_b128 v185, v[16:19] offset:32768
	s_waitcnt vmcnt(46)
	ds_write_b128 v185, v[20:23] offset:40960
	s_waitcnt vmcnt(45)
	ds_write_b128 v185, v[24:27] offset:49152
	s_waitcnt vmcnt(44)
	ds_write_b128 v185, v[28:31] offset:57344
	v_add_co_u32_e32 v20, vcc, s1, v186
	s_waitcnt lgkmcnt(4)
	v_mfma_f32_16x16x32_bf16 v[160:163], v[228:231], v[224:227], v[112:115]
	v_cvt_pk_bf16_f32 v16, v156, v157
	v_cvt_pk_bf16_f32 v17, v158, v159
	v_cvt_pk_bf16_f32 v18, v128, v129
	v_cvt_pk_bf16_f32 v19, v130, v131
	v_addc_co_u32_e32 v21, vcc, 0, v187, vcc
	global_load_dwordx4 v[112:115], v[188:189], off offset:2432
	global_load_dwordx4 v[116:119], v[190:191], off offset:2432
	global_load_dwordx4 v[120:123], v[192:193], off offset:2432
	global_load_dwordx4 v[124:127], v[194:195], off offset:2432
	s_waitcnt lgkmcnt(0)
	s_barrier
	global_store_dwordx4 v[20:21], v[16:19], off
	s_mov_b32 s1, 0x70000
	s_nop 0
	v_cvt_pk_bf16_f32 v16, v148, v149
	v_cvt_pk_bf16_f32 v17, v150, v151
	v_cvt_pk_bf16_f32 v18, v144, v145
	v_cvt_pk_bf16_f32 v19, v146, v147
	global_store_dwordx4 v[20:21], v[16:19], off offset:1024
	s_nop 1
	v_cvt_pk_bf16_f32 v16, v132, v133
	v_cvt_pk_bf16_f32 v17, v134, v135
	v_cvt_pk_bf16_f32 v18, v136, v137
	v_cvt_pk_bf16_f32 v19, v138, v139
	global_store_dwordx4 v[20:21], v[16:19], off offset:2048
	s_nop 1
	v_cvt_pk_bf16_f32 v16, v140, v141
	v_cvt_pk_bf16_f32 v17, v142, v143
	v_cvt_pk_bf16_f32 v18, v160, v161
	v_cvt_pk_bf16_f32 v19, v162, v163
	global_store_dwordx4 v[20:21], v[16:19], off offset:3072
	ds_read_b128 v[216:219], v208 offset:49152
	ds_read_b128 v[220:223], v0 offset:32768
	ds_read_b128 v[224:227], v208 offset:50176
	ds_read_b128 v[228:231], v0 offset:33792
	ds_read_b128 v[232:235], v0 offset:34816
	ds_read_b128 v[236:239], v0 offset:35840
	ds_read_b128 v[240:243], v0 offset:36864
	ds_read_b128 v[244:247], v0 offset:37888
	ds_read_b128 v[248:251], v0 offset:38912
	v_pk_mul_f32 v[18:19], v[184:185], v[158:159] op_sel_hi:[0,1]
	v_pk_mul_f32 v[16:17], v[184:185], v[156:157] op_sel_hi:[0,1]
	s_nop 0
	s_waitcnt lgkmcnt(7)
	v_mfma_f32_16x16x32_bf16 v[16:19], v[220:223], v[216:219], v[16:19]
	ds_read_b128 v[220:223], v0 offset:39936
	s_waitcnt lgkmcnt(6)
	v_mfma_f32_16x16x32_bf16 v[164:167], v[228:231], v[224:227], v[16:19]
	ds_read_b128 v[228:231], v0 offset:40960
	s_nop 5
	v_mul_f32_e64 v18, v184, v130
	v_mul_f32_e64 v19, v184, v131
	v_pk_mul_f32 v[16:17], v[184:185], v[128:129] op_sel_hi:[0,1]
	s_waitcnt lgkmcnt(6)
	v_mfma_f32_16x16x32_bf16 v[16:19], v[232:235], v[216:219], v[16:19]
	ds_read_b128 v[232:235], v0 offset:41984
	v_mul_f32_e64 v30, v184, v150
	v_mul_f32_e64 v31, v184, v151
	v_pk_mul_f32 v[28:29], v[184:185], v[148:149] op_sel_hi:[0,1]
	s_waitcnt lgkmcnt(6)
	v_mfma_f32_16x16x32_bf16 v[16:19], v[236:239], v[224:227], v[16:19]
	ds_read_b128 v[236:239], v0 offset:43008
	s_waitcnt lgkmcnt(6)
	v_mfma_f32_16x16x32_bf16 v[28:31], v[240:243], v[216:219], v[28:31]
	ds_read_b128 v[240:243], v0 offset:44032
	v_mul_f32_e64 v130, v184, v146
	v_mul_f32_e64 v131, v184, v147
	v_pk_mul_f32 v[128:129], v[184:185], v[144:145] op_sel_hi:[0,1]
	s_waitcnt lgkmcnt(6)
	v_mfma_f32_16x16x32_bf16 v[28:31], v[244:247], v[224:227], v[28:31]
	ds_read_b128 v[244:247], v0 offset:45056
	s_waitcnt lgkmcnt(6)
	v_mfma_f32_16x16x32_bf16 v[128:131], v[248:251], v[216:219], v[128:131]
	ds_read_b128 v[248:251], v0 offset:46080
	s_waitcnt lgkmcnt(6)
	v_mfma_f32_16x16x32_bf16 v[144:147], v[220:223], v[224:227], v[128:131]
	ds_read_b128 v[220:223], v0 offset:47104
	s_nop 5
	v_mul_f32_e64 v130, v184, v134
	v_mul_f32_e64 v131, v184, v135
	v_pk_mul_f32 v[128:129], v[184:185], v[132:133] op_sel_hi:[0,1]
	s_waitcnt lgkmcnt(6)
	v_mfma_f32_16x16x32_bf16 v[128:131], v[228:231], v[216:219], v[128:131]
	ds_read_b128 v[228:231], v0 offset:48128
	s_waitcnt lgkmcnt(6)
	v_mfma_f32_16x16x32_bf16 v[148:151], v[232:235], v[224:227], v[128:131]
	s_nop 5
	v_mul_f32_e64 v130, v184, v138
	v_mul_f32_e64 v131, v184, v139
	v_pk_mul_f32 v[128:129], v[184:185], v[136:137] op_sel_hi:[0,1]
	s_waitcnt lgkmcnt(5)
	v_mfma_f32_16x16x32_bf16 v[128:131], v[236:239], v[216:219], v[128:131]
	s_waitcnt lgkmcnt(4)
	v_mfma_f32_16x16x32_bf16 v[152:155], v[240:243], v[224:227], v[128:131]
	s_nop 3
	v_pk_mul_f32 v[130:131], v[184:185], v[142:143] op_sel_hi:[0,1]
	v_pk_mul_f32 v[128:129], v[184:185], v[140:141] op_sel_hi:[0,1]
	s_nop 0
	s_waitcnt lgkmcnt(3)
	v_mfma_f32_16x16x32_bf16 v[128:131], v[244:247], v[216:219], v[128:131]
	s_waitcnt lgkmcnt(2)
	v_mfma_f32_16x16x32_bf16 v[156:159], v[248:251], v[224:227], v[128:131]
	s_waitcnt vmcnt(47)
	ds_write_b128 v185, v[32:35]
	s_waitcnt vmcnt(46)
	ds_write_b128 v185, v[36:39] offset:8192
	s_waitcnt vmcnt(45)
	ds_write_b128 v185, v[40:43] offset:16384
	s_waitcnt vmcnt(44)
	ds_write_b128 v185, v[44:47] offset:24576
	v_pk_mul_f32 v[130:131], v[184:185], v[162:163] op_sel_hi:[0,1]
	v_pk_mul_f32 v[128:129], v[184:185], v[160:161] op_sel_hi:[0,1]
	v_pk_mul_f32 v[34:35], v[184:185], v[166:167] op_sel_hi:[0,1]
	v_pk_mul_f32 v[32:33], v[184:185], v[164:165] op_sel_hi:[0,1]
	s_waitcnt lgkmcnt(5)
	v_mfma_f32_16x16x32_bf16 v[24:27], v[220:223], v[216:219], v[128:131]
	s_waitcnt lgkmcnt(4)
	v_mfma_f32_16x16x32_bf16 v[160:163], v[228:231], v[224:227], v[24:27]
	v_cvt_pk_bf16_f32 v20, v164, v165
	v_cvt_pk_bf16_f32 v21, v166, v167
	v_cvt_pk_bf16_f32 v22, v16, v17
	s_nop 2
	v_add_co_u32_e32 v24, vcc, s1, v186
	v_cvt_pk_bf16_f32 v23, v18, v19
	s_nop 0
	v_addc_co_u32_e32 v25, vcc, 0, v187, vcc
	global_load_dwordx4 v[128:131], v[188:189], off offset:2560
	global_load_dwordx4 v[132:135], v[190:191], off offset:2560
	global_load_dwordx4 v[136:139], v[192:193], off offset:2560
	global_load_dwordx4 v[140:143], v[194:195], off offset:2560
	s_waitcnt lgkmcnt(0)
	s_barrier
	global_store_dwordx4 v[24:25], v[20:23], off
	v_pk_mul_f32 v[18:19], v[184:185], v[18:19] op_sel_hi:[0,1]
	v_pk_mul_f32 v[16:17], v[184:185], v[16:17] op_sel_hi:[0,1]
	v_cvt_pk_bf16_f32 v20, v28, v29
	v_cvt_pk_bf16_f32 v21, v30, v31
	v_cvt_pk_bf16_f32 v22, v144, v145
	v_cvt_pk_bf16_f32 v23, v146, v147
	global_store_dwordx4 v[24:25], v[20:23], off offset:1024
	v_pk_mul_f32 v[30:31], v[184:185], v[30:31] op_sel_hi:[0,1]
	v_pk_mul_f32 v[28:29], v[184:185], v[28:29] op_sel_hi:[0,1]
	v_cvt_pk_bf16_f32 v20, v148, v149
	v_cvt_pk_bf16_f32 v21, v150, v151
	v_cvt_pk_bf16_f32 v22, v152, v153
	v_cvt_pk_bf16_f32 v23, v154, v155
	global_store_dwordx4 v[24:25], v[20:23], off offset:2048
	s_mov_b32 s1, 0x78000
	s_nop 0
	v_cvt_pk_bf16_f32 v20, v156, v157
	v_cvt_pk_bf16_f32 v21, v158, v159
	v_cvt_pk_bf16_f32 v22, v160, v161
	v_cvt_pk_bf16_f32 v23, v162, v163
	global_store_dwordx4 v[24:25], v[20:23], off offset:3072
	ds_read_b128 v[216:219], v208 offset:16384
	ds_read_b128 v[220:223], v0
	ds_read_b128 v[224:227], v208 offset:17408
	ds_read_b128 v[228:231], v0 offset:1024
	ds_read_b128 v[232:235], v0 offset:2048
	ds_read_b128 v[236:239], v0 offset:3072
	ds_read_b128 v[240:243], v0 offset:4096
	ds_read_b128 v[244:247], v0 offset:5120
	ds_read_b128 v[248:251], v0 offset:6144
	s_waitcnt lgkmcnt(7)
	v_mfma_f32_16x16x32_bf16 v[32:35], v[220:223], v[216:219], v[32:35]
	ds_read_b128 v[220:223], v0 offset:7168
	s_waitcnt lgkmcnt(6)
	v_mfma_f32_16x16x32_bf16 v[164:167], v[228:231], v[224:227], v[32:35]
	ds_read_b128 v[228:231], v0 offset:8192
	s_waitcnt lgkmcnt(6)
	v_mfma_f32_16x16x32_bf16 v[16:19], v[232:235], v[216:219], v[16:19]
	ds_read_b128 v[232:235], v0 offset:9216
	s_waitcnt lgkmcnt(6)
	v_mfma_f32_16x16x32_bf16 v[16:19], v[236:239], v[224:227], v[16:19]
	ds_read_b128 v[236:239], v0 offset:10240
	s_waitcnt lgkmcnt(6)
	v_mfma_f32_16x16x32_bf16 v[28:31], v[240:243], v[216:219], v[28:31]
	ds_read_b128 v[240:243], v0 offset:11264
	v_mul_f32_e64 v34, v184, v146
	v_mul_f32_e64 v35, v184, v147
	v_pk_mul_f32 v[32:33], v[184:185], v[144:145] op_sel_hi:[0,1]
	s_waitcnt lgkmcnt(6)
	v_mfma_f32_16x16x32_bf16 v[28:31], v[244:247], v[224:227], v[28:31]
	ds_read_b128 v[244:247], v0 offset:12288
	s_waitcnt lgkmcnt(6)
	v_mfma_f32_16x16x32_bf16 v[32:35], v[248:251], v[216:219], v[32:35]
	ds_read_b128 v[248:251], v0 offset:13312
	v_mul_f32_e64 v38, v184, v150
	v_mul_f32_e64 v39, v184, v151
	v_pk_mul_f32 v[36:37], v[184:185], v[148:149] op_sel_hi:[0,1]
	s_waitcnt lgkmcnt(6)
	v_mfma_f32_16x16x32_bf16 v[32:35], v[220:223], v[224:227], v[32:35]
	ds_read_b128 v[220:223], v0 offset:14336
	s_waitcnt lgkmcnt(6)
	v_mfma_f32_16x16x32_bf16 v[36:39], v[228:231], v[216:219], v[36:39]
	ds_read_b128 v[228:231], v0 offset:15360
	v_mul_f32_e64 v42, v184, v154
	v_mul_f32_e64 v43, v184, v155
	v_pk_mul_f32 v[40:41], v[184:185], v[152:153] op_sel_hi:[0,1]
	s_waitcnt lgkmcnt(6)
	v_mfma_f32_16x16x32_bf16 v[36:39], v[232:235], v[224:227], v[36:39]
	s_waitcnt lgkmcnt(5)
	v_mfma_f32_16x16x32_bf16 v[40:43], v[236:239], v[216:219], v[40:43]
	v_mul_f32_e64 v46, v184, v158
	v_mul_f32_e64 v47, v184, v159
	v_pk_mul_f32 v[44:45], v[184:185], v[156:157] op_sel_hi:[0,1]
	s_waitcnt lgkmcnt(4)
	v_mfma_f32_16x16x32_bf16 v[40:43], v[240:243], v[224:227], v[40:43]
	s_waitcnt lgkmcnt(3)
	v_mfma_f32_16x16x32_bf16 v[44:47], v[244:247], v[216:219], v[44:47]
	v_mul_f32_e64 v146, v184, v162
	v_mul_f32_e64 v147, v184, v163
	v_pk_mul_f32 v[144:145], v[184:185], v[160:161] op_sel_hi:[0,1]
	s_waitcnt lgkmcnt(2)
	v_mfma_f32_16x16x32_bf16 v[44:47], v[248:251], v[224:227], v[44:47]
	s_waitcnt vmcnt(47)
	ds_write_b128 v185, v[48:51] offset:32768
	s_waitcnt vmcnt(46)
	ds_write_b128 v185, v[52:55] offset:40960
	s_waitcnt vmcnt(45)
	ds_write_b128 v185, v[56:59] offset:49152
	s_waitcnt vmcnt(44)
	ds_write_b128 v185, v[60:63] offset:57344
	v_pk_mul_f32 v[50:51], v[184:185], v[166:167] op_sel_hi:[0,1]
	s_waitcnt lgkmcnt(5)
	v_mfma_f32_16x16x32_bf16 v[24:27], v[220:223], v[216:219], v[144:147]
	v_mul_f32_e64 v48, v184, v164
	v_mul_f32_e64 v49, v184, v165
	s_waitcnt lgkmcnt(4)
	v_mfma_f32_16x16x32_bf16 v[160:163], v[228:231], v[224:227], v[24:27]
	v_cvt_pk_bf16_f32 v20, v164, v165
	v_cvt_pk_bf16_f32 v21, v166, v167
	v_cvt_pk_bf16_f32 v22, v16, v17
	s_nop 0
	v_add_co_u32_e32 v24, vcc, s1, v186
	v_cvt_pk_bf16_f32 v23, v18, v19
	s_nop 0
	v_addc_co_u32_e32 v25, vcc, 0, v187, vcc
	global_load_dwordx4 v[144:147], v[188:189], off offset:2688
	global_load_dwordx4 v[148:151], v[190:191], off offset:2688
	global_load_dwordx4 v[152:155], v[192:193], off offset:2688
	global_load_dwordx4 v[156:159], v[194:195], off offset:2688
	s_waitcnt lgkmcnt(0)
	s_barrier
	global_store_dwordx4 v[24:25], v[20:23], off
	v_pk_mul_f32 v[18:19], v[184:185], v[18:19] op_sel_hi:[0,1]
	v_pk_mul_f32 v[16:17], v[184:185], v[16:17] op_sel_hi:[0,1]
	v_cvt_pk_bf16_f32 v20, v28, v29
	v_cvt_pk_bf16_f32 v21, v30, v31
	v_cvt_pk_bf16_f32 v22, v32, v33
	v_cvt_pk_bf16_f32 v23, v34, v35
	global_store_dwordx4 v[24:25], v[20:23], off offset:1024
	v_pk_mul_f32 v[30:31], v[184:185], v[30:31] op_sel_hi:[0,1]
	v_pk_mul_f32 v[28:29], v[184:185], v[28:29] op_sel_hi:[0,1]
	v_cvt_pk_bf16_f32 v20, v36, v37
	v_cvt_pk_bf16_f32 v21, v38, v39
	v_cvt_pk_bf16_f32 v22, v40, v41
	v_cvt_pk_bf16_f32 v23, v42, v43
	global_store_dwordx4 v[24:25], v[20:23], off offset:2048
	v_pk_mul_f32 v[34:35], v[184:185], v[34:35] op_sel_hi:[0,1]
	v_pk_mul_f32 v[32:33], v[184:185], v[32:33] op_sel_hi:[0,1]
	v_cvt_pk_bf16_f32 v20, v44, v45
	v_cvt_pk_bf16_f32 v21, v46, v47
	v_cvt_pk_bf16_f32 v22, v160, v161
	v_cvt_pk_bf16_f32 v23, v162, v163
	global_store_dwordx4 v[24:25], v[20:23], off offset:3072
	ds_read_b128 v[216:219], v208 offset:49152
	ds_read_b128 v[220:223], v0 offset:32768
	ds_read_b128 v[224:227], v0 offset:33792
	ds_read_b128 v[228:231], v0 offset:34816
	ds_read_b128 v[232:235], v0 offset:35840
	ds_read_b128 v[236:239], v0 offset:36864
	ds_read_b128 v[240:243], v0 offset:37888
	ds_read_b128 v[244:247], v0 offset:38912
	ds_read_b128 v[248:251], v0 offset:39936
	ds_read_b128 v[20:23], v208 offset:50176
	s_waitcnt lgkmcnt(8)
	v_mfma_f32_16x16x32_bf16 v[48:51], v[220:223], v[216:219], v[48:51]
	ds_read_b128 v[220:223], v0 offset:40960
	s_mov_b32 s1, 0x88000
	s_waitcnt lgkmcnt(1)
	v_mfma_f32_16x16x32_bf16 v[52:55], v[224:227], v[20:23], v[48:51]
	ds_read_b128 v[224:227], v0 offset:41984
	s_waitcnt lgkmcnt(8)
	v_mfma_f32_16x16x32_bf16 v[16:19], v[228:231], v[216:219], v[16:19]
	ds_read_b128 v[228:231], v0 offset:43008
	s_waitcnt lgkmcnt(3)
	v_mfma_f32_16x16x32_bf16 v[16:19], v[232:235], v[20:23], v[16:19]
	ds_read_b128 v[232:235], v0 offset:44032
	s_waitcnt lgkmcnt(8)
	v_mfma_f32_16x16x32_bf16 v[28:31], v[236:239], v[216:219], v[28:31]
	ds_read_b128 v[236:239], v0 offset:45056
	s_waitcnt lgkmcnt(5)
	v_mfma_f32_16x16x32_bf16 v[28:31], v[240:243], v[20:23], v[28:31]
	ds_read_b128 v[240:243], v0 offset:46080
	s_waitcnt lgkmcnt(8)
	v_mfma_f32_16x16x32_bf16 v[32:35], v[244:247], v[216:219], v[32:35]
	ds_read_b128 v[244:247], v0 offset:47104
	s_waitcnt lgkmcnt(7)
	v_mfma_f32_16x16x32_bf16 v[48:51], v[248:251], v[20:23], v[32:35]
	s_nop 5
	v_mul_f32_e64 v34, v184, v38
	v_mul_f32_e64 v35, v184, v39
	v_pk_mul_f32 v[32:33], v[184:185], v[36:37] op_sel_hi:[0,1]
	s_waitcnt lgkmcnt(6)
	v_mfma_f32_16x16x32_bf16 v[32:35], v[220:223], v[216:219], v[32:35]
	s_waitcnt lgkmcnt(5)
	v_mfma_f32_16x16x32_bf16 v[36:39], v[224:227], v[20:23], v[32:35]
	s_nop 5
	v_mul_f32_e64 v34, v184, v42
	v_mul_f32_e64 v35, v184, v43
	v_pk_mul_f32 v[32:33], v[184:185], v[40:41] op_sel_hi:[0,1]
	s_waitcnt lgkmcnt(4)
	v_mfma_f32_16x16x32_bf16 v[32:35], v[228:231], v[216:219], v[32:35]
	s_waitcnt lgkmcnt(3)
	v_mfma_f32_16x16x32_bf16 v[56:59], v[232:235], v[20:23], v[32:35]
	s_nop 5
	v_mul_f32_e64 v34, v184, v46
	v_mul_f32_e64 v35, v184, v47
	v_pk_mul_f32 v[32:33], v[184:185], v[44:45] op_sel_hi:[0,1]
	s_waitcnt lgkmcnt(2)
	v_mfma_f32_16x16x32_bf16 v[32:35], v[236:239], v[216:219], v[32:35]
	s_waitcnt lgkmcnt(1)
	v_mfma_f32_16x16x32_bf16 v[60:63], v[240:243], v[20:23], v[32:35]
	ds_read_b128 v[44:47], v0 offset:48128
	s_waitcnt vmcnt(47)
	ds_write_b128 v185, v[64:67]
	s_waitcnt vmcnt(46)
	ds_write_b128 v185, v[68:71] offset:8192
	s_waitcnt vmcnt(45)
	ds_write_b128 v185, v[72:75] offset:16384
	s_waitcnt vmcnt(44)
	ds_write_b128 v185, v[76:79] offset:24576
	v_pk_mul_f32 v[34:35], v[184:185], v[162:163] op_sel_hi:[0,1]
	v_pk_mul_f32 v[32:33], v[184:185], v[160:161] op_sel_hi:[0,1]
	global_load_dwordx4 v[160:163], v[188:189], off offset:2816
	global_load_dwordx4 v[164:167], v[190:191], off offset:2816
	global_load_dwordx4 v[168:171], v[192:193], off offset:2816
	global_load_dwordx4 v[172:175], v[194:195], off offset:2816
	s_waitcnt lgkmcnt(5)
	v_mfma_f32_16x16x32_bf16 v[24:27], v[244:247], v[216:219], v[32:35]
	s_waitcnt lgkmcnt(0)
	s_barrier
	v_mfma_f32_16x16x32_bf16 v[176:179], v[44:47], v[20:23], v[24:27]
	ds_read_b128 v[216:219], v208 offset:16384
	ds_read_b128 v[220:223], v0
	ds_read_b128 v[224:227], v208 offset:17408
	ds_read_b128 v[228:231], v0 offset:1024
	ds_read_b128 v[232:235], v0 offset:2048
	ds_read_b128 v[236:239], v0 offset:3072
	ds_read_b128 v[240:243], v0 offset:4096
	ds_read_b128 v[244:247], v0 offset:5120
	ds_read_b128 v[248:251], v0 offset:6144
	v_cvt_pk_bf16_f32 v20, v52, v53
	v_cvt_pk_bf16_f32 v21, v54, v55
	v_cvt_pk_bf16_f32 v22, v16, v17
	s_nop 1
	v_add_co_u32_e32 v24, vcc, s15, v186
	v_cvt_pk_bf16_f32 v23, v18, v19
	s_nop 0
	v_addc_co_u32_e32 v25, vcc, 0, v187, vcc
	global_store_dwordx4 v[24:25], v[20:23], off
	v_pk_mul_f32 v[34:35], v[184:185], v[54:55] op_sel_hi:[0,1]
	v_pk_mul_f32 v[32:33], v[184:185], v[52:53] op_sel_hi:[0,1]
	v_cvt_pk_bf16_f32 v20, v28, v29
	v_cvt_pk_bf16_f32 v21, v30, v31
	v_cvt_pk_bf16_f32 v22, v48, v49
	v_cvt_pk_bf16_f32 v23, v50, v51
	global_store_dwordx4 v[24:25], v[20:23], off offset:1024
	v_pk_mul_f32 v[18:19], v[184:185], v[18:19] op_sel_hi:[0,1]
	v_pk_mul_f32 v[16:17], v[184:185], v[16:17] op_sel_hi:[0,1]
	v_cvt_pk_bf16_f32 v20, v36, v37
	v_cvt_pk_bf16_f32 v21, v38, v39
	v_cvt_pk_bf16_f32 v22, v56, v57
	v_cvt_pk_bf16_f32 v23, v58, v59
	global_store_dwordx4 v[24:25], v[20:23], off offset:2048
	s_nop 1
	v_cvt_pk_bf16_f32 v20, v60, v61
	v_cvt_pk_bf16_f32 v21, v62, v63
	v_cvt_pk_bf16_f32 v22, v176, v177
	v_cvt_pk_bf16_f32 v23, v178, v179
	global_store_dwordx4 v[24:25], v[20:23], off offset:3072
	s_waitcnt lgkmcnt(7)
	v_mfma_f32_16x16x32_bf16 v[32:35], v[220:223], v[216:219], v[32:35]
	ds_read_b128 v[220:223], v0 offset:7168
	s_waitcnt lgkmcnt(6)
	v_mfma_f32_16x16x32_bf16 v[68:71], v[228:231], v[224:227], v[32:35]
	ds_read_b128 v[228:231], v0 offset:8192
	s_waitcnt lgkmcnt(6)
	v_mfma_f32_16x16x32_bf16 v[16:19], v[232:235], v[216:219], v[16:19]
	ds_read_b128 v[232:235], v0 offset:9216
	s_waitcnt lgkmcnt(6)
	v_mfma_f32_16x16x32_bf16 v[32:35], v[236:239], v[224:227], v[16:19]
	ds_read_b128 v[236:239], v0 offset:10240
	s_nop 5
	v_mul_f32_e64 v18, v184, v30
	v_mul_f32_e64 v19, v184, v31
	v_pk_mul_f32 v[16:17], v[184:185], v[28:29] op_sel_hi:[0,1]
	s_waitcnt lgkmcnt(6)
	v_mfma_f32_16x16x32_bf16 v[16:19], v[240:243], v[216:219], v[16:19]
	ds_read_b128 v[240:243], v0 offset:11264
	s_waitcnt lgkmcnt(6)
	v_mfma_f32_16x16x32_bf16 v[40:43], v[244:247], v[224:227], v[16:19]
	ds_read_b128 v[244:247], v0 offset:12288
	s_nop 3
	v_mul_f32_e64 v18, v184, v50
	v_mul_f32_e64 v19, v184, v51
	v_pk_mul_f32 v[16:17], v[184:185], v[48:49] op_sel_hi:[0,1]
	v_add_co_u32_e32 v48, vcc, s1, v186
	s_waitcnt lgkmcnt(6)
	v_mfma_f32_16x16x32_bf16 v[16:19], v[248:251], v[216:219], v[16:19]
	ds_read_b128 v[248:251], v0 offset:13312
	v_addc_co_u32_e32 v49, vcc, 0, v187, vcc
	v_pk_mul_f32 v[50:51], v[184:185], v[70:71] op_sel_hi:[0,1]
	s_waitcnt lgkmcnt(6)
	v_mfma_f32_16x16x32_bf16 v[44:47], v[220:223], v[224:227], v[16:19]
	ds_read_b128 v[220:223], v0 offset:14336
	s_mov_b32 s1, 0x90000
	s_nop 2
	v_pk_mul_f32 v[18:19], v[184:185], v[38:39] op_sel_hi:[0,1]
	v_pk_mul_f32 v[16:17], v[184:185], v[36:37] op_sel_hi:[0,1]
	s_waitcnt lgkmcnt(6)
	v_mfma_f32_16x16x32_bf16 v[16:19], v[228:231], v[216:219], v[16:19]
	ds_read_b128 v[228:231], v0 offset:15360
	s_waitcnt lgkmcnt(6)
	v_mfma_f32_16x16x32_bf16 v[52:55], v[232:235], v[224:227], v[16:19]
	s_nop 3
	v_pk_mul_f32 v[18:19], v[184:185], v[58:59] op_sel_hi:[0,1]
	v_pk_mul_f32 v[16:17], v[184:185], v[56:57] op_sel_hi:[0,1]
	s_nop 0
	s_waitcnt lgkmcnt(5)
	v_mfma_f32_16x16x32_bf16 v[16:19], v[236:239], v[216:219], v[16:19]
	s_waitcnt lgkmcnt(4)
	v_mfma_f32_16x16x32_bf16 v[56:59], v[240:243], v[224:227], v[16:19]
	s_nop 3
	v_pk_mul_f32 v[18:19], v[184:185], v[62:63] op_sel_hi:[0,1]
	v_pk_mul_f32 v[16:17], v[184:185], v[60:61] op_sel_hi:[0,1]
	s_nop 0
	s_waitcnt lgkmcnt(3)
	v_mfma_f32_16x16x32_bf16 v[16:19], v[244:247], v[216:219], v[16:19]
	s_waitcnt lgkmcnt(2)
	v_mfma_f32_16x16x32_bf16 v[60:63], v[248:251], v[224:227], v[16:19]
	s_waitcnt vmcnt(47)
	ds_write_b128 v185, v[80:83] offset:32768
	s_waitcnt vmcnt(46)
	ds_write_b128 v185, v[84:87] offset:40960
	s_waitcnt vmcnt(45)
	ds_write_b128 v185, v[88:91] offset:49152
	s_waitcnt vmcnt(44)
	ds_write_b128 v185, v[92:95] offset:57344
	v_pk_mul_f32 v[18:19], v[184:185], v[178:179] op_sel_hi:[0,1]
	v_pk_mul_f32 v[16:17], v[184:185], v[176:177] op_sel_hi:[0,1]
	s_nop 0
	s_waitcnt lgkmcnt(5)
	v_mfma_f32_16x16x32_bf16 v[16:19], v[220:223], v[216:219], v[16:19]
	s_waitcnt lgkmcnt(4)
	v_mfma_f32_16x16x32_bf16 v[176:179], v[228:231], v[224:227], v[16:19]
	v_cvt_pk_bf16_f32 v36, v68, v69
	v_cvt_pk_bf16_f32 v37, v70, v71
	v_cvt_pk_bf16_f32 v38, v32, v33
	v_cvt_pk_bf16_f32 v39, v34, v35
	s_nop 1
	global_load_dwordx4 v[16:19], v[188:189], off offset:2944
	global_load_dwordx4 v[20:23], v[190:191], off offset:2944
	global_load_dwordx4 v[24:27], v[192:193], off offset:2944
	global_load_dwordx4 v[28:31], v[194:195], off offset:2944
	s_waitcnt lgkmcnt(0)
	s_barrier
	global_store_dwordx4 v[48:49], v[36:39], off
	v_pk_mul_f32 v[34:35], v[184:185], v[34:35] op_sel_hi:[0,1]
	v_pk_mul_f32 v[32:33], v[184:185], v[32:33] op_sel_hi:[0,1]
	v_cvt_pk_bf16_f32 v36, v40, v41
	v_cvt_pk_bf16_f32 v37, v42, v43
	v_cvt_pk_bf16_f32 v38, v44, v45
	v_cvt_pk_bf16_f32 v39, v46, v47
	global_store_dwordx4 v[48:49], v[36:39], off offset:1024
	s_nop 1
	v_cvt_pk_bf16_f32 v36, v52, v53
	v_cvt_pk_bf16_f32 v37, v54, v55
	v_cvt_pk_bf16_f32 v38, v56, v57
	v_cvt_pk_bf16_f32 v39, v58, v59
	global_store_dwordx4 v[48:49], v[36:39], off offset:2048
	s_nop 1
	v_cvt_pk_bf16_f32 v36, v60, v61
	v_cvt_pk_bf16_f32 v37, v62, v63
	v_cvt_pk_bf16_f32 v38, v176, v177
	v_cvt_pk_bf16_f32 v39, v178, v179
	global_store_dwordx4 v[48:49], v[36:39], off offset:3072
	ds_read_b128 v[216:219], v208 offset:49152
	ds_read_b128 v[220:223], v0 offset:32768
	ds_read_b128 v[224:227], v208 offset:50176
	ds_read_b128 v[228:231], v0 offset:33792
	ds_read_b128 v[232:235], v0 offset:34816
	ds_read_b128 v[236:239], v0 offset:35840
	ds_read_b128 v[240:243], v0 offset:36864
	ds_read_b128 v[244:247], v0 offset:37888
	ds_read_b128 v[248:251], v0 offset:38912
	v_pk_mul_f32 v[48:49], v[184:185], v[68:69] op_sel_hi:[0,1]
	s_waitcnt lgkmcnt(7)
	v_mfma_f32_16x16x32_bf16 v[48:51], v[220:223], v[216:219], v[48:51]
	ds_read_b128 v[220:223], v0 offset:39936
	s_waitcnt lgkmcnt(6)
	v_mfma_f32_16x16x32_bf16 v[84:87], v[228:231], v[224:227], v[48:51]
	ds_read_b128 v[228:231], v0 offset:40960
	s_waitcnt lgkmcnt(6)
	v_mfma_f32_16x16x32_bf16 v[32:35], v[232:235], v[216:219], v[32:35]
	ds_read_b128 v[232:235], v0 offset:41984
	s_waitcnt lgkmcnt(6)
	v_mfma_f32_16x16x32_bf16 v[48:51], v[236:239], v[224:227], v[32:35]
	ds_read_b128 v[236:239], v0 offset:43008
	s_nop 5
	v_mul_f32_e64 v34, v184, v42
	v_mul_f32_e64 v35, v184, v43
	v_pk_mul_f32 v[32:33], v[184:185], v[40:41] op_sel_hi:[0,1]
	s_waitcnt lgkmcnt(6)
	v_mfma_f32_16x16x32_bf16 v[32:35], v[240:243], v[216:219], v[32:35]
	ds_read_b128 v[240:243], v0 offset:44032
	s_waitcnt lgkmcnt(6)
	v_mfma_f32_16x16x32_bf16 v[68:71], v[244:247], v[224:227], v[32:35]
	ds_read_b128 v[244:247], v0 offset:45056
	s_nop 5
	v_mul_f32_e64 v34, v184, v46
	v_mul_f32_e64 v35, v184, v47
	v_pk_mul_f32 v[32:33], v[184:185], v[44:45] op_sel_hi:[0,1]
	s_waitcnt lgkmcnt(6)
	v_mfma_f32_16x16x32_bf16 v[32:35], v[248:251], v[216:219], v[32:35]
	ds_read_b128 v[248:251], v0 offset:46080
	s_waitcnt lgkmcnt(6)
	v_mfma_f32_16x16x32_bf16 v[72:75], v[220:223], v[224:227], v[32:35]
	ds_read_b128 v[220:223], v0 offset:47104
	s_nop 3
	v_pk_mul_f32 v[34:35], v[184:185], v[54:55] op_sel_hi:[0,1]
	v_pk_mul_f32 v[32:33], v[184:185], v[52:53] op_sel_hi:[0,1]
	v_cvt_pk_bf16_f32 v52, v84, v85
	v_cvt_pk_bf16_f32 v53, v86, v87
	s_waitcnt lgkmcnt(6)
	v_mfma_f32_16x16x32_bf16 v[32:35], v[228:231], v[216:219], v[32:35]
	ds_read_b128 v[228:231], v0 offset:48128
	v_cvt_pk_bf16_f32 v54, v48, v49
	v_cvt_pk_bf16_f32 v55, v50, v51
	v_pk_mul_f32 v[50:51], v[184:185], v[50:51] op_sel_hi:[0,1]
	s_waitcnt lgkmcnt(6)
	v_mfma_f32_16x16x32_bf16 v[76:79], v[232:235], v[224:227], v[32:35]
	v_pk_mul_f32 v[48:49], v[184:185], v[48:49] op_sel_hi:[0,1]
	v_pk_mul_f32 v[34:35], v[184:185], v[58:59] op_sel_hi:[0,1]
	v_pk_mul_f32 v[32:33], v[184:185], v[56:57] op_sel_hi:[0,1]
	s_nop 0
	s_waitcnt lgkmcnt(5)
	v_mfma_f32_16x16x32_bf16 v[32:35], v[236:239], v[216:219], v[32:35]
	s_waitcnt lgkmcnt(4)
	v_mfma_f32_16x16x32_bf16 v[56:59], v[240:243], v[224:227], v[32:35]
	s_nop 3
	v_pk_mul_f32 v[34:35], v[184:185], v[62:63] op_sel_hi:[0,1]
	v_pk_mul_f32 v[32:33], v[184:185], v[60:61] op_sel_hi:[0,1]
	s_nop 0
	s_waitcnt lgkmcnt(3)
	v_mfma_f32_16x16x32_bf16 v[32:35], v[244:247], v[216:219], v[32:35]
	s_waitcnt lgkmcnt(2)
	v_mfma_f32_16x16x32_bf16 v[60:63], v[248:251], v[224:227], v[32:35]
	s_waitcnt vmcnt(47)
	ds_write_b128 v185, v[96:99]
	s_waitcnt vmcnt(46)
	ds_write_b128 v185, v[100:103] offset:8192
	s_waitcnt vmcnt(45)
	ds_write_b128 v185, v[104:107] offset:16384
	s_waitcnt vmcnt(44)
	ds_write_b128 v185, v[108:111] offset:24576
	v_pk_mul_f32 v[34:35], v[184:185], v[178:179] op_sel_hi:[0,1]
	v_pk_mul_f32 v[32:33], v[184:185], v[176:177] op_sel_hi:[0,1]
	s_nop 0
	s_waitcnt lgkmcnt(5)
	v_mfma_f32_16x16x32_bf16 v[32:35], v[220:223], v[216:219], v[32:35]
	v_add_co_u32_e32 v64, vcc, s1, v186
	v_pk_mul_f32 v[66:67], v[184:185], v[86:87] op_sel_hi:[0,1]
	s_waitcnt lgkmcnt(4)
	v_mfma_f32_16x16x32_bf16 v[176:179], v[228:231], v[224:227], v[32:35]
	v_addc_co_u32_e32 v65, vcc, 0, v187, vcc
	s_nop 2
	global_load_dwordx4 v[32:35], v[188:189], off offset:3072
	global_load_dwordx4 v[36:39], v[190:191], off offset:3072
	global_load_dwordx4 v[40:43], v[192:193], off offset:3072
	global_load_dwordx4 v[44:47], v[194:195], off offset:3072
	s_waitcnt lgkmcnt(0)
	s_barrier
	global_store_dwordx4 v[64:65], v[52:55], off
	s_mov_b32 s1, 0x98000
	s_nop 0
	v_cvt_pk_bf16_f32 v52, v68, v69
	v_cvt_pk_bf16_f32 v53, v70, v71
	v_cvt_pk_bf16_f32 v54, v72, v73
	v_cvt_pk_bf16_f32 v55, v74, v75
	global_store_dwordx4 v[64:65], v[52:55], off offset:1024
	s_nop 1
	v_cvt_pk_bf16_f32 v52, v76, v77
	v_cvt_pk_bf16_f32 v53, v78, v79
	v_cvt_pk_bf16_f32 v54, v56, v57
	v_cvt_pk_bf16_f32 v55, v58, v59
	global_store_dwordx4 v[64:65], v[52:55], off offset:2048
	s_nop 1
	v_cvt_pk_bf16_f32 v52, v60, v61
	v_cvt_pk_bf16_f32 v53, v62, v63
	v_cvt_pk_bf16_f32 v54, v176, v177
	v_cvt_pk_bf16_f32 v55, v178, v179
	global_store_dwordx4 v[64:65], v[52:55], off offset:3072
	ds_read_b128 v[216:219], v208 offset:16384
	ds_read_b128 v[220:223], v0
	ds_read_b128 v[224:227], v208 offset:17408
	ds_read_b128 v[228:231], v0 offset:1024
	ds_read_b128 v[232:235], v0 offset:2048
	ds_read_b128 v[236:239], v0 offset:3072
	ds_read_b128 v[240:243], v0 offset:4096
	ds_read_b128 v[244:247], v0 offset:5120
	ds_read_b128 v[248:251], v0 offset:6144
	v_pk_mul_f32 v[64:65], v[184:185], v[84:85] op_sel_hi:[0,1]
	s_waitcnt lgkmcnt(7)
	v_mfma_f32_16x16x32_bf16 v[64:67], v[220:223], v[216:219], v[64:67]
	ds_read_b128 v[220:223], v0 offset:7168
	s_waitcnt lgkmcnt(6)
	v_mfma_f32_16x16x32_bf16 v[100:103], v[228:231], v[224:227], v[64:67]
	ds_read_b128 v[228:231], v0 offset:8192
	s_waitcnt lgkmcnt(6)
	v_mfma_f32_16x16x32_bf16 v[48:51], v[232:235], v[216:219], v[48:51]
	ds_read_b128 v[232:235], v0 offset:9216
	s_waitcnt lgkmcnt(6)
	v_mfma_f32_16x16x32_bf16 v[64:67], v[236:239], v[224:227], v[48:51]
	ds_read_b128 v[236:239], v0 offset:10240
	s_nop 5
	v_mul_f32_e64 v50, v184, v70
	v_mul_f32_e64 v51, v184, v71
	v_pk_mul_f32 v[48:49], v[184:185], v[68:69] op_sel_hi:[0,1]
	s_waitcnt lgkmcnt(6)
	v_mfma_f32_16x16x32_bf16 v[48:51], v[240:243], v[216:219], v[48:51]
	ds_read_b128 v[240:243], v0 offset:11264
	s_waitcnt lgkmcnt(6)
	v_mfma_f32_16x16x32_bf16 v[84:87], v[244:247], v[224:227], v[48:51]
	ds_read_b128 v[244:247], v0 offset:12288
	s_nop 5
	v_mul_f32_e64 v50, v184, v74
	v_mul_f32_e64 v51, v184, v75
	v_pk_mul_f32 v[48:49], v[184:185], v[72:73] op_sel_hi:[0,1]
	s_waitcnt lgkmcnt(6)
	v_mfma_f32_16x16x32_bf16 v[48:51], v[248:251], v[216:219], v[48:51]
	ds_read_b128 v[248:251], v0 offset:13312
	s_waitcnt lgkmcnt(6)
	v_mfma_f32_16x16x32_bf16 v[72:75], v[220:223], v[224:227], v[48:51]
	ds_read_b128 v[220:223], v0 offset:14336
	s_nop 5
	v_mul_f32_e64 v50, v184, v78
	v_mul_f32_e64 v51, v184, v79
	v_pk_mul_f32 v[48:49], v[184:185], v[76:77] op_sel_hi:[0,1]
	s_waitcnt lgkmcnt(6)
	v_mfma_f32_16x16x32_bf16 v[48:51], v[228:231], v[216:219], v[48:51]
	ds_read_b128 v[228:231], v0 offset:15360
	s_waitcnt lgkmcnt(6)
	v_mfma_f32_16x16x32_bf16 v[76:79], v[232:235], v[224:227], v[48:51]
	s_nop 5
	v_mul_f32_e64 v50, v184, v58
	v_mul_f32_e64 v51, v184, v59
	v_pk_mul_f32 v[48:49], v[184:185], v[56:57] op_sel_hi:[0,1]
	s_waitcnt lgkmcnt(5)
	v_mfma_f32_16x16x32_bf16 v[48:51], v[236:239], v[216:219], v[48:51]
	s_waitcnt lgkmcnt(4)
	v_mfma_f32_16x16x32_bf16 v[88:91], v[240:243], v[224:227], v[48:51]
	v_cvt_pk_bf16_f32 v68, v100, v101
	v_cvt_pk_bf16_f32 v69, v102, v103
	v_cvt_pk_bf16_f32 v70, v64, v65
	s_nop 2
	v_pk_mul_f32 v[50:51], v[184:185], v[62:63] op_sel_hi:[0,1]
	v_pk_mul_f32 v[48:49], v[184:185], v[60:61] op_sel_hi:[0,1]
	s_waitcnt lgkmcnt(3)
	v_mfma_f32_16x16x32_bf16 v[48:51], v[244:247], v[216:219], v[48:51]
	v_cvt_pk_bf16_f32 v71, v66, v67
	v_pk_mul_f32 v[66:67], v[184:185], v[66:67] op_sel_hi:[0,1]
	v_pk_mul_f32 v[64:65], v[184:185], v[64:65] op_sel_hi:[0,1]
	s_waitcnt lgkmcnt(2)
	v_mfma_f32_16x16x32_bf16 v[92:95], v[248:251], v[224:227], v[48:51]
	s_waitcnt vmcnt(47)
	ds_write_b128 v185, v[112:115] offset:32768
	s_waitcnt vmcnt(46)
	ds_write_b128 v185, v[116:119] offset:40960
	s_waitcnt vmcnt(45)
	ds_write_b128 v185, v[120:123] offset:49152
	s_waitcnt vmcnt(44)
	ds_write_b128 v185, v[124:127] offset:57344
	v_pk_mul_f32 v[50:51], v[184:185], v[178:179] op_sel_hi:[0,1]
	v_pk_mul_f32 v[48:49], v[184:185], v[176:177] op_sel_hi:[0,1]
	s_nop 0
	s_waitcnt lgkmcnt(5)
	v_mfma_f32_16x16x32_bf16 v[48:51], v[220:223], v[216:219], v[48:51]
	v_add_co_u32_e32 v80, vcc, s1, v186
	v_pk_mul_f32 v[82:83], v[184:185], v[102:103] op_sel_hi:[0,1]
	s_waitcnt lgkmcnt(4)
	v_mfma_f32_16x16x32_bf16 v[176:179], v[228:231], v[224:227], v[48:51]
	v_addc_co_u32_e32 v81, vcc, 0, v187, vcc
	s_nop 2
	global_load_dwordx4 v[48:51], v[188:189], off offset:3200
	global_load_dwordx4 v[52:55], v[190:191], off offset:3200
	global_load_dwordx4 v[56:59], v[192:193], off offset:3200
	global_load_dwordx4 v[60:63], v[194:195], off offset:3200
	s_waitcnt lgkmcnt(0)
	s_barrier
	global_store_dwordx4 v[80:81], v[68:71], off
	s_mov_b32 s1, 0xa0000
	s_nop 0
	v_cvt_pk_bf16_f32 v68, v84, v85
	v_cvt_pk_bf16_f32 v69, v86, v87
	v_cvt_pk_bf16_f32 v70, v72, v73
	v_cvt_pk_bf16_f32 v71, v74, v75
	global_store_dwordx4 v[80:81], v[68:71], off offset:1024
	s_nop 1
	v_cvt_pk_bf16_f32 v68, v76, v77
	v_cvt_pk_bf16_f32 v69, v78, v79
	v_cvt_pk_bf16_f32 v70, v88, v89
	v_cvt_pk_bf16_f32 v71, v90, v91
	global_store_dwordx4 v[80:81], v[68:71], off offset:2048
	s_nop 1
	v_cvt_pk_bf16_f32 v68, v92, v93
	v_cvt_pk_bf16_f32 v69, v94, v95
	v_cvt_pk_bf16_f32 v70, v176, v177
	v_cvt_pk_bf16_f32 v71, v178, v179
	global_store_dwordx4 v[80:81], v[68:71], off offset:3072
	ds_read_b128 v[216:219], v208 offset:49152
	ds_read_b128 v[220:223], v0 offset:32768
	ds_read_b128 v[224:227], v208 offset:50176
	ds_read_b128 v[228:231], v0 offset:33792
	ds_read_b128 v[232:235], v0 offset:34816
	ds_read_b128 v[236:239], v0 offset:35840
	ds_read_b128 v[240:243], v0 offset:36864
	ds_read_b128 v[244:247], v0 offset:37888
	ds_read_b128 v[248:251], v0 offset:38912
	v_pk_mul_f32 v[80:81], v[184:185], v[100:101] op_sel_hi:[0,1]
	s_waitcnt lgkmcnt(7)
	v_mfma_f32_16x16x32_bf16 v[80:83], v[220:223], v[216:219], v[80:83]
	ds_read_b128 v[220:223], v0 offset:39936
	s_waitcnt lgkmcnt(6)
	v_mfma_f32_16x16x32_bf16 v[116:119], v[228:231], v[224:227], v[80:83]
	ds_read_b128 v[228:231], v0 offset:40960
	s_waitcnt lgkmcnt(6)
	v_mfma_f32_16x16x32_bf16 v[64:67], v[232:235], v[216:219], v[64:67]
	ds_read_b128 v[232:235], v0 offset:41984
	s_waitcnt lgkmcnt(6)
	v_mfma_f32_16x16x32_bf16 v[80:83], v[236:239], v[224:227], v[64:67]
	ds_read_b128 v[236:239], v0 offset:43008
	s_nop 5
	v_mul_f32_e64 v66, v184, v86
	v_mul_f32_e64 v67, v184, v87
	v_pk_mul_f32 v[64:65], v[184:185], v[84:85] op_sel_hi:[0,1]
	s_waitcnt lgkmcnt(6)
	v_mfma_f32_16x16x32_bf16 v[64:67], v[240:243], v[216:219], v[64:67]
	ds_read_b128 v[240:243], v0 offset:44032
	s_waitcnt lgkmcnt(6)
	v_mfma_f32_16x16x32_bf16 v[100:103], v[244:247], v[224:227], v[64:67]
	ds_read_b128 v[244:247], v0 offset:45056
	s_nop 5
	v_mul_f32_e64 v66, v184, v74
	v_mul_f32_e64 v67, v184, v75
	v_pk_mul_f32 v[64:65], v[184:185], v[72:73] op_sel_hi:[0,1]
	s_waitcnt lgkmcnt(6)
	v_mfma_f32_16x16x32_bf16 v[64:67], v[248:251], v[216:219], v[64:67]
	ds_read_b128 v[248:251], v0 offset:46080
	s_waitcnt lgkmcnt(6)
	v_mfma_f32_16x16x32_bf16 v[104:107], v[220:223], v[224:227], v[64:67]
	ds_read_b128 v[220:223], v0 offset:47104
	v_cvt_pk_bf16_f32 v84, v116, v117
	v_cvt_pk_bf16_f32 v85, v118, v119
	v_cvt_pk_bf16_f32 v86, v80, v81
	s_nop 2
	v_pk_mul_f32 v[66:67], v[184:185], v[78:79] op_sel_hi:[0,1]
	v_pk_mul_f32 v[64:65], v[184:185], v[76:77] op_sel_hi:[0,1]
	s_waitcnt lgkmcnt(6)
	v_mfma_f32_16x16x32_bf16 v[64:67], v[228:231], v[216:219], v[64:67]
	ds_read_b128 v[228:231], v0 offset:48128
	v_cvt_pk_bf16_f32 v87, v82, v83
	v_pk_mul_f32 v[82:83], v[184:185], v[82:83] op_sel_hi:[0,1]
	v_pk_mul_f32 v[80:81], v[184:185], v[80:81] op_sel_hi:[0,1]
	s_waitcnt lgkmcnt(6)
	v_mfma_f32_16x16x32_bf16 v[108:111], v[232:235], v[224:227], v[64:67]
	s_nop 0
	v_pk_mul_f32 v[66:67], v[184:185], v[90:91] op_sel_hi:[0,1]
	v_pk_mul_f32 v[64:65], v[184:185], v[88:89] op_sel_hi:[0,1]
	s_nop 0
	s_waitcnt lgkmcnt(5)
	v_mfma_f32_16x16x32_bf16 v[64:67], v[236:239], v[216:219], v[64:67]
	s_waitcnt lgkmcnt(4)
	v_mfma_f32_16x16x32_bf16 v[88:91], v[240:243], v[224:227], v[64:67]
	s_nop 3
	v_pk_mul_f32 v[66:67], v[184:185], v[94:95] op_sel_hi:[0,1]
	v_pk_mul_f32 v[64:65], v[184:185], v[92:93] op_sel_hi:[0,1]
	s_nop 0
	s_waitcnt lgkmcnt(3)
	v_mfma_f32_16x16x32_bf16 v[64:67], v[244:247], v[216:219], v[64:67]
	s_waitcnt lgkmcnt(2)
	v_mfma_f32_16x16x32_bf16 v[92:95], v[248:251], v[224:227], v[64:67]
	s_waitcnt vmcnt(47)
	ds_write_b128 v185, v[128:131]
	s_waitcnt vmcnt(46)
	ds_write_b128 v185, v[132:135] offset:8192
	s_waitcnt vmcnt(45)
	ds_write_b128 v185, v[136:139] offset:16384
	s_waitcnt vmcnt(44)
	ds_write_b128 v185, v[140:143] offset:24576
	v_pk_mul_f32 v[66:67], v[184:185], v[178:179] op_sel_hi:[0,1]
	v_pk_mul_f32 v[64:65], v[184:185], v[176:177] op_sel_hi:[0,1]
	s_nop 0
	s_waitcnt lgkmcnt(5)
	v_mfma_f32_16x16x32_bf16 v[64:67], v[220:223], v[216:219], v[64:67]
	v_add_co_u32_e32 v96, vcc, s1, v186
	v_pk_mul_f32 v[98:99], v[184:185], v[118:119] op_sel_hi:[0,1]
	s_waitcnt lgkmcnt(4)
	v_mfma_f32_16x16x32_bf16 v[176:179], v[228:231], v[224:227], v[64:67]
	v_addc_co_u32_e32 v97, vcc, 0, v187, vcc
	s_nop 2
	global_load_dwordx4 v[64:67], v[188:189], off offset:3328
	global_load_dwordx4 v[68:71], v[190:191], off offset:3328
	global_load_dwordx4 v[72:75], v[192:193], off offset:3328
	global_load_dwordx4 v[76:79], v[194:195], off offset:3328
	s_waitcnt lgkmcnt(0)
	s_barrier
	global_store_dwordx4 v[96:97], v[84:87], off
	s_mov_b32 s1, 0xa8000
	s_nop 0
	v_cvt_pk_bf16_f32 v84, v100, v101
	v_cvt_pk_bf16_f32 v85, v102, v103
	v_cvt_pk_bf16_f32 v86, v104, v105
	v_cvt_pk_bf16_f32 v87, v106, v107
	global_store_dwordx4 v[96:97], v[84:87], off offset:1024
	s_nop 1
	v_cvt_pk_bf16_f32 v84, v108, v109
	v_cvt_pk_bf16_f32 v85, v110, v111
	v_cvt_pk_bf16_f32 v86, v88, v89
	v_cvt_pk_bf16_f32 v87, v90, v91
	global_store_dwordx4 v[96:97], v[84:87], off offset:2048
	s_nop 1
	v_cvt_pk_bf16_f32 v84, v92, v93
	v_cvt_pk_bf16_f32 v85, v94, v95
	v_cvt_pk_bf16_f32 v86, v176, v177
	v_cvt_pk_bf16_f32 v87, v178, v179
	global_store_dwordx4 v[96:97], v[84:87], off offset:3072
	ds_read_b128 v[216:219], v208 offset:16384
	ds_read_b128 v[220:223], v0
	ds_read_b128 v[224:227], v208 offset:17408
	ds_read_b128 v[228:231], v0 offset:1024
	ds_read_b128 v[232:235], v0 offset:2048
	ds_read_b128 v[236:239], v0 offset:3072
	ds_read_b128 v[240:243], v0 offset:4096
	ds_read_b128 v[244:247], v0 offset:5120
	ds_read_b128 v[248:251], v0 offset:6144
	v_pk_mul_f32 v[96:97], v[184:185], v[116:117] op_sel_hi:[0,1]
	s_waitcnt lgkmcnt(7)
	v_mfma_f32_16x16x32_bf16 v[96:99], v[220:223], v[216:219], v[96:99]
	ds_read_b128 v[220:223], v0 offset:7168
	s_waitcnt lgkmcnt(6)
	v_mfma_f32_16x16x32_bf16 v[132:135], v[228:231], v[224:227], v[96:99]
	ds_read_b128 v[228:231], v0 offset:8192
	s_waitcnt lgkmcnt(6)
	v_mfma_f32_16x16x32_bf16 v[80:83], v[232:235], v[216:219], v[80:83]
	ds_read_b128 v[232:235], v0 offset:9216
	s_waitcnt lgkmcnt(6)
	v_mfma_f32_16x16x32_bf16 v[96:99], v[236:239], v[224:227], v[80:83]
	ds_read_b128 v[236:239], v0 offset:10240
	s_nop 5
	v_mul_f32_e64 v82, v184, v102
	v_mul_f32_e64 v83, v184, v103
	v_pk_mul_f32 v[80:81], v[184:185], v[100:101] op_sel_hi:[0,1]
	s_waitcnt lgkmcnt(6)
	v_mfma_f32_16x16x32_bf16 v[80:83], v[240:243], v[216:219], v[80:83]
	ds_read_b128 v[240:243], v0 offset:11264
	s_waitcnt lgkmcnt(6)
	v_mfma_f32_16x16x32_bf16 v[116:119], v[244:247], v[224:227], v[80:83]
	ds_read_b128 v[244:247], v0 offset:12288
	s_nop 5
	v_mul_f32_e64 v82, v184, v106
	v_mul_f32_e64 v83, v184, v107
	v_pk_mul_f32 v[80:81], v[184:185], v[104:105] op_sel_hi:[0,1]
	s_waitcnt lgkmcnt(6)
	v_mfma_f32_16x16x32_bf16 v[80:83], v[248:251], v[216:219], v[80:83]
	ds_read_b128 v[248:251], v0 offset:13312
	s_waitcnt lgkmcnt(6)
	v_mfma_f32_16x16x32_bf16 v[104:107], v[220:223], v[224:227], v[80:83]
	ds_read_b128 v[220:223], v0 offset:14336
	s_nop 5
	v_mul_f32_e64 v82, v184, v110
	v_mul_f32_e64 v83, v184, v111
	v_pk_mul_f32 v[80:81], v[184:185], v[108:109] op_sel_hi:[0,1]
	s_waitcnt lgkmcnt(6)
	v_mfma_f32_16x16x32_bf16 v[80:83], v[228:231], v[216:219], v[80:83]
	ds_read_b128 v[228:231], v0 offset:15360
	s_waitcnt lgkmcnt(6)
	v_mfma_f32_16x16x32_bf16 v[108:111], v[232:235], v[224:227], v[80:83]
	s_nop 5
	v_mul_f32_e64 v82, v184, v90
	v_mul_f32_e64 v83, v184, v91
	v_pk_mul_f32 v[80:81], v[184:185], v[88:89] op_sel_hi:[0,1]
	s_waitcnt lgkmcnt(5)
	v_mfma_f32_16x16x32_bf16 v[80:83], v[236:239], v[216:219], v[80:83]
	s_waitcnt lgkmcnt(4)
	v_mfma_f32_16x16x32_bf16 v[120:123], v[240:243], v[224:227], v[80:83]
	v_cvt_pk_bf16_f32 v100, v132, v133
	v_cvt_pk_bf16_f32 v101, v134, v135
	v_cvt_pk_bf16_f32 v102, v96, v97
	s_nop 2
	v_pk_mul_f32 v[82:83], v[184:185], v[94:95] op_sel_hi:[0,1]
	v_pk_mul_f32 v[80:81], v[184:185], v[92:93] op_sel_hi:[0,1]
	s_waitcnt lgkmcnt(3)
	v_mfma_f32_16x16x32_bf16 v[80:83], v[244:247], v[216:219], v[80:83]
	v_cvt_pk_bf16_f32 v103, v98, v99
	v_pk_mul_f32 v[98:99], v[184:185], v[98:99] op_sel_hi:[0,1]
	v_pk_mul_f32 v[96:97], v[184:185], v[96:97] op_sel_hi:[0,1]
	s_waitcnt lgkmcnt(2)
	v_mfma_f32_16x16x32_bf16 v[124:127], v[248:251], v[224:227], v[80:83]
	s_waitcnt vmcnt(47)
	ds_write_b128 v185, v[144:147] offset:32768
	s_waitcnt vmcnt(46)
	ds_write_b128 v185, v[148:151] offset:40960
	s_waitcnt vmcnt(45)
	ds_write_b128 v185, v[152:155] offset:49152
	s_waitcnt vmcnt(44)
	ds_write_b128 v185, v[156:159] offset:57344
	v_pk_mul_f32 v[82:83], v[184:185], v[178:179] op_sel_hi:[0,1]
	v_pk_mul_f32 v[80:81], v[184:185], v[176:177] op_sel_hi:[0,1]
	s_nop 0
	s_waitcnt lgkmcnt(5)
	v_mfma_f32_16x16x32_bf16 v[80:83], v[220:223], v[216:219], v[80:83]
	v_add_co_u32_e32 v112, vcc, s1, v186
	v_pk_mul_f32 v[114:115], v[184:185], v[134:135] op_sel_hi:[0,1]
	s_waitcnt lgkmcnt(4)
	v_mfma_f32_16x16x32_bf16 v[176:179], v[228:231], v[224:227], v[80:83]
	v_addc_co_u32_e32 v113, vcc, 0, v187, vcc
	s_nop 2
	global_load_dwordx4 v[80:83], v[188:189], off offset:3456
	global_load_dwordx4 v[84:87], v[190:191], off offset:3456
	global_load_dwordx4 v[88:91], v[192:193], off offset:3456
	global_load_dwordx4 v[92:95], v[194:195], off offset:3456
	s_waitcnt lgkmcnt(0)
	s_barrier
	global_store_dwordx4 v[112:113], v[100:103], off
	s_mov_b32 s1, 0xb0000
	s_nop 0
	v_cvt_pk_bf16_f32 v100, v116, v117
	v_cvt_pk_bf16_f32 v101, v118, v119
	v_cvt_pk_bf16_f32 v102, v104, v105
	v_cvt_pk_bf16_f32 v103, v106, v107
	global_store_dwordx4 v[112:113], v[100:103], off offset:1024
	s_nop 1
	v_cvt_pk_bf16_f32 v100, v108, v109
	v_cvt_pk_bf16_f32 v101, v110, v111
	v_cvt_pk_bf16_f32 v102, v120, v121
	v_cvt_pk_bf16_f32 v103, v122, v123
	global_store_dwordx4 v[112:113], v[100:103], off offset:2048
	s_nop 1
	v_cvt_pk_bf16_f32 v100, v124, v125
	v_cvt_pk_bf16_f32 v101, v126, v127
	v_cvt_pk_bf16_f32 v102, v176, v177
	v_cvt_pk_bf16_f32 v103, v178, v179
	global_store_dwordx4 v[112:113], v[100:103], off offset:3072
	ds_read_b128 v[216:219], v208 offset:49152
	ds_read_b128 v[220:223], v0 offset:32768
	ds_read_b128 v[224:227], v208 offset:50176
	ds_read_b128 v[228:231], v0 offset:33792
	ds_read_b128 v[232:235], v0 offset:34816
	ds_read_b128 v[236:239], v0 offset:35840
	ds_read_b128 v[240:243], v0 offset:36864
	ds_read_b128 v[244:247], v0 offset:37888
	ds_read_b128 v[248:251], v0 offset:38912
	v_pk_mul_f32 v[112:113], v[184:185], v[132:133] op_sel_hi:[0,1]
	s_waitcnt lgkmcnt(7)
	v_mfma_f32_16x16x32_bf16 v[112:115], v[220:223], v[216:219], v[112:115]
	ds_read_b128 v[220:223], v0 offset:39936
	s_waitcnt lgkmcnt(6)
	v_mfma_f32_16x16x32_bf16 v[148:151], v[228:231], v[224:227], v[112:115]
	ds_read_b128 v[228:231], v0 offset:40960
	s_waitcnt lgkmcnt(6)
	v_mfma_f32_16x16x32_bf16 v[96:99], v[232:235], v[216:219], v[96:99]
	ds_read_b128 v[232:235], v0 offset:41984
	s_waitcnt lgkmcnt(6)
	v_mfma_f32_16x16x32_bf16 v[112:115], v[236:239], v[224:227], v[96:99]
	ds_read_b128 v[236:239], v0 offset:43008
	s_nop 5
	v_mul_f32_e64 v98, v184, v118
	v_mul_f32_e64 v99, v184, v119
	v_pk_mul_f32 v[96:97], v[184:185], v[116:117] op_sel_hi:[0,1]
	s_waitcnt lgkmcnt(6)
	v_mfma_f32_16x16x32_bf16 v[96:99], v[240:243], v[216:219], v[96:99]
	ds_read_b128 v[240:243], v0 offset:44032
	s_waitcnt lgkmcnt(6)
	v_mfma_f32_16x16x32_bf16 v[132:135], v[244:247], v[224:227], v[96:99]
	ds_read_b128 v[244:247], v0 offset:45056
	s_nop 5
	v_mul_f32_e64 v98, v184, v106
	v_mul_f32_e64 v99, v184, v107
	v_pk_mul_f32 v[96:97], v[184:185], v[104:105] op_sel_hi:[0,1]
	s_waitcnt lgkmcnt(6)
	v_mfma_f32_16x16x32_bf16 v[96:99], v[248:251], v[216:219], v[96:99]
	ds_read_b128 v[248:251], v0 offset:46080
	s_waitcnt lgkmcnt(6)
	v_mfma_f32_16x16x32_bf16 v[136:139], v[220:223], v[224:227], v[96:99]
	ds_read_b128 v[220:223], v0 offset:47104
	v_cvt_pk_bf16_f32 v116, v148, v149
	v_cvt_pk_bf16_f32 v117, v150, v151
	v_cvt_pk_bf16_f32 v118, v112, v113
	s_nop 2
	v_pk_mul_f32 v[98:99], v[184:185], v[110:111] op_sel_hi:[0,1]
	v_pk_mul_f32 v[96:97], v[184:185], v[108:109] op_sel_hi:[0,1]
	s_waitcnt lgkmcnt(6)
	v_mfma_f32_16x16x32_bf16 v[96:99], v[228:231], v[216:219], v[96:99]
	ds_read_b128 v[228:231], v0 offset:48128
	v_cvt_pk_bf16_f32 v119, v114, v115
	v_pk_mul_f32 v[150:151], v[184:185], v[150:151] op_sel_hi:[0,1]
	v_pk_mul_f32 v[148:149], v[184:185], v[148:149] op_sel_hi:[0,1]
	s_waitcnt lgkmcnt(6)
	v_mfma_f32_16x16x32_bf16 v[140:143], v[232:235], v[224:227], v[96:99]
	v_pk_mul_f32 v[114:115], v[184:185], v[114:115] op_sel_hi:[0,1]
	v_pk_mul_f32 v[98:99], v[184:185], v[122:123] op_sel_hi:[0,1]
	v_pk_mul_f32 v[96:97], v[184:185], v[120:121] op_sel_hi:[0,1]
	v_pk_mul_f32 v[112:113], v[184:185], v[112:113] op_sel_hi:[0,1]
	s_waitcnt lgkmcnt(5)
	v_mfma_f32_16x16x32_bf16 v[96:99], v[236:239], v[216:219], v[96:99]
	s_waitcnt lgkmcnt(4)
	v_mfma_f32_16x16x32_bf16 v[120:123], v[240:243], v[224:227], v[96:99]
	s_nop 3
	v_pk_mul_f32 v[98:99], v[184:185], v[126:127] op_sel_hi:[0,1]
	v_pk_mul_f32 v[96:97], v[184:185], v[124:125] op_sel_hi:[0,1]
	s_nop 0
	s_waitcnt lgkmcnt(3)
	v_mfma_f32_16x16x32_bf16 v[96:99], v[244:247], v[216:219], v[96:99]
	s_waitcnt lgkmcnt(2)
	v_mfma_f32_16x16x32_bf16 v[124:127], v[248:251], v[224:227], v[96:99]
	s_waitcnt vmcnt(47)
	ds_write_b128 v185, v[160:163]
	s_waitcnt vmcnt(46)
	ds_write_b128 v185, v[164:167] offset:8192
	s_waitcnt vmcnt(45)
	ds_write_b128 v185, v[168:171] offset:16384
	s_waitcnt vmcnt(44)
	ds_write_b128 v185, v[172:175] offset:24576
	v_pk_mul_f32 v[98:99], v[184:185], v[178:179] op_sel_hi:[0,1]
	v_pk_mul_f32 v[96:97], v[184:185], v[176:177] op_sel_hi:[0,1]
	s_nop 0
	s_waitcnt lgkmcnt(5)
	v_mfma_f32_16x16x32_bf16 v[96:99], v[220:223], v[216:219], v[96:99]
	v_add_co_u32_e32 v128, vcc, s1, v186
	s_mov_b32 s1, 0xb8000
	s_waitcnt lgkmcnt(4)
	v_mfma_f32_16x16x32_bf16 v[144:147], v[228:231], v[224:227], v[96:99]
	v_addc_co_u32_e32 v129, vcc, 0, v187, vcc
	s_nop 2
	global_load_dwordx4 v[96:99], v[188:189], off offset:3584
	global_load_dwordx4 v[100:103], v[190:191], off offset:3584
	global_load_dwordx4 v[104:107], v[192:193], off offset:3584
	global_load_dwordx4 v[108:111], v[194:195], off offset:3584
	s_waitcnt lgkmcnt(0)
	s_barrier
	global_store_dwordx4 v[128:129], v[116:119], off
	s_nop 1
	v_cvt_pk_bf16_f32 v116, v132, v133
	v_cvt_pk_bf16_f32 v117, v134, v135
	v_cvt_pk_bf16_f32 v118, v136, v137
	v_cvt_pk_bf16_f32 v119, v138, v139
	global_store_dwordx4 v[128:129], v[116:119], off offset:1024
	v_pk_mul_f32 v[134:135], v[184:185], v[134:135] op_sel_hi:[0,1]
	v_pk_mul_f32 v[132:133], v[184:185], v[132:133] op_sel_hi:[0,1]
	v_cvt_pk_bf16_f32 v116, v140, v141
	v_cvt_pk_bf16_f32 v117, v142, v143
	v_cvt_pk_bf16_f32 v118, v120, v121
	v_cvt_pk_bf16_f32 v119, v122, v123
	global_store_dwordx4 v[128:129], v[116:119], off offset:2048
	v_pk_mul_f32 v[138:139], v[184:185], v[138:139] op_sel_hi:[0,1]
	v_pk_mul_f32 v[136:137], v[184:185], v[136:137] op_sel_hi:[0,1]
	v_cvt_pk_bf16_f32 v116, v124, v125
	v_cvt_pk_bf16_f32 v117, v126, v127
	v_cvt_pk_bf16_f32 v118, v144, v145
	v_cvt_pk_bf16_f32 v119, v146, v147
	global_store_dwordx4 v[128:129], v[116:119], off offset:3072
	ds_read_b128 v[216:219], v208 offset:16384
	ds_read_b128 v[220:223], v0
	ds_read_b128 v[224:227], v0 offset:1024
	ds_read_b128 v[228:231], v0 offset:2048
	ds_read_b128 v[232:235], v0 offset:3072
	ds_read_b128 v[236:239], v0 offset:4096
	ds_read_b128 v[240:243], v0 offset:5120
	ds_read_b128 v[244:247], v0 offset:6144
	ds_read_b128 v[248:251], v0 offset:7168
	ds_read_b128 v[116:119], v208 offset:17408
	s_waitcnt lgkmcnt(8)
	v_mfma_f32_16x16x32_bf16 v[148:151], v[220:223], v[216:219], v[148:151]
	ds_read_b128 v[220:223], v0 offset:8192
	v_mul_f32_e64 v142, v184, v142
	v_mul_f32_e64 v143, v184, v143
	v_pk_mul_f32 v[140:141], v[184:185], v[140:141] op_sel_hi:[0,1]
	v_pk_mul_f32 v[122:123], v[184:185], v[122:123] op_sel_hi:[0,1]
	s_waitcnt lgkmcnt(1)
	v_mfma_f32_16x16x32_bf16 v[148:151], v[224:227], v[116:119], v[148:151]
	ds_read_b128 v[224:227], v0 offset:9216
	v_pk_mul_f32 v[120:121], v[184:185], v[120:121] op_sel_hi:[0,1]
	v_pk_mul_f32 v[126:127], v[184:185], v[126:127] op_sel_hi:[0,1]
	s_waitcnt lgkmcnt(8)
	v_mfma_f32_16x16x32_bf16 v[112:115], v[228:231], v[216:219], v[112:115]
	ds_read_b128 v[228:231], v0 offset:10240
	v_mul_f32_e64 v124, v184, v124
	v_mul_f32_e64 v125, v184, v125
	v_pk_mul_f32 v[146:147], v[184:185], v[146:147] op_sel_hi:[0,1]
	v_pk_mul_f32 v[144:145], v[184:185], v[144:145] op_sel_hi:[0,1]
	s_waitcnt lgkmcnt(3)
	v_mfma_f32_16x16x32_bf16 v[112:115], v[232:235], v[116:119], v[112:115]
	ds_read_b128 v[232:235], v0 offset:11264
	s_waitcnt lgkmcnt(8)
	v_mfma_f32_16x16x32_bf16 v[132:135], v[236:239], v[216:219], v[132:135]
	ds_read_b128 v[236:239], v0 offset:12288
	s_waitcnt lgkmcnt(5)
	v_mfma_f32_16x16x32_bf16 v[132:135], v[240:243], v[116:119], v[132:135]
	ds_read_b128 v[240:243], v0 offset:13312
	s_waitcnt lgkmcnt(8)
	v_mfma_f32_16x16x32_bf16 v[136:139], v[244:247], v[216:219], v[136:139]
	ds_read_b128 v[244:247], v0 offset:14336
	s_waitcnt lgkmcnt(7)
	v_mfma_f32_16x16x32_bf16 v[136:139], v[248:251], v[116:119], v[136:139]
	s_waitcnt lgkmcnt(6)
	v_mfma_f32_16x16x32_bf16 v[140:143], v[220:223], v[216:219], v[140:143]
	s_waitcnt lgkmcnt(5)
	v_mfma_f32_16x16x32_bf16 v[140:143], v[224:227], v[116:119], v[140:143]
	s_waitcnt lgkmcnt(4)
	v_mfma_f32_16x16x32_bf16 v[120:123], v[228:231], v[216:219], v[120:123]
	s_waitcnt lgkmcnt(3)
	v_mfma_f32_16x16x32_bf16 v[120:123], v[232:235], v[116:119], v[120:123]
	s_waitcnt lgkmcnt(2)
	v_mfma_f32_16x16x32_bf16 v[124:127], v[236:239], v[216:219], v[124:127]
	s_waitcnt lgkmcnt(1)
	v_mfma_f32_16x16x32_bf16 v[124:127], v[240:243], v[116:119], v[124:127]
	ds_read_b128 v[156:159], v0 offset:15360
	s_waitcnt vmcnt(47)
	ds_write_b128 v185, v[16:19] offset:32768
	s_waitcnt vmcnt(46)
	ds_write_b128 v185, v[20:23] offset:40960
	s_waitcnt vmcnt(45)
	ds_write_b128 v185, v[24:27] offset:49152
	s_waitcnt vmcnt(44)
	ds_write_b128 v185, v[28:31] offset:57344
	global_load_dwordx4 v[16:19], v[188:189], off offset:3712
	global_load_dwordx4 v[20:23], v[190:191], off offset:3712
	global_load_dwordx4 v[24:27], v[192:193], off offset:3712
	global_load_dwordx4 v[28:31], v[194:195], off offset:3712
	s_waitcnt lgkmcnt(5)
	v_mfma_f32_16x16x32_bf16 v[128:131], v[244:247], v[216:219], v[144:147]
	s_waitcnt lgkmcnt(0)
	s_barrier
	v_mfma_f32_16x16x32_bf16 v[144:147], v[156:159], v[116:119], v[128:131]
	ds_read_b128 v[216:219], v208 offset:49152
	ds_read_b128 v[220:223], v0 offset:32768
	ds_read_b128 v[224:227], v0 offset:33792
	ds_read_b128 v[228:231], v0 offset:34816
	ds_read_b128 v[232:235], v0 offset:35840
	ds_read_b128 v[236:239], v0 offset:36864
	ds_read_b128 v[240:243], v0 offset:37888
	ds_read_b128 v[244:247], v0 offset:38912
	ds_read_b128 v[248:251], v0 offset:39936
	v_cvt_pk_bf16_f32 v116, v148, v149
	v_cvt_pk_bf16_f32 v117, v150, v151
	v_cvt_pk_bf16_f32 v118, v112, v113
	s_nop 1
	v_add_co_u32_e32 v128, vcc, s1, v186
	v_cvt_pk_bf16_f32 v119, v114, v115
	s_nop 0
	v_addc_co_u32_e32 v129, vcc, 0, v187, vcc
	global_store_dwordx4 v[128:129], v[116:119], off
	v_pk_mul_f32 v[150:151], v[184:185], v[150:151] op_sel_hi:[0,1]
	v_pk_mul_f32 v[148:149], v[184:185], v[148:149] op_sel_hi:[0,1]
	v_cvt_pk_bf16_f32 v116, v132, v133
	v_cvt_pk_bf16_f32 v117, v134, v135
	v_cvt_pk_bf16_f32 v118, v136, v137
	v_cvt_pk_bf16_f32 v119, v138, v139
	global_store_dwordx4 v[128:129], v[116:119], off offset:1024
	v_pk_mul_f32 v[114:115], v[184:185], v[114:115] op_sel_hi:[0,1]
	v_pk_mul_f32 v[112:113], v[184:185], v[112:113] op_sel_hi:[0,1]
	v_cvt_pk_bf16_f32 v116, v140, v141
	v_cvt_pk_bf16_f32 v117, v142, v143
	v_cvt_pk_bf16_f32 v118, v120, v121
	v_cvt_pk_bf16_f32 v119, v122, v123
	global_store_dwordx4 v[128:129], v[116:119], off offset:2048
	v_pk_mul_f32 v[134:135], v[184:185], v[134:135] op_sel_hi:[0,1]
	v_pk_mul_f32 v[132:133], v[184:185], v[132:133] op_sel_hi:[0,1]
	v_cvt_pk_bf16_f32 v116, v124, v125
	v_cvt_pk_bf16_f32 v117, v126, v127
	v_cvt_pk_bf16_f32 v118, v144, v145
	v_cvt_pk_bf16_f32 v119, v146, v147
	global_store_dwordx4 v[128:129], v[116:119], off offset:3072
	ds_read_b128 v[116:119], v208 offset:50176
	s_waitcnt lgkmcnt(8)
	v_mfma_f32_16x16x32_bf16 v[148:151], v[220:223], v[216:219], v[148:151]
	ds_read_b128 v[220:223], v0 offset:40960
	v_mul_f32_e64 v138, v184, v138
	v_mul_f32_e64 v139, v184, v139
	v_pk_mul_f32 v[136:137], v[184:185], v[136:137] op_sel_hi:[0,1]
	v_pk_mul_f32 v[142:143], v[184:185], v[142:143] op_sel_hi:[0,1]
	s_waitcnt lgkmcnt(1)
	v_mfma_f32_16x16x32_bf16 v[148:151], v[224:227], v[116:119], v[148:151]
	ds_read_b128 v[224:227], v0 offset:41984
	v_pk_mul_f32 v[140:141], v[184:185], v[140:141] op_sel_hi:[0,1]
	v_pk_mul_f32 v[122:123], v[184:185], v[122:123] op_sel_hi:[0,1]
	s_waitcnt lgkmcnt(8)
	v_mfma_f32_16x16x32_bf16 v[112:115], v[228:231], v[216:219], v[112:115]
	ds_read_b128 v[228:231], v0 offset:43008
	v_mul_f32_e64 v120, v184, v120
	v_mul_f32_e64 v121, v184, v121
	v_pk_mul_f32 v[126:127], v[184:185], v[126:127] op_sel_hi:[0,1]
	v_pk_mul_f32 v[124:125], v[184:185], v[124:125] op_sel_hi:[0,1]
	s_waitcnt lgkmcnt(3)
	v_mfma_f32_16x16x32_bf16 v[112:115], v[232:235], v[116:119], v[112:115]
	ds_read_b128 v[232:235], v0 offset:44032
	v_pk_mul_f32 v[146:147], v[184:185], v[146:147] op_sel_hi:[0,1]
	v_pk_mul_f32 v[144:145], v[184:185], v[144:145] op_sel_hi:[0,1]
	s_waitcnt lgkmcnt(8)
	v_mfma_f32_16x16x32_bf16 v[132:135], v[236:239], v[216:219], v[132:135]
	ds_read_b128 v[236:239], v0 offset:45056
	s_mov_b32 s1, 0xc0000
	s_waitcnt lgkmcnt(5)
	v_mfma_f32_16x16x32_bf16 v[132:135], v[240:243], v[116:119], v[132:135]
	ds_read_b128 v[240:243], v0 offset:46080
	s_waitcnt lgkmcnt(8)
	v_mfma_f32_16x16x32_bf16 v[136:139], v[244:247], v[216:219], v[136:139]
	ds_read_b128 v[244:247], v0 offset:47104
	s_waitcnt lgkmcnt(7)
	v_mfma_f32_16x16x32_bf16 v[136:139], v[248:251], v[116:119], v[136:139]
	s_waitcnt lgkmcnt(6)
	v_mfma_f32_16x16x32_bf16 v[140:143], v[220:223], v[216:219], v[140:143]
	s_waitcnt lgkmcnt(5)
	v_mfma_f32_16x16x32_bf16 v[140:143], v[224:227], v[116:119], v[140:143]
	s_waitcnt lgkmcnt(4)
	v_mfma_f32_16x16x32_bf16 v[120:123], v[228:231], v[216:219], v[120:123]
	s_waitcnt lgkmcnt(3)
	v_mfma_f32_16x16x32_bf16 v[120:123], v[232:235], v[116:119], v[120:123]
	s_waitcnt lgkmcnt(2)
	v_mfma_f32_16x16x32_bf16 v[124:127], v[236:239], v[216:219], v[124:127]
	s_waitcnt lgkmcnt(1)
	v_mfma_f32_16x16x32_bf16 v[124:127], v[240:243], v[116:119], v[124:127]
	ds_read_b128 v[156:159], v0 offset:48128
	s_waitcnt vmcnt(47)
	ds_write_b128 v185, v[32:35]
	s_waitcnt vmcnt(46)
	ds_write_b128 v185, v[36:39] offset:8192
	s_waitcnt vmcnt(45)
	ds_write_b128 v185, v[40:43] offset:16384
	s_waitcnt vmcnt(44)
	ds_write_b128 v185, v[44:47] offset:24576
	global_load_dwordx4 v[32:35], v[188:189], off offset:3840
	global_load_dwordx4 v[36:39], v[190:191], off offset:3840
	global_load_dwordx4 v[40:43], v[192:193], off offset:3840
	global_load_dwordx4 v[44:47], v[194:195], off offset:3840
	s_waitcnt lgkmcnt(5)
	v_mfma_f32_16x16x32_bf16 v[128:131], v[244:247], v[216:219], v[144:147]
	s_waitcnt lgkmcnt(0)
	s_barrier
	v_mfma_f32_16x16x32_bf16 v[144:147], v[156:159], v[116:119], v[128:131]
	ds_read_b128 v[216:219], v208 offset:16384
	ds_read_b128 v[220:223], v0
	ds_read_b128 v[224:227], v0 offset:1024
	ds_read_b128 v[228:231], v0 offset:2048
	ds_read_b128 v[232:235], v0 offset:3072
	ds_read_b128 v[236:239], v0 offset:4096
	ds_read_b128 v[240:243], v0 offset:5120
	ds_read_b128 v[244:247], v0 offset:6144
	ds_read_b128 v[248:251], v0 offset:7168
	v_cvt_pk_bf16_f32 v116, v148, v149
	v_cvt_pk_bf16_f32 v117, v150, v151
	v_cvt_pk_bf16_f32 v118, v112, v113
	s_nop 1
	v_add_co_u32_e32 v128, vcc, s1, v186
	v_cvt_pk_bf16_f32 v119, v114, v115
	s_nop 0
	v_addc_co_u32_e32 v129, vcc, 0, v187, vcc
	global_store_dwordx4 v[128:129], v[116:119], off
	v_pk_mul_f32 v[150:151], v[184:185], v[150:151] op_sel_hi:[0,1]
	v_pk_mul_f32 v[148:149], v[184:185], v[148:149] op_sel_hi:[0,1]
	v_cvt_pk_bf16_f32 v116, v132, v133
	v_cvt_pk_bf16_f32 v117, v134, v135
	v_cvt_pk_bf16_f32 v118, v136, v137
	v_cvt_pk_bf16_f32 v119, v138, v139
	global_store_dwordx4 v[128:129], v[116:119], off offset:1024
	v_pk_mul_f32 v[114:115], v[184:185], v[114:115] op_sel_hi:[0,1]
	v_pk_mul_f32 v[112:113], v[184:185], v[112:113] op_sel_hi:[0,1]
	v_cvt_pk_bf16_f32 v116, v140, v141
	v_cvt_pk_bf16_f32 v117, v142, v143
	v_cvt_pk_bf16_f32 v118, v120, v121
	v_cvt_pk_bf16_f32 v119, v122, v123
	global_store_dwordx4 v[128:129], v[116:119], off offset:2048
	v_pk_mul_f32 v[134:135], v[184:185], v[134:135] op_sel_hi:[0,1]
	v_pk_mul_f32 v[132:133], v[184:185], v[132:133] op_sel_hi:[0,1]
	v_cvt_pk_bf16_f32 v116, v124, v125
	v_cvt_pk_bf16_f32 v117, v126, v127
	v_cvt_pk_bf16_f32 v118, v144, v145
	v_cvt_pk_bf16_f32 v119, v146, v147
	global_store_dwordx4 v[128:129], v[116:119], off offset:3072
	ds_read_b128 v[116:119], v208 offset:17408
	s_waitcnt lgkmcnt(8)
	v_mfma_f32_16x16x32_bf16 v[148:151], v[220:223], v[216:219], v[148:151]
	ds_read_b128 v[220:223], v0 offset:8192
	v_mul_f32_e64 v138, v184, v138
	v_mul_f32_e64 v139, v184, v139
	v_pk_mul_f32 v[136:137], v[184:185], v[136:137] op_sel_hi:[0,1]
	v_pk_mul_f32 v[142:143], v[184:185], v[142:143] op_sel_hi:[0,1]
	s_waitcnt lgkmcnt(1)
	v_mfma_f32_16x16x32_bf16 v[148:151], v[224:227], v[116:119], v[148:151]
	ds_read_b128 v[224:227], v0 offset:9216
	v_pk_mul_f32 v[140:141], v[184:185], v[140:141] op_sel_hi:[0,1]
	v_pk_mul_f32 v[122:123], v[184:185], v[122:123] op_sel_hi:[0,1]
	s_waitcnt lgkmcnt(8)
	v_mfma_f32_16x16x32_bf16 v[112:115], v[228:231], v[216:219], v[112:115]
	ds_read_b128 v[228:231], v0 offset:10240
	v_mul_f32_e64 v120, v184, v120
	v_mul_f32_e64 v121, v184, v121
	v_pk_mul_f32 v[126:127], v[184:185], v[126:127] op_sel_hi:[0,1]
	v_pk_mul_f32 v[124:125], v[184:185], v[124:125] op_sel_hi:[0,1]
	s_waitcnt lgkmcnt(3)
	v_mfma_f32_16x16x32_bf16 v[112:115], v[232:235], v[116:119], v[112:115]
	ds_read_b128 v[232:235], v0 offset:11264
	v_pk_mul_f32 v[146:147], v[184:185], v[146:147] op_sel_hi:[0,1]
	v_pk_mul_f32 v[144:145], v[184:185], v[144:145] op_sel_hi:[0,1]
	s_waitcnt lgkmcnt(8)
	v_mfma_f32_16x16x32_bf16 v[132:135], v[236:239], v[216:219], v[132:135]
	ds_read_b128 v[236:239], v0 offset:12288
	s_mov_b32 s1, 0xc8000
	s_waitcnt lgkmcnt(5)
	v_mfma_f32_16x16x32_bf16 v[132:135], v[240:243], v[116:119], v[132:135]
	ds_read_b128 v[240:243], v0 offset:13312
	s_waitcnt lgkmcnt(8)
	v_mfma_f32_16x16x32_bf16 v[136:139], v[244:247], v[216:219], v[136:139]
	ds_read_b128 v[244:247], v0 offset:14336
	s_waitcnt lgkmcnt(7)
	v_mfma_f32_16x16x32_bf16 v[136:139], v[248:251], v[116:119], v[136:139]
	s_waitcnt lgkmcnt(6)
	v_mfma_f32_16x16x32_bf16 v[140:143], v[220:223], v[216:219], v[140:143]
	s_waitcnt lgkmcnt(5)
	v_mfma_f32_16x16x32_bf16 v[140:143], v[224:227], v[116:119], v[140:143]
	s_waitcnt lgkmcnt(4)
	v_mfma_f32_16x16x32_bf16 v[120:123], v[228:231], v[216:219], v[120:123]
	s_waitcnt lgkmcnt(3)
	v_mfma_f32_16x16x32_bf16 v[120:123], v[232:235], v[116:119], v[120:123]
	s_waitcnt lgkmcnt(2)
	v_mfma_f32_16x16x32_bf16 v[124:127], v[236:239], v[216:219], v[124:127]
	s_waitcnt lgkmcnt(1)
	v_mfma_f32_16x16x32_bf16 v[124:127], v[240:243], v[116:119], v[124:127]
	ds_read_b128 v[156:159], v0 offset:15360
	s_waitcnt vmcnt(47)
	ds_write_b128 v185, v[48:51] offset:32768
	s_waitcnt vmcnt(46)
	ds_write_b128 v185, v[52:55] offset:40960
	s_waitcnt vmcnt(45)
	ds_write_b128 v185, v[56:59] offset:49152
	s_waitcnt vmcnt(44)
	ds_write_b128 v185, v[60:63] offset:57344
	global_load_dwordx4 v[48:51], v[188:189], off offset:3968
	global_load_dwordx4 v[52:55], v[190:191], off offset:3968
	global_load_dwordx4 v[56:59], v[192:193], off offset:3968
	global_load_dwordx4 v[60:63], v[194:195], off offset:3968
	s_waitcnt lgkmcnt(5)
	v_mfma_f32_16x16x32_bf16 v[128:131], v[244:247], v[216:219], v[144:147]
	s_waitcnt lgkmcnt(0)
	s_barrier
	v_mfma_f32_16x16x32_bf16 v[144:147], v[156:159], v[116:119], v[128:131]
	ds_read_b128 v[216:219], v208 offset:49152
	ds_read_b128 v[220:223], v0 offset:32768
	ds_read_b128 v[224:227], v208 offset:50176
	ds_read_b128 v[228:231], v0 offset:33792
	ds_read_b128 v[232:235], v0 offset:34816
	ds_read_b128 v[236:239], v0 offset:35840
	ds_read_b128 v[240:243], v0 offset:36864
	ds_read_b128 v[244:247], v0 offset:37888
	ds_read_b128 v[248:251], v0 offset:38912
	v_cvt_pk_bf16_f32 v116, v148, v149
	v_cvt_pk_bf16_f32 v117, v150, v151
	v_cvt_pk_bf16_f32 v118, v112, v113
	s_nop 1
	v_add_co_u32_e32 v128, vcc, s1, v186
	v_cvt_pk_bf16_f32 v119, v114, v115
	s_nop 0
	v_addc_co_u32_e32 v129, vcc, 0, v187, vcc
	global_store_dwordx4 v[128:129], v[116:119], off
	v_pk_mul_f32 v[150:151], v[184:185], v[150:151] op_sel_hi:[0,1]
	v_pk_mul_f32 v[148:149], v[184:185], v[148:149] op_sel_hi:[0,1]
	v_cvt_pk_bf16_f32 v116, v132, v133
	v_cvt_pk_bf16_f32 v117, v134, v135
	v_cvt_pk_bf16_f32 v118, v136, v137
	v_cvt_pk_bf16_f32 v119, v138, v139
	global_store_dwordx4 v[128:129], v[116:119], off offset:1024
	v_pk_mul_f32 v[114:115], v[184:185], v[114:115] op_sel_hi:[0,1]
	v_pk_mul_f32 v[112:113], v[184:185], v[112:113] op_sel_hi:[0,1]
	v_cvt_pk_bf16_f32 v116, v140, v141
	v_cvt_pk_bf16_f32 v117, v142, v143
	v_cvt_pk_bf16_f32 v118, v120, v121
	v_cvt_pk_bf16_f32 v119, v122, v123
	global_store_dwordx4 v[128:129], v[116:119], off offset:2048
	v_pk_mul_f32 v[134:135], v[184:185], v[134:135] op_sel_hi:[0,1]
	v_pk_mul_f32 v[132:133], v[184:185], v[132:133] op_sel_hi:[0,1]
	v_cvt_pk_bf16_f32 v116, v124, v125
	v_cvt_pk_bf16_f32 v117, v126, v127
	v_cvt_pk_bf16_f32 v118, v144, v145
	v_cvt_pk_bf16_f32 v119, v146, v147
	global_store_dwordx4 v[128:129], v[116:119], off offset:3072
	s_waitcnt lgkmcnt(7)
	v_mfma_f32_16x16x32_bf16 v[148:151], v[220:223], v[216:219], v[148:151]
	ds_read_b128 v[220:223], v0 offset:39936
	v_mul_f32_e64 v138, v184, v138
	v_mul_f32_e64 v139, v184, v139
	v_pk_mul_f32 v[136:137], v[184:185], v[136:137] op_sel_hi:[0,1]
	v_pk_mul_f32 v[142:143], v[184:185], v[142:143] op_sel_hi:[0,1]
	s_waitcnt lgkmcnt(6)
	v_mfma_f32_16x16x32_bf16 v[148:151], v[228:231], v[224:227], v[148:151]
	ds_read_b128 v[228:231], v0 offset:40960
	v_pk_mul_f32 v[140:141], v[184:185], v[140:141] op_sel_hi:[0,1]
	v_pk_mul_f32 v[122:123], v[184:185], v[122:123] op_sel_hi:[0,1]
	s_waitcnt lgkmcnt(6)
	v_mfma_f32_16x16x32_bf16 v[112:115], v[232:235], v[216:219], v[112:115]
	ds_read_b128 v[232:235], v0 offset:41984
	v_mul_f32_e64 v120, v184, v120
	v_mul_f32_e64 v121, v184, v121
	v_pk_mul_f32 v[126:127], v[184:185], v[126:127] op_sel_hi:[0,1]
	v_pk_mul_f32 v[124:125], v[184:185], v[124:125] op_sel_hi:[0,1]
	s_waitcnt lgkmcnt(6)
	v_mfma_f32_16x16x32_bf16 v[112:115], v[236:239], v[224:227], v[112:115]
	ds_read_b128 v[236:239], v0 offset:43008
	v_pk_mul_f32 v[146:147], v[184:185], v[146:147] op_sel_hi:[0,1]
	v_pk_mul_f32 v[144:145], v[184:185], v[144:145] op_sel_hi:[0,1]
	s_waitcnt lgkmcnt(6)
	v_mfma_f32_16x16x32_bf16 v[132:135], v[240:243], v[216:219], v[132:135]
	ds_read_b128 v[240:243], v0 offset:44032
	s_mov_b32 s1, 0xd0000
	s_waitcnt lgkmcnt(6)
	v_mfma_f32_16x16x32_bf16 v[132:135], v[244:247], v[224:227], v[132:135]
	ds_read_b128 v[244:247], v0 offset:45056
	s_waitcnt lgkmcnt(6)
	v_mfma_f32_16x16x32_bf16 v[136:139], v[248:251], v[216:219], v[136:139]
	ds_read_b128 v[248:251], v0 offset:46080
	s_waitcnt lgkmcnt(6)
	v_mfma_f32_16x16x32_bf16 v[136:139], v[220:223], v[224:227], v[136:139]
	ds_read_b128 v[220:223], v0 offset:47104
	s_waitcnt lgkmcnt(6)
	v_mfma_f32_16x16x32_bf16 v[140:143], v[228:231], v[216:219], v[140:143]
	ds_read_b128 v[228:231], v0 offset:48128
	s_waitcnt lgkmcnt(6)
	v_mfma_f32_16x16x32_bf16 v[140:143], v[232:235], v[224:227], v[140:143]
	s_waitcnt lgkmcnt(5)
	v_mfma_f32_16x16x32_bf16 v[120:123], v[236:239], v[216:219], v[120:123]
	s_waitcnt lgkmcnt(4)
	v_mfma_f32_16x16x32_bf16 v[120:123], v[240:243], v[224:227], v[120:123]
	s_waitcnt lgkmcnt(3)
	v_mfma_f32_16x16x32_bf16 v[124:127], v[244:247], v[216:219], v[124:127]
	s_waitcnt lgkmcnt(2)
	v_mfma_f32_16x16x32_bf16 v[124:127], v[248:251], v[224:227], v[124:127]
	s_waitcnt vmcnt(47)
	ds_write_b128 v185, v[64:67]
	s_waitcnt vmcnt(46)
	ds_write_b128 v185, v[68:71] offset:8192
	s_waitcnt vmcnt(45)
	ds_write_b128 v185, v[72:75] offset:16384
	s_waitcnt vmcnt(44)
	ds_write_b128 v185, v[76:79] offset:24576
	v_add_co_u32_e32 v68, vcc, s1, v186
	s_waitcnt lgkmcnt(5)
	v_mfma_f32_16x16x32_bf16 v[128:131], v[220:223], v[216:219], v[144:147]
	v_cvt_pk_bf16_f32 v64, v148, v149
	v_cvt_pk_bf16_f32 v65, v150, v151
	v_cvt_pk_bf16_f32 v66, v112, v113
	s_waitcnt lgkmcnt(4)
	v_mfma_f32_16x16x32_bf16 v[128:131], v[228:231], v[224:227], v[128:131]
	v_cvt_pk_bf16_f32 v67, v114, v115
	v_addc_co_u32_e32 v69, vcc, 0, v187, vcc
	s_waitcnt lgkmcnt(0)
	s_barrier
	global_store_dwordx4 v[68:69], v[64:67], off
	v_pk_mul_f32 v[70:71], v[184:185], v[150:151] op_sel_hi:[0,1]
	s_mov_b32 s1, 0xd8000
	v_cvt_pk_bf16_f32 v64, v132, v133
	v_cvt_pk_bf16_f32 v65, v134, v135
	v_cvt_pk_bf16_f32 v66, v136, v137
	v_cvt_pk_bf16_f32 v67, v138, v139
	global_store_dwordx4 v[68:69], v[64:67], off offset:1024
	s_nop 1
	v_cvt_pk_bf16_f32 v64, v140, v141
	v_cvt_pk_bf16_f32 v65, v142, v143
	v_cvt_pk_bf16_f32 v66, v120, v121
	v_cvt_pk_bf16_f32 v67, v122, v123
	global_store_dwordx4 v[68:69], v[64:67], off offset:2048
	v_pk_mul_f32 v[122:123], v[184:185], v[122:123] op_sel_hi:[0,1]
	v_pk_mul_f32 v[120:121], v[184:185], v[120:121] op_sel_hi:[0,1]
	v_cvt_pk_bf16_f32 v64, v124, v125
	v_cvt_pk_bf16_f32 v65, v126, v127
	v_cvt_pk_bf16_f32 v66, v128, v129
	v_cvt_pk_bf16_f32 v67, v130, v131
	global_store_dwordx4 v[68:69], v[64:67], off offset:3072
	ds_read_b128 v[72:75], v208 offset:16384
	ds_read_b128 v[64:67], v208 offset:17408
	ds_read_b128 v[76:79], v0
	ds_read_b128 v[116:119], v0 offset:1024
	v_pk_mul_f32 v[68:69], v[184:185], v[148:149] op_sel_hi:[0,1]
	v_pk_mul_f32 v[126:127], v[184:185], v[126:127] op_sel_hi:[0,1]
	v_pk_mul_f32 v[124:125], v[184:185], v[124:125] op_sel_hi:[0,1]
	s_waitcnt lgkmcnt(1)
	v_mfma_f32_16x16x32_bf16 v[68:71], v[76:79], v[72:75], v[68:71]
	v_mul_f32_e64 v130, v184, v130
	v_mul_f32_e64 v131, v184, v131
	v_pk_mul_f32 v[128:129], v[184:185], v[128:129] op_sel_hi:[0,1]
	s_waitcnt lgkmcnt(0)
	v_mfma_f32_16x16x32_bf16 v[144:147], v[116:119], v[64:67], v[68:71]
	s_nop 2
	v_mul_f32_e64 v70, v184, v114
	v_mul_f32_e64 v71, v184, v115
	v_pk_mul_f32 v[68:69], v[184:185], v[112:113] op_sel_hi:[0,1]
	ds_read_b128 v[76:79], v0 offset:2048
	ds_read_b128 v[112:115], v0 offset:3072
	s_waitcnt lgkmcnt(1)
	v_mfma_f32_16x16x32_bf16 v[68:71], v[76:79], v[72:75], v[68:71]
	v_mul_f32_e64 v78, v184, v134
	v_mul_f32_e64 v79, v184, v135
	v_pk_mul_f32 v[76:77], v[184:185], v[132:133] op_sel_hi:[0,1]
	s_waitcnt lgkmcnt(0)
	v_mfma_f32_16x16x32_bf16 v[68:71], v[112:115], v[64:67], v[68:71]
	ds_read_b128 v[112:115], v0 offset:4096
	ds_read_b128 v[116:119], v0 offset:5120
	s_waitcnt lgkmcnt(1)
	v_mfma_f32_16x16x32_bf16 v[76:79], v[112:115], v[72:75], v[76:79]
	v_mul_f32_e64 v114, v184, v138
	v_mul_f32_e64 v115, v184, v139
	v_pk_mul_f32 v[112:113], v[184:185], v[136:137] op_sel_hi:[0,1]
	s_waitcnt lgkmcnt(0)
	v_mfma_f32_16x16x32_bf16 v[76:79], v[116:119], v[64:67], v[76:79]
	ds_read_b128 v[116:119], v0 offset:6144
	ds_read_b128 v[132:135], v0 offset:7168
	s_waitcnt lgkmcnt(1)
	v_mfma_f32_16x16x32_bf16 v[112:115], v[116:119], v[72:75], v[112:115]
	v_mul_f32_e64 v118, v184, v142
	v_mul_f32_e64 v119, v184, v143
	v_pk_mul_f32 v[116:117], v[184:185], v[140:141] op_sel_hi:[0,1]
	s_waitcnt lgkmcnt(0)
	v_mfma_f32_16x16x32_bf16 v[112:115], v[132:135], v[64:67], v[112:115]
	ds_read_b128 v[132:135], v0 offset:8192
	ds_read_b128 v[136:139], v0 offset:9216
	s_waitcnt lgkmcnt(1)
	v_mfma_f32_16x16x32_bf16 v[116:119], v[132:135], v[72:75], v[116:119]
	s_waitcnt lgkmcnt(0)
	v_mfma_f32_16x16x32_bf16 v[116:119], v[136:139], v[64:67], v[116:119]
	ds_read_b128 v[132:135], v0 offset:10240
	ds_read_b128 v[136:139], v0 offset:11264
	s_waitcnt lgkmcnt(1)
	v_mfma_f32_16x16x32_bf16 v[120:123], v[132:135], v[72:75], v[120:123]
	s_waitcnt lgkmcnt(0)
	v_mfma_f32_16x16x32_bf16 v[120:123], v[136:139], v[64:67], v[120:123]
	ds_read_b128 v[132:135], v0 offset:12288
	ds_read_b128 v[136:139], v0 offset:13312
	s_waitcnt lgkmcnt(1)
	v_mfma_f32_16x16x32_bf16 v[124:127], v[132:135], v[72:75], v[124:127]
	s_waitcnt lgkmcnt(0)
	v_mfma_f32_16x16x32_bf16 v[124:127], v[136:139], v[64:67], v[124:127]
	ds_read_b128 v[132:135], v0 offset:14336
	ds_read_b128 v[136:139], v0 offset:15360
	s_waitcnt vmcnt(43)
	ds_write_b128 v185, v[80:83] offset:32768
	s_waitcnt vmcnt(42)
	ds_write_b128 v185, v[84:87] offset:40960
	s_waitcnt vmcnt(41)
	ds_write_b128 v185, v[88:91] offset:49152
	s_waitcnt vmcnt(40)
	ds_write_b128 v185, v[92:95] offset:57344
	s_waitcnt lgkmcnt(0)
	v_mfma_f32_16x16x32_bf16 v[72:75], v[132:135], v[72:75], v[128:131]
	s_barrier
	v_pk_mul_f32 v[82:83], v[184:185], v[146:147] op_sel_hi:[0,1]
	v_mfma_f32_16x16x32_bf16 v[128:131], v[136:139], v[64:67], v[72:75]
	v_cvt_pk_bf16_f32 v64, v144, v145
	v_cvt_pk_bf16_f32 v65, v146, v147
	v_cvt_pk_bf16_f32 v66, v68, v69
	s_nop 1
	v_add_co_u32_e32 v72, vcc, s1, v186
	v_cvt_pk_bf16_f32 v67, v70, v71
	s_nop 0
	v_addc_co_u32_e32 v73, vcc, 0, v187, vcc
	global_store_dwordx4 v[72:73], v[64:67], off
	v_pk_mul_f32 v[80:81], v[184:185], v[144:145] op_sel_hi:[0,1]
	v_pk_mul_f32 v[70:71], v[184:185], v[70:71] op_sel_hi:[0,1]
	v_cvt_pk_bf16_f32 v64, v76, v77
	v_cvt_pk_bf16_f32 v65, v78, v79
	v_cvt_pk_bf16_f32 v66, v112, v113
	v_cvt_pk_bf16_f32 v67, v114, v115
	global_store_dwordx4 v[72:73], v[64:67], off offset:1024
	v_pk_mul_f32 v[68:69], v[184:185], v[68:69] op_sel_hi:[0,1]
	v_pk_mul_f32 v[78:79], v[184:185], v[78:79] op_sel_hi:[0,1]
	v_cvt_pk_bf16_f32 v64, v116, v117
	v_cvt_pk_bf16_f32 v65, v118, v119
	v_cvt_pk_bf16_f32 v66, v120, v121
	v_cvt_pk_bf16_f32 v67, v122, v123
	global_store_dwordx4 v[72:73], v[64:67], off offset:2048
	v_pk_mul_f32 v[76:77], v[184:185], v[76:77] op_sel_hi:[0,1]
	s_mov_b32 s1, 0xe0000
	v_cvt_pk_bf16_f32 v64, v124, v125
	v_cvt_pk_bf16_f32 v65, v126, v127
	v_cvt_pk_bf16_f32 v66, v128, v129
	v_cvt_pk_bf16_f32 v67, v130, v131
	global_store_dwordx4 v[72:73], v[64:67], off offset:3072
	ds_read_b128 v[72:75], v208 offset:49152
	ds_read_b128 v[64:67], v208 offset:50176
	ds_read_b128 v[84:87], v0 offset:32768
	ds_read_b128 v[88:91], v0 offset:33792
	s_waitcnt lgkmcnt(1)
	v_mfma_f32_16x16x32_bf16 v[80:83], v[84:87], v[72:75], v[80:83]
	s_waitcnt lgkmcnt(0)
	v_mfma_f32_16x16x32_bf16 v[132:135], v[88:91], v[64:67], v[80:83]
	s_nop 5
	ds_read_b128 v[80:83], v0 offset:34816
	ds_read_b128 v[84:87], v0 offset:35840
	s_waitcnt lgkmcnt(1)
	v_mfma_f32_16x16x32_bf16 v[68:71], v[80:83], v[72:75], v[68:71]
	s_waitcnt lgkmcnt(0)
	v_mfma_f32_16x16x32_bf16 v[68:71], v[84:87], v[64:67], v[68:71]
	ds_read_b128 v[80:83], v0 offset:36864
	ds_read_b128 v[84:87], v0 offset:37888
	s_waitcnt lgkmcnt(1)
	v_mfma_f32_16x16x32_bf16 v[76:79], v[80:83], v[72:75], v[76:79]
	v_mul_f32_e64 v82, v184, v114
	v_mul_f32_e64 v83, v184, v115
	v_pk_mul_f32 v[80:81], v[184:185], v[112:113] op_sel_hi:[0,1]
	s_waitcnt lgkmcnt(0)
	v_mfma_f32_16x16x32_bf16 v[76:79], v[84:87], v[64:67], v[76:79]
	ds_read_b128 v[84:87], v0 offset:38912
	ds_read_b128 v[88:91], v0 offset:39936
	s_waitcnt lgkmcnt(1)
	v_mfma_f32_16x16x32_bf16 v[80:83], v[84:87], v[72:75], v[80:83]
	v_mul_f32_e64 v86, v184, v118
	v_mul_f32_e64 v87, v184, v119
	v_pk_mul_f32 v[84:85], v[184:185], v[116:117] op_sel_hi:[0,1]
	s_waitcnt lgkmcnt(0)
	v_mfma_f32_16x16x32_bf16 v[80:83], v[88:91], v[64:67], v[80:83]
	ds_read_b128 v[88:91], v0 offset:40960
	ds_read_b128 v[92:95], v0 offset:41984
	s_waitcnt lgkmcnt(1)
	v_mfma_f32_16x16x32_bf16 v[84:87], v[88:91], v[72:75], v[84:87]
	v_mul_f32_e64 v90, v184, v122
	v_mul_f32_e64 v91, v184, v123
	v_pk_mul_f32 v[88:89], v[184:185], v[120:121] op_sel_hi:[0,1]
	s_waitcnt lgkmcnt(0)
	v_mfma_f32_16x16x32_bf16 v[84:87], v[92:95], v[64:67], v[84:87]
	ds_read_b128 v[92:95], v0 offset:43008
	ds_read_b128 v[112:115], v0 offset:44032
	s_waitcnt lgkmcnt(1)
	v_mfma_f32_16x16x32_bf16 v[88:91], v[92:95], v[72:75], v[88:91]
	v_mul_f32_e64 v94, v184, v126
	v_mul_f32_e64 v95, v184, v127
	v_pk_mul_f32 v[92:93], v[184:185], v[124:125] op_sel_hi:[0,1]
	s_waitcnt lgkmcnt(0)
	v_mfma_f32_16x16x32_bf16 v[88:91], v[112:115], v[64:67], v[88:91]
	ds_read_b128 v[112:115], v0 offset:45056
	ds_read_b128 v[116:119], v0 offset:46080
	s_waitcnt lgkmcnt(1)
	v_mfma_f32_16x16x32_bf16 v[92:95], v[112:115], v[72:75], v[92:95]
	v_mul_f32_e64 v114, v184, v130
	v_mul_f32_e64 v115, v184, v131
	v_pk_mul_f32 v[112:113], v[184:185], v[128:129] op_sel_hi:[0,1]
	s_waitcnt lgkmcnt(0)
	v_mfma_f32_16x16x32_bf16 v[92:95], v[116:119], v[64:67], v[92:95]
	ds_read_b128 v[116:119], v0 offset:47104
	ds_read_b128 v[120:123], v0 offset:48128
	s_waitcnt vmcnt(39)
	ds_write_b128 v185, v[96:99]
	s_waitcnt vmcnt(38)
	ds_write_b128 v185, v[100:103] offset:8192
	s_waitcnt vmcnt(37)
	ds_write_b128 v185, v[104:107] offset:16384
	s_waitcnt vmcnt(36)
	ds_write_b128 v185, v[108:111] offset:24576
	s_waitcnt lgkmcnt(0)
	v_mfma_f32_16x16x32_bf16 v[72:75], v[116:119], v[72:75], v[112:115]
	s_barrier
	v_pk_mul_f32 v[98:99], v[184:185], v[134:135] op_sel_hi:[0,1]
	v_mfma_f32_16x16x32_bf16 v[112:115], v[120:123], v[64:67], v[72:75]
	ds_read_b128 v[216:219], v208 offset:16384
	ds_read_b128 v[220:223], v0
	ds_read_b128 v[224:227], v208 offset:17408
	ds_read_b128 v[228:231], v0 offset:1024
	ds_read_b128 v[232:235], v0 offset:2048
	ds_read_b128 v[236:239], v0 offset:3072
	ds_read_b128 v[240:243], v0 offset:4096
	ds_read_b128 v[244:247], v0 offset:5120
	ds_read_b128 v[248:251], v0 offset:6144
	v_cvt_pk_bf16_f32 v64, v132, v133
	v_cvt_pk_bf16_f32 v65, v134, v135
	v_cvt_pk_bf16_f32 v66, v68, v69
	s_nop 1
	v_add_co_u32_e32 v72, vcc, s1, v186
	v_cvt_pk_bf16_f32 v67, v70, v71
	s_nop 0
	v_addc_co_u32_e32 v73, vcc, 0, v187, vcc
	global_store_dwordx4 v[72:73], v[64:67], off
	v_pk_mul_f32 v[96:97], v[184:185], v[132:133] op_sel_hi:[0,1]
	v_pk_mul_f32 v[70:71], v[184:185], v[70:71] op_sel_hi:[0,1]
	v_cvt_pk_bf16_f32 v64, v76, v77
	v_cvt_pk_bf16_f32 v65, v78, v79
	v_cvt_pk_bf16_f32 v66, v80, v81
	v_cvt_pk_bf16_f32 v67, v82, v83
	global_store_dwordx4 v[72:73], v[64:67], off offset:1024
	v_pk_mul_f32 v[68:69], v[184:185], v[68:69] op_sel_hi:[0,1]
	v_pk_mul_f32 v[78:79], v[184:185], v[78:79] op_sel_hi:[0,1]
	v_cvt_pk_bf16_f32 v64, v84, v85
	v_cvt_pk_bf16_f32 v65, v86, v87
	v_cvt_pk_bf16_f32 v66, v88, v89
	v_cvt_pk_bf16_f32 v67, v90, v91
	global_store_dwordx4 v[72:73], v[64:67], off offset:2048
	v_pk_mul_f32 v[76:77], v[184:185], v[76:77] op_sel_hi:[0,1]
	v_pk_mul_f32 v[82:83], v[184:185], v[82:83] op_sel_hi:[0,1]
	v_cvt_pk_bf16_f32 v64, v92, v93
	v_cvt_pk_bf16_f32 v65, v94, v95
	v_cvt_pk_bf16_f32 v66, v112, v113
	v_cvt_pk_bf16_f32 v67, v114, v115
	global_store_dwordx4 v[72:73], v[64:67], off offset:3072
	s_waitcnt lgkmcnt(7)
	v_mfma_f32_16x16x32_bf16 v[96:99], v[220:223], v[216:219], v[96:99]
	ds_read_b128 v[220:223], v0 offset:7168
	v_mul_f32_e64 v80, v184, v80
	v_mul_f32_e64 v81, v184, v81
	v_pk_mul_f32 v[86:87], v[184:185], v[86:87] op_sel_hi:[0,1]
	v_pk_mul_f32 v[84:85], v[184:185], v[84:85] op_sel_hi:[0,1]
	s_waitcnt lgkmcnt(6)
	v_mfma_f32_16x16x32_bf16 v[100:103], v[228:231], v[224:227], v[96:99]
	ds_read_b128 v[228:231], v0 offset:8192
	v_pk_mul_f32 v[90:91], v[184:185], v[90:91] op_sel_hi:[0,1]
	v_pk_mul_f32 v[88:89], v[184:185], v[88:89] op_sel_hi:[0,1]
	s_waitcnt lgkmcnt(6)
	v_mfma_f32_16x16x32_bf16 v[68:71], v[232:235], v[216:219], v[68:71]
	ds_read_b128 v[232:235], v0 offset:9216
	v_mul_f32_e64 v94, v184, v94
	v_mul_f32_e64 v95, v184, v95
	v_pk_mul_f32 v[92:93], v[184:185], v[92:93] op_sel_hi:[0,1]
	s_mov_b32 s1, 0xe8000
	s_waitcnt lgkmcnt(6)
	v_mfma_f32_16x16x32_bf16 v[68:71], v[236:239], v[224:227], v[68:71]
	ds_read_b128 v[236:239], v0 offset:10240
	s_waitcnt lgkmcnt(6)
	v_mfma_f32_16x16x32_bf16 v[76:79], v[240:243], v[216:219], v[76:79]
	ds_read_b128 v[240:243], v0 offset:11264
	s_waitcnt lgkmcnt(6)
	v_mfma_f32_16x16x32_bf16 v[76:79], v[244:247], v[224:227], v[76:79]
	ds_read_b128 v[244:247], v0 offset:12288
	s_waitcnt lgkmcnt(6)
	v_mfma_f32_16x16x32_bf16 v[80:83], v[248:251], v[216:219], v[80:83]
	ds_read_b128 v[248:251], v0 offset:13312
	s_waitcnt lgkmcnt(6)
	v_mfma_f32_16x16x32_bf16 v[80:83], v[220:223], v[224:227], v[80:83]
	ds_read_b128 v[220:223], v0 offset:14336
	s_waitcnt lgkmcnt(6)
	v_mfma_f32_16x16x32_bf16 v[84:87], v[228:231], v[216:219], v[84:87]
	ds_read_b128 v[228:231], v0 offset:15360
	s_waitcnt lgkmcnt(6)
	v_mfma_f32_16x16x32_bf16 v[84:87], v[232:235], v[224:227], v[84:87]
	s_waitcnt lgkmcnt(5)
	v_mfma_f32_16x16x32_bf16 v[88:91], v[236:239], v[216:219], v[88:91]
	s_waitcnt lgkmcnt(4)
	v_mfma_f32_16x16x32_bf16 v[88:91], v[240:243], v[224:227], v[88:91]
	s_waitcnt lgkmcnt(3)
	v_mfma_f32_16x16x32_bf16 v[92:95], v[244:247], v[216:219], v[92:95]
	v_mul_f32_e64 v98, v184, v114
	v_mul_f32_e64 v99, v184, v115
	v_pk_mul_f32 v[96:97], v[184:185], v[112:113] op_sel_hi:[0,1]
	s_waitcnt lgkmcnt(2)
	v_mfma_f32_16x16x32_bf16 v[92:95], v[248:251], v[224:227], v[92:95]
	s_waitcnt vmcnt(35)
	ds_write_b128 v185, v[16:19] offset:32768
	s_waitcnt vmcnt(34)
	ds_write_b128 v185, v[20:23] offset:40960
	s_waitcnt vmcnt(33)
	ds_write_b128 v185, v[24:27] offset:49152
	s_waitcnt vmcnt(32)
	ds_write_b128 v185, v[28:31] offset:57344
	v_add_co_u32_e32 v20, vcc, s1, v186
	s_waitcnt lgkmcnt(5)
	v_mfma_f32_16x16x32_bf16 v[72:75], v[220:223], v[216:219], v[96:99]
	v_cvt_pk_bf16_f32 v16, v100, v101
	v_cvt_pk_bf16_f32 v17, v102, v103
	v_cvt_pk_bf16_f32 v18, v68, v69
	s_waitcnt lgkmcnt(4)
	v_mfma_f32_16x16x32_bf16 v[96:99], v[228:231], v[224:227], v[72:75]
	v_cvt_pk_bf16_f32 v19, v70, v71
	v_addc_co_u32_e32 v21, vcc, 0, v187, vcc
	s_waitcnt lgkmcnt(0)
	s_barrier
	global_store_dwordx4 v[20:21], v[16:19], off
	v_pk_mul_f32 v[22:23], v[184:185], v[102:103] op_sel_hi:[0,1]
	s_mov_b32 s1, 0xf0000
	v_cvt_pk_bf16_f32 v16, v76, v77
	v_cvt_pk_bf16_f32 v17, v78, v79
	v_cvt_pk_bf16_f32 v18, v80, v81
	v_cvt_pk_bf16_f32 v19, v82, v83
	global_store_dwordx4 v[20:21], v[16:19], off offset:1024
	s_nop 1
	v_cvt_pk_bf16_f32 v16, v84, v85
	v_cvt_pk_bf16_f32 v17, v86, v87
	v_cvt_pk_bf16_f32 v18, v88, v89
	v_cvt_pk_bf16_f32 v19, v90, v91
	global_store_dwordx4 v[20:21], v[16:19], off offset:2048
	s_nop 1
	v_cvt_pk_bf16_f32 v16, v92, v93
	v_cvt_pk_bf16_f32 v17, v94, v95
	v_cvt_pk_bf16_f32 v18, v96, v97
	v_cvt_pk_bf16_f32 v19, v98, v99
	global_store_dwordx4 v[20:21], v[16:19], off offset:3072
	ds_read_b128 v[24:27], v208 offset:49152
	ds_read_b128 v[16:19], v208 offset:50176
	ds_read_b128 v[28:31], v0 offset:32768
	ds_read_b128 v[64:67], v0 offset:33792
	v_pk_mul_f32 v[20:21], v[184:185], v[100:101] op_sel_hi:[0,1]
	s_waitcnt lgkmcnt(1)
	s_nop 0
	v_mfma_f32_16x16x32_bf16 v[20:23], v[28:31], v[24:27], v[20:23]
	s_waitcnt lgkmcnt(0)
	v_mfma_f32_16x16x32_bf16 v[100:103], v[64:67], v[16:19], v[20:23]
	ds_read_b128 v[28:31], v0 offset:34816
	ds_read_b128 v[64:67], v0 offset:35840
	s_nop 3
	v_pk_mul_f32 v[22:23], v[184:185], v[70:71] op_sel_hi:[0,1]
	v_pk_mul_f32 v[20:21], v[184:185], v[68:69] op_sel_hi:[0,1]
	s_waitcnt lgkmcnt(1)
	s_nop 0
	v_mfma_f32_16x16x32_bf16 v[20:23], v[28:31], v[24:27], v[20:23]
	v_mul_f32_e64 v30, v184, v78
	v_mul_f32_e64 v31, v184, v79
	v_pk_mul_f32 v[28:29], v[184:185], v[76:77] op_sel_hi:[0,1]
	s_waitcnt lgkmcnt(0)
	v_mfma_f32_16x16x32_bf16 v[20:23], v[64:67], v[16:19], v[20:23]
	ds_read_b128 v[64:67], v0 offset:36864
	ds_read_b128 v[68:71], v0 offset:37888
	s_waitcnt lgkmcnt(1)
	v_mfma_f32_16x16x32_bf16 v[28:31], v[64:67], v[24:27], v[28:31]
	v_mul_f32_e64 v66, v184, v82
	v_mul_f32_e64 v67, v184, v83
	v_pk_mul_f32 v[64:65], v[184:185], v[80:81] op_sel_hi:[0,1]
	s_waitcnt lgkmcnt(0)
	v_mfma_f32_16x16x32_bf16 v[28:31], v[68:71], v[16:19], v[28:31]
	ds_read_b128 v[68:71], v0 offset:38912
	ds_read_b128 v[72:75], v0 offset:39936
	s_waitcnt lgkmcnt(1)
	v_mfma_f32_16x16x32_bf16 v[64:67], v[68:71], v[24:27], v[64:67]
	v_mul_f32_e64 v70, v184, v86
	v_mul_f32_e64 v71, v184, v87
	v_pk_mul_f32 v[68:69], v[184:185], v[84:85] op_sel_hi:[0,1]
	s_waitcnt lgkmcnt(0)
	v_mfma_f32_16x16x32_bf16 v[64:67], v[72:75], v[16:19], v[64:67]
	ds_read_b128 v[72:75], v0 offset:40960
	ds_read_b128 v[76:79], v0 offset:41984
	s_waitcnt lgkmcnt(1)
	v_mfma_f32_16x16x32_bf16 v[68:71], v[72:75], v[24:27], v[68:71]
	v_mul_f32_e64 v74, v184, v90
	v_mul_f32_e64 v75, v184, v91
	v_pk_mul_f32 v[72:73], v[184:185], v[88:89] op_sel_hi:[0,1]
	s_waitcnt lgkmcnt(0)
	v_mfma_f32_16x16x32_bf16 v[68:71], v[76:79], v[16:19], v[68:71]
	ds_read_b128 v[76:79], v0 offset:43008
	ds_read_b128 v[80:83], v0 offset:44032
	s_waitcnt lgkmcnt(1)
	v_mfma_f32_16x16x32_bf16 v[72:75], v[76:79], v[24:27], v[72:75]
	v_mul_f32_e64 v78, v184, v94
	v_mul_f32_e64 v79, v184, v95
	v_pk_mul_f32 v[76:77], v[184:185], v[92:93] op_sel_hi:[0,1]
	s_waitcnt lgkmcnt(0)
	v_mfma_f32_16x16x32_bf16 v[72:75], v[80:83], v[16:19], v[72:75]
	ds_read_b128 v[80:83], v0 offset:45056
	ds_read_b128 v[84:87], v0 offset:46080
	s_waitcnt lgkmcnt(1)
	v_mfma_f32_16x16x32_bf16 v[76:79], v[80:83], v[24:27], v[76:79]
	v_mul_f32_e64 v82, v184, v98
	v_mul_f32_e64 v83, v184, v99
	v_pk_mul_f32 v[80:81], v[184:185], v[96:97] op_sel_hi:[0,1]
	s_waitcnt lgkmcnt(0)
	v_mfma_f32_16x16x32_bf16 v[76:79], v[84:87], v[16:19], v[76:79]
	ds_read_b128 v[84:87], v0 offset:47104
	ds_read_b128 v[88:91], v0 offset:48128
	s_waitcnt vmcnt(31)
	ds_write_b128 v185, v[32:35]
	s_waitcnt vmcnt(30)
	ds_write_b128 v185, v[36:39] offset:8192
	s_waitcnt vmcnt(29)
	ds_write_b128 v185, v[40:43] offset:16384
	s_waitcnt vmcnt(28)
	ds_write_b128 v185, v[44:47] offset:24576
	s_waitcnt lgkmcnt(0)
	v_mfma_f32_16x16x32_bf16 v[24:27], v[84:87], v[24:27], v[80:83]
	s_barrier
	v_pk_mul_f32 v[34:35], v[184:185], v[102:103] op_sel_hi:[0,1]
	v_mfma_f32_16x16x32_bf16 v[80:83], v[88:91], v[16:19], v[24:27]
	v_cvt_pk_bf16_f32 v16, v100, v101
	v_cvt_pk_bf16_f32 v17, v102, v103
	v_cvt_pk_bf16_f32 v18, v20, v21
	s_nop 1
	v_add_co_u32_e32 v24, vcc, s1, v186
	v_cvt_pk_bf16_f32 v19, v22, v23
	s_nop 0
	v_addc_co_u32_e32 v25, vcc, 0, v187, vcc
	global_store_dwordx4 v[24:25], v[16:19], off
	v_pk_mul_f32 v[32:33], v[184:185], v[100:101] op_sel_hi:[0,1]
	v_pk_mul_f32 v[22:23], v[184:185], v[22:23] op_sel_hi:[0,1]
	v_cvt_pk_bf16_f32 v16, v28, v29
	v_cvt_pk_bf16_f32 v17, v30, v31
	v_cvt_pk_bf16_f32 v18, v64, v65
	v_cvt_pk_bf16_f32 v19, v66, v67
	global_store_dwordx4 v[24:25], v[16:19], off offset:1024
	v_pk_mul_f32 v[20:21], v[184:185], v[20:21] op_sel_hi:[0,1]
	v_pk_mul_f32 v[30:31], v[184:185], v[30:31] op_sel_hi:[0,1]
	v_cvt_pk_bf16_f32 v16, v68, v69
	v_cvt_pk_bf16_f32 v17, v70, v71
	v_cvt_pk_bf16_f32 v18, v72, v73
	v_cvt_pk_bf16_f32 v19, v74, v75
	global_store_dwordx4 v[24:25], v[16:19], off offset:2048
	v_pk_mul_f32 v[28:29], v[184:185], v[28:29] op_sel_hi:[0,1]
	s_mov_b32 s1, 0xf8000
	v_cvt_pk_bf16_f32 v16, v76, v77
	v_cvt_pk_bf16_f32 v17, v78, v79
	v_cvt_pk_bf16_f32 v18, v80, v81
	v_cvt_pk_bf16_f32 v19, v82, v83
	global_store_dwordx4 v[24:25], v[16:19], off offset:3072
	ds_read_b128 v[24:27], v208 offset:16384
	ds_read_b128 v[16:19], v208 offset:17408
	ds_read_b128 v[36:39], v0
	ds_read_b128 v[40:43], v0 offset:1024
	s_waitcnt lgkmcnt(1)
	v_mfma_f32_16x16x32_bf16 v[32:35], v[36:39], v[24:27], v[32:35]
	s_waitcnt lgkmcnt(0)
	v_mfma_f32_16x16x32_bf16 v[84:87], v[40:43], v[16:19], v[32:35]
	s_nop 5
	ds_read_b128 v[32:35], v0 offset:2048
	ds_read_b128 v[36:39], v0 offset:3072
	s_waitcnt lgkmcnt(1)
	v_mfma_f32_16x16x32_bf16 v[20:23], v[32:35], v[24:27], v[20:23]
	s_waitcnt lgkmcnt(0)
	v_mfma_f32_16x16x32_bf16 v[20:23], v[36:39], v[16:19], v[20:23]
	ds_read_b128 v[32:35], v0 offset:4096
	ds_read_b128 v[36:39], v0 offset:5120
	s_waitcnt lgkmcnt(1)
	v_mfma_f32_16x16x32_bf16 v[28:31], v[32:35], v[24:27], v[28:31]
	v_mul_f32_e64 v34, v184, v66
	v_mul_f32_e64 v35, v184, v67
	v_pk_mul_f32 v[32:33], v[184:185], v[64:65] op_sel_hi:[0,1]
	s_waitcnt lgkmcnt(0)
	v_mfma_f32_16x16x32_bf16 v[28:31], v[36:39], v[16:19], v[28:31]
	ds_read_b128 v[36:39], v0 offset:6144
	ds_read_b128 v[40:43], v0 offset:7168
	s_waitcnt lgkmcnt(1)
	v_mfma_f32_16x16x32_bf16 v[32:35], v[36:39], v[24:27], v[32:35]
	v_mul_f32_e64 v38, v184, v70
	v_mul_f32_e64 v39, v184, v71
	v_pk_mul_f32 v[36:37], v[184:185], v[68:69] op_sel_hi:[0,1]
	s_waitcnt lgkmcnt(0)
	v_mfma_f32_16x16x32_bf16 v[32:35], v[40:43], v[16:19], v[32:35]
	ds_read_b128 v[40:43], v0 offset:8192
	ds_read_b128 v[44:47], v0 offset:9216
	s_waitcnt lgkmcnt(1)
	v_mfma_f32_16x16x32_bf16 v[36:39], v[40:43], v[24:27], v[36:39]
	v_mul_f32_e64 v42, v184, v74
	v_mul_f32_e64 v43, v184, v75
	v_pk_mul_f32 v[40:41], v[184:185], v[72:73] op_sel_hi:[0,1]
	s_waitcnt lgkmcnt(0)
	v_mfma_f32_16x16x32_bf16 v[36:39], v[44:47], v[16:19], v[36:39]
	ds_read_b128 v[44:47], v0 offset:10240
	ds_read_b128 v[64:67], v0 offset:11264
	s_waitcnt lgkmcnt(1)
	v_mfma_f32_16x16x32_bf16 v[40:43], v[44:47], v[24:27], v[40:43]
	v_mul_f32_e64 v46, v184, v78
	v_mul_f32_e64 v47, v184, v79
	v_pk_mul_f32 v[44:45], v[184:185], v[76:77] op_sel_hi:[0,1]
	s_waitcnt lgkmcnt(0)
	v_mfma_f32_16x16x32_bf16 v[40:43], v[64:67], v[16:19], v[40:43]
	ds_read_b128 v[64:67], v0 offset:12288
	ds_read_b128 v[68:71], v0 offset:13312
	s_waitcnt lgkmcnt(1)
	v_mfma_f32_16x16x32_bf16 v[44:47], v[64:67], v[24:27], v[44:47]
	v_mul_f32_e64 v66, v184, v82
	v_mul_f32_e64 v67, v184, v83
	v_pk_mul_f32 v[64:65], v[184:185], v[80:81] op_sel_hi:[0,1]
	s_waitcnt lgkmcnt(0)
	v_mfma_f32_16x16x32_bf16 v[44:47], v[68:71], v[16:19], v[44:47]
	ds_read_b128 v[68:71], v0 offset:14336
	ds_read_b128 v[72:75], v0 offset:15360
	s_waitcnt vmcnt(27)
	ds_write_b128 v185, v[48:51] offset:32768
	s_waitcnt vmcnt(26)
	ds_write_b128 v185, v[52:55] offset:40960
	s_waitcnt vmcnt(25)
	ds_write_b128 v185, v[56:59] offset:49152
	s_waitcnt vmcnt(24)
	ds_write_b128 v185, v[60:63] offset:57344
	s_waitcnt lgkmcnt(0)
	v_mfma_f32_16x16x32_bf16 v[24:27], v[68:71], v[24:27], v[64:67]
	s_barrier
	v_pk_mul_f32 v[50:51], v[184:185], v[86:87] op_sel_hi:[0,1]
	v_mfma_f32_16x16x32_bf16 v[64:67], v[72:75], v[16:19], v[24:27]
	v_cvt_pk_bf16_f32 v16, v84, v85
	v_cvt_pk_bf16_f32 v17, v86, v87
	v_cvt_pk_bf16_f32 v18, v20, v21
	s_nop 1
	v_add_co_u32_e32 v24, vcc, s1, v186
	v_cvt_pk_bf16_f32 v19, v22, v23
	s_nop 0
	v_addc_co_u32_e32 v25, vcc, 0, v187, vcc
	global_store_dwordx4 v[24:25], v[16:19], off
	v_pk_mul_f32 v[48:49], v[184:185], v[84:85] op_sel_hi:[0,1]
	v_pk_mul_f32 v[22:23], v[184:185], v[22:23] op_sel_hi:[0,1]
	v_cvt_pk_bf16_f32 v16, v28, v29
	v_cvt_pk_bf16_f32 v17, v30, v31
	v_cvt_pk_bf16_f32 v18, v32, v33
	v_cvt_pk_bf16_f32 v19, v34, v35
	global_store_dwordx4 v[24:25], v[16:19], off offset:1024
	v_pk_mul_f32 v[20:21], v[184:185], v[20:21] op_sel_hi:[0,1]
	v_pk_mul_f32 v[30:31], v[184:185], v[30:31] op_sel_hi:[0,1]
	v_cvt_pk_bf16_f32 v16, v36, v37
	v_cvt_pk_bf16_f32 v17, v38, v39
	v_cvt_pk_bf16_f32 v18, v40, v41
	v_cvt_pk_bf16_f32 v19, v42, v43
	global_store_dwordx4 v[24:25], v[16:19], off offset:2048
	v_pk_mul_f32 v[28:29], v[184:185], v[28:29] op_sel_hi:[0,1]
	v_pk_mul_f32 v[34:35], v[184:185], v[34:35] op_sel_hi:[0,1]
	v_cvt_pk_bf16_f32 v16, v44, v45
	v_cvt_pk_bf16_f32 v17, v46, v47
	v_cvt_pk_bf16_f32 v18, v64, v65
	v_cvt_pk_bf16_f32 v19, v66, v67
	global_store_dwordx4 v[24:25], v[16:19], off offset:3072
	ds_read_b128 v[24:27], v208 offset:49152
	ds_read_b128 v[16:19], v208 offset:50176
	ds_read_b128 v[52:55], v0 offset:32768
	ds_read_b128 v[56:59], v0 offset:33792
	s_waitcnt lgkmcnt(1)
	v_mfma_f32_16x16x32_bf16 v[48:51], v[52:55], v[24:27], v[48:51]
	v_mul_f32_e64 v32, v184, v32
	v_mul_f32_e64 v33, v184, v33
	v_pk_mul_f32 v[38:39], v[184:185], v[38:39] op_sel_hi:[0,1]
	v_pk_mul_f32 v[36:37], v[184:185], v[36:37] op_sel_hi:[0,1]
	s_waitcnt lgkmcnt(0)
	v_mfma_f32_16x16x32_bf16 v[48:51], v[56:59], v[16:19], v[48:51]
	ds_read_b128 v[52:55], v0 offset:34816
	ds_read_b128 v[56:59], v0 offset:35840
	v_pk_mul_f32 v[42:43], v[184:185], v[42:43] op_sel_hi:[0,1]
	v_pk_mul_f32 v[40:41], v[184:185], v[40:41] op_sel_hi:[0,1]
	s_waitcnt lgkmcnt(1)
	v_mfma_f32_16x16x32_bf16 v[20:23], v[52:55], v[24:27], v[20:23]
	v_mul_f32_e64 v46, v184, v46
	v_mul_f32_e64 v47, v184, v47
	v_pk_mul_f32 v[44:45], v[184:185], v[44:45] op_sel_hi:[0,1]
	s_mov_b32 s1, 0x100000
	s_waitcnt lgkmcnt(0)
	v_mfma_f32_16x16x32_bf16 v[20:23], v[56:59], v[16:19], v[20:23]
	ds_read_b128 v[52:55], v0 offset:36864
	ds_read_b128 v[56:59], v0 offset:37888
	s_waitcnt lgkmcnt(1)
	v_mfma_f32_16x16x32_bf16 v[28:31], v[52:55], v[24:27], v[28:31]
	s_waitcnt lgkmcnt(0)
	v_mfma_f32_16x16x32_bf16 v[28:31], v[56:59], v[16:19], v[28:31]
	ds_read_b128 v[52:55], v0 offset:38912
	ds_read_b128 v[56:59], v0 offset:39936
	s_waitcnt lgkmcnt(1)
	v_mfma_f32_16x16x32_bf16 v[32:35], v[52:55], v[24:27], v[32:35]
	s_waitcnt lgkmcnt(0)
	v_mfma_f32_16x16x32_bf16 v[32:35], v[56:59], v[16:19], v[32:35]
	ds_read_b128 v[52:55], v0 offset:40960
	ds_read_b128 v[56:59], v0 offset:41984
	s_waitcnt lgkmcnt(1)
	v_mfma_f32_16x16x32_bf16 v[36:39], v[52:55], v[24:27], v[36:39]
	s_waitcnt lgkmcnt(0)
	v_mfma_f32_16x16x32_bf16 v[36:39], v[56:59], v[16:19], v[36:39]
	ds_read_b128 v[52:55], v0 offset:43008
	ds_read_b128 v[56:59], v0 offset:44032
	s_waitcnt lgkmcnt(1)
	v_mfma_f32_16x16x32_bf16 v[40:43], v[52:55], v[24:27], v[40:43]
	s_waitcnt lgkmcnt(0)
	v_mfma_f32_16x16x32_bf16 v[40:43], v[56:59], v[16:19], v[40:43]
	ds_read_b128 v[52:55], v0 offset:45056
	ds_read_b128 v[56:59], v0 offset:46080
	s_waitcnt lgkmcnt(1)
	v_mfma_f32_16x16x32_bf16 v[44:47], v[52:55], v[24:27], v[44:47]
	v_mul_f32_e64 v54, v184, v66
	v_mul_f32_e64 v55, v184, v67
	v_pk_mul_f32 v[52:53], v[184:185], v[64:65] op_sel_hi:[0,1]
	s_waitcnt lgkmcnt(0)
	v_mfma_f32_16x16x32_bf16 v[44:47], v[56:59], v[16:19], v[44:47]
	ds_read_b128 v[56:59], v0 offset:47104
	ds_read_b128 v[60:63], v0 offset:48128
	s_waitcnt lgkmcnt(1)
	v_mfma_f32_16x16x32_bf16 v[24:27], v[56:59], v[24:27], v[52:55]
	s_waitcnt lgkmcnt(0)
	v_mfma_f32_16x16x32_bf16 v[16:19], v[60:63], v[16:19], v[24:27]
	s_nop 5
	v_cvt_pk_bf16_f32 v24, v48, v49
	v_add_co_u32_e32 v48, vcc, s1, v186
	v_cvt_pk_bf16_f32 v26, v20, v21
	v_cvt_pk_bf16_f32 v27, v22, v23
	v_addc_co_u32_e32 v49, vcc, 0, v187, vcc
	v_cvt_pk_bf16_f32 v20, v28, v29
	v_cvt_pk_bf16_f32 v21, v30, v31
	v_cvt_pk_bf16_f32 v22, v32, v33
	v_cvt_pk_bf16_f32 v23, v34, v35
	global_store_dwordx4 v[48:49], v[20:23], off offset:1024
	v_cvt_pk_bf16_f32 v25, v50, v51
	global_store_dwordx4 v[48:49], v[24:27], off
	v_cvt_pk_bf16_f32 v20, v36, v37
	v_cvt_pk_bf16_f32 v21, v38, v39
	v_cvt_pk_bf16_f32 v22, v40, v41
	v_cvt_pk_bf16_f32 v23, v42, v43
	global_store_dwordx4 v[48:49], v[20:23], off offset:2048
	s_nop 1
	v_cvt_pk_bf16_f32 v20, v44, v45
	v_cvt_pk_bf16_f32 v21, v46, v47
	v_cvt_pk_bf16_f32 v22, v16, v17
	v_cvt_pk_bf16_f32 v23, v18, v19
	global_store_dwordx4 v[48:49], v[20:23], off offset:3072
	s_waitcnt vmcnt(0)
	s_barrier
	s_and_saveexec_b64 s[18:19], s[46:47]
	s_cbranch_execz .LBB0_314
	s_mov_b64 s[22:23], exec
	v_mbcnt_lo_u32_b32 v0, s22, 0
	buffer_wbl2 sc1
	s_waitcnt vmcnt(0)
	s_waitcnt vmcnt(0)
	v_mbcnt_hi_u32_b32 v0, s23, v0
	v_cmp_eq_u32_e32 vcc, 0, v0
	s_and_b64 s[24:25], exec, vcc
	s_mov_b64 exec, s[24:25]
	s_cbranch_execz .LBB0_314
	s_bcnt1_i32_b64 s1, s[22:23]
	v_mov_b32_e32 v0, s1
	global_atomic_add v[182:183], v0, off offset:136
	s_branch .LBB0_314
